# M6 + sliver K-loops specialised per wave half (variant branch hoisted out of the loop, loop body duplicated)
# speedup vs baseline: 1.0079x; 1.0001x over previous
; template <class Epi, class Sched, bool ALIGN_EPI = false, bool SP2 = false, bool SLIVER = false>
; __device__ __forceinline__ void gemm_phase(PG8_LAS unsigned char* lds, const Gemm g, const Sched& S, const Epi& E) {
;     ...
;         const bool has_next = S.next(ui + 1, nxt);
;         const char* nA = has_next ? (const char*)g.A + (size_t)nxt.pm * tstep + Epi::k0(nxt.seg) * 2 : cA; const char* nB = has_next ? (const char*)g.Bt + (size_t)nxt.pn * tstep + Epi::k0(nxt.seg) * 2 : cB;
;         const char* nS = has_next ? (const char*)g.A + (size_t)S.srow0 * K * 2 + (size_t)nxt.pm * sstep + Epi::k0(nxt.seg) * 2 : cS;
;         for (int t = 0; t < nt; t += 2) {
;             const bool last = (t == nt - 2);
;             const char* a1 = cA + (size_t)(t + 1) * kstep;
;             const char* a2 = last ? nA : cA + (size_t)(t + 2) * kstep; const char* b2 = last ? nB : cB + (size_t)(t + 2) * kstep;
;             const char* a3 = a2 + kstep; const char* b3 = b2 + kstep;
;             const char* s1 = cS + (size_t)(t + 1) * kstep; const char* s2 = last ? nS : cS + (size_t)(t + 2) * kstep;
;             if (last && has_next) S.a_ready(nxt);
.LBB0_496:
	s_add_u32 s12, s80, 0x100
	s_addc_u32 s13, s81, 0
	s_lshl_b32 s40, s3, 7
	v_lshl_add_u64 v[138:139], s[62:63], 0, v[218:219]
	s_addk_i32 s40, 0xf800
	v_lshl_add_u64 v[188:189], s[16:17], 0, v[216:217]
	v_lshl_add_u64 v[190:191], v[138:139], 0, s[26:27]
	s_add_u32 s66, s40, 0x700
	s_mov_b32 s67, 0
	s_mov_b64 s[80:81], 0
	s_and_b64 vcc, exec, s[52:53]
	s_cbranch_vccz .LslvB_hdr0
	s_branch .LBB0_498

; #define PG8_SB(B) __builtin_amdgcn_rcpf(1.f + expneg(B))
; #define PG8_SB(B) __builtin_amdgcn_rcpf(1.f + expneg(B))
; #define PG8_STAGE(bufoff, gbase, voff) do { _Pragma("unroll") for (int _i = 0; _i < 2; ++_i) \
;         __builtin_amdgcn_global_load_lds((const unsigned*)((const char*)(gbase) + (size_t)_i * qstep + (voff)[0]), (PG8_LAS unsigned*)(lds + (bufoff) + ldsw + _i * 8192), 16, 0, 0); } while (0)
; #define PG8_LDA(dst, b, h) do { _Pragma("unroll") for (int m = 0; m < 4; ++m) _Pragma("unroll") for (int k = 0; k < 2; ++k) dst[m][k] = *(const PG8_LAS bf16x8*)(lds + PG8_SA(b, h) + aoff + m * 2048 + k * 1024); } while (0)
; #define PG8_LDB(dst, b, h) do { _Pragma("unroll") for (int n = 0; n < 2; ++n) _Pragma("unroll") for (int k = 0; k < 2; ++k) dst[n][k] = *(const PG8_LAS bf16x8*)(lds + PG8_SB(b, h) + boff + n * 2048 + k * 1024); } while (0)
; #define PG8_WAIT_V89() do { if constexpr (SLIVER) PG8_WAIT_V(9); else PG8_WAIT_V(8); } while (0)
; #define PG8_STAGE_S(b, gbase) do { if constexpr (SLIVER) __builtin_amdgcn_global_load_lds((const unsigned*)((const char*)(gbase) + voffS), (PG8_LAS unsigned*)(lds + STAGE_BYTES + (b) * 2048 + wid * 256), 4, 0, 0); } while (0)
; template <class Epi, class Sched, bool ALIGN_EPI = false, bool SP2 = false, bool SLIVER = false>
; __device__ __forceinline__ void gemm_phase(PG8_LAS unsigned char* lds, const Gemm g, const Sched& S, const Epi& E) {
;     ...
;         for (int t = 0; t < nt; t += 2) {
;             const bool last = (t == nt - 2);
;             const char* a1 = cA + (size_t)(t + 1) * kstep;
;             const char* a2 = last ? nA : cA + (size_t)(t + 2) * kstep; const char* b2 = last ? nB : cB + (size_t)(t + 2) * kstep;
;             const char* a3 = a2 + kstep; const char* b3 = b2 + kstep;
;             const char* s1 = cS + (size_t)(t + 1) * kstep; const char* s2 = last ? nS : cS + (size_t)(t + 2) * kstep;
;             if (last && has_next) S.a_ready(nxt);
;             if constexpr (SP2) {
;             PG8_LDB(B0, 0, 0); PG8_LDB(B1, 0, 1); PG8_SCHED; PG8_LDA(At, 0, 0); PG8_STAGE(PG8_SA(1, 1), a1 + hstep, voffA); PG8_STAGE_S(1, s1);
;             PG8_WAIT_V89(); PG8_WAIT_L(0); PG8_BAR; PG8_MMA(0, 0, At, B0); PG8_MMA(0, 1, At, B1); PG8_BAR; PG8_SCHED;
;             PG8_LDA(At, 0, 1); PG8_LDS_S(0); PG8_STAGE(PG8_SB(0, 0), b2, voffB); PG8_STAGE(PG8_SB(0, 1), b2 + hstep, voffB); PG8_STAGE(PG8_SA(0, 0), a2, voffA);
.LBB0_498:
	s_cmp_eq_u32 s66, s80
	s_cselect_b64 s[86:87], -1, 0
	s_add_u32 s40, s16, s80
	s_addc_u32 s41, s17, s81
	s_add_u32 s68, s40, 0x100
	s_addc_u32 s69, s41, 0
	s_and_b64 s[40:41], s[86:87], exec
	s_cselect_b32 s41, s55, s69
	s_cselect_b32 s40, s54, s68
	s_add_u32 s76, s12, s80
	s_addc_u32 s77, s13, s81
	s_add_i32 s78, 0, 0x10000
	s_and_b64 s[68:69], s[86:87], exec
	v_add_u32_e32 v138, s78, v239
	s_cselect_b32 s69, s83, s77
	s_cselect_b32 s68, s82, s76
	s_add_i32 s76, 0, 0x14000
	ds_read_b128 v[146:149], v138
	ds_read_b128 v[150:153], v138 offset:1024
	ds_read_b128 v[154:157], v138 offset:2048
	ds_read_b128 v[158:161], v138 offset:3072
	v_add_u32_e32 v138, s76, v239
	ds_read_b128 v[166:169], v138
	ds_read_b128 v[170:173], v138 offset:1024
	ds_read_b128 v[174:177], v138 offset:2048
	ds_read_b128 v[162:165], v138 offset:3072
	v_lshl_add_u64 v[208:209], v[188:189], 0, s[80:81]
	v_lshl_add_u64 v[224:225], v[208:209], 0, s[34:35]
	s_add_i32 m0, s96, 0xc000
	s_mov_b64 s[88:89], 0x120080
	ds_read_b128 v[138:141], v242
	ds_read_b128 v[142:145], v242 offset:1024
	ds_read_b128 v[180:183], v242 offset:2048
	ds_read_b128 v[184:187], v242 offset:3072
	ds_read_b128 v[192:195], v242 offset:4096
	ds_read_b128 v[196:199], v242 offset:5120
	ds_read_b128 v[200:203], v242 offset:6144
	ds_read_b128 v[220:223], v242 offset:7168
	global_load_lds_dwordx4 v[224:225], off
	v_lshl_add_u64 v[208:209], v[208:209], 0, s[88:89]
	s_add_i32 m0, s96, 0xe000
	s_nop 0
	global_load_lds_dwordx4 v[208:209], off
	v_lshl_add_u64 v[208:209], v[190:191], 0, s[80:81]
	s_add_i32 m0, s94, 0x20800
	s_nop 0
	global_load_lds_dword v[208:209], off
	s_waitcnt vmcnt(9)
	s_waitcnt lgkmcnt(0)
	s_setprio 1
	s_barrier
	v_mfma_f32_16x16x32_bf16 v[134:137], v[146:149], v[138:141], v[134:137]
	v_mfma_f32_16x16x32_bf16 v[130:133], v[154:157], v[138:141], v[130:133]
	v_mfma_f32_16x16x32_bf16 v[126:129], v[146:149], v[180:183], v[126:129]
	v_mfma_f32_16x16x32_bf16 v[122:125], v[154:157], v[180:183], v[122:125]
	v_mfma_f32_16x16x32_bf16 v[118:121], v[146:149], v[192:195], v[118:121]
	v_mfma_f32_16x16x32_bf16 v[114:117], v[154:157], v[192:195], v[114:117]
	v_mfma_f32_16x16x32_bf16 v[110:113], v[146:149], v[200:203], v[110:113]
	v_mfma_f32_16x16x32_bf16 v[106:109], v[154:157], v[200:203], v[106:109]
	v_mfma_f32_16x16x32_bf16 v[134:137], v[150:153], v[142:145], v[134:137]
	v_mfma_f32_16x16x32_bf16 v[130:133], v[158:161], v[142:145], v[130:133]
	v_mfma_f32_16x16x32_bf16 v[126:129], v[150:153], v[184:187], v[126:129]
	v_mfma_f32_16x16x32_bf16 v[122:125], v[158:161], v[184:187], v[122:125]
	v_mfma_f32_16x16x32_bf16 v[118:121], v[150:153], v[196:199], v[118:121]
	v_mfma_f32_16x16x32_bf16 v[114:117], v[158:161], v[196:199], v[114:117]
	v_mfma_f32_16x16x32_bf16 v[110:113], v[150:153], v[220:223], v[110:113]
	v_mfma_f32_16x16x32_bf16 v[106:109], v[158:161], v[220:223], v[106:109]
	s_setprio 0
	s_setprio 1
	v_mfma_f32_16x16x32_bf16 v[102:105], v[166:169], v[138:141], v[102:105]
	v_mfma_f32_16x16x32_bf16 v[98:101], v[174:177], v[138:141], v[98:101]
	v_mfma_f32_16x16x32_bf16 v[90:93], v[166:169], v[180:183], v[90:93]
	v_mfma_f32_16x16x32_bf16 v[86:89], v[174:177], v[180:183], v[86:89]
	v_mfma_f32_16x16x32_bf16 v[78:81], v[166:169], v[192:195], v[78:81]
	v_mfma_f32_16x16x32_bf16 v[74:77], v[174:177], v[192:195], v[74:77]
	v_mfma_f32_16x16x32_bf16 v[70:73], v[166:169], v[200:203], v[70:73]
	v_mfma_f32_16x16x32_bf16 v[66:69], v[174:177], v[200:203], v[66:69]
	v_mfma_f32_16x16x32_bf16 v[102:105], v[170:173], v[142:145], v[102:105]
	v_mfma_f32_16x16x32_bf16 v[98:101], v[162:165], v[142:145], v[98:101]
	v_mfma_f32_16x16x32_bf16 v[90:93], v[170:173], v[184:187], v[90:93]
	v_mfma_f32_16x16x32_bf16 v[86:89], v[162:165], v[184:187], v[86:89]
	v_mfma_f32_16x16x32_bf16 v[78:81], v[170:173], v[196:199], v[78:81]
	v_mfma_f32_16x16x32_bf16 v[74:77], v[162:165], v[196:199], v[74:77]
	v_mfma_f32_16x16x32_bf16 v[70:73], v[170:173], v[220:223], v[70:73]
	v_mfma_f32_16x16x32_bf16 v[66:69], v[162:165], v[220:223], v[66:69]
	s_barrier
	s_setprio 0
	s_add_i32 s77, 0, 0x20000
	v_lshl_add_u64 v[192:193], s[68:69], 0, v[212:213]
	s_add_i32 s68, s78, s95
	v_add_u32_e32 v178, s77, v240
	v_add_u32_e32 v184, s77, v241
	s_mov_b32 m0, s68
	s_mov_b64 s[88:89], 0x60000
	ds_read_b128 v[138:141], v242 offset:16384
	ds_read_b128 v[142:145], v242 offset:17408
	ds_read_b128 v[196:199], v242 offset:18432
	ds_read_b128 v[200:203], v242 offset:19456
	ds_read_b128 v[220:223], v242 offset:20480
	ds_read_b128 v[224:227], v242 offset:21504
	ds_read_b128 v[228:231], v242 offset:22528
	ds_read_b128 v[232:235], v242 offset:23552
	ds_read_b128 v[180:183], v178
	ds_read_b128 v[184:187], v184
	global_load_lds_dwordx4 v[192:193], off
	v_lshl_add_u64 v[194:195], v[192:193], 0, s[88:89]
	s_add_i32 m0, s68, 0x2000
	s_add_i32 s68, s76, s95
	global_load_lds_dwordx4 v[194:195], off
	v_lshl_add_u64 v[194:195], v[192:193], 0, s[24:25]
	s_mov_b32 m0, s68
	s_nop 0
	global_load_lds_dwordx4 v[194:195], off
	v_lshl_add_u64 v[194:195], v[192:193], 0, s[14:15]
	s_add_i32 m0, s68, 0x2000
	s_nop 0
	global_load_lds_dwordx4 v[194:195], off
	v_lshl_add_u64 v[194:195], s[40:41], 0, v[210:211]
	s_mov_b32 m0, s96
	v_lshl_add_u64 v[208:209], v[194:195], 0, s[88:89]
	global_load_lds_dwordx4 v[194:195], off
	s_mov_b32 m0, s19
	s_nop 0
	global_load_lds_dwordx4 v[208:209], off
	s_waitcnt vmcnt(9)
	s_waitcnt lgkmcnt(0)
	s_setprio 1
	s_barrier
; #define PG8_STAGE(bufoff, gbase, voff) do { _Pragma("unroll") for (int _i = 0; _i < 2; ++_i) \
;         __builtin_amdgcn_global_load_lds((const unsigned*)((const char*)(gbase) + (size_t)_i * qstep + (voff)[0]), (PG8_LAS unsigned*)(lds + (bufoff) + ldsw + _i * 8192), 16, 0, 0); } while (0)
; #define PG8_LDA(dst, b, h) do { _Pragma("unroll") for (int m = 0; m < 4; ++m) _Pragma("unroll") for (int k = 0; k < 2; ++k) dst[m][k] = *(const PG8_LAS bf16x8*)(lds + PG8_SA(b, h) + aoff + m * 2048 + k * 1024); } while (0)
; #define PG8_LDB(dst, b, h) do { _Pragma("unroll") for (int n = 0; n < 2; ++n) _Pragma("unroll") for (int k = 0; k < 2; ++k) dst[n][k] = *(const PG8_LAS bf16x8*)(lds + PG8_SB(b, h) + boff + n * 2048 + k * 1024); } while (0)
; #define PG8_MMA(ai, bj, At, Bt) do { __builtin_amdgcn_s_setprio(1); _Pragma("unroll") for (int m = 0; m < 4; ++m) _Pragma("unroll") for (int n = 0; n < 2; ++n) _Pragma("unroll") for (int k = 0; k < 2; ++k) \
;         acc[ai][bj][m][n] = __builtin_amdgcn_mfma_f32_16x16x32_bf16(Bt[n][k], At[m][k], acc[ai][bj][m][n], 0, 0, 0); __builtin_amdgcn_s_setprio(0); } while (0)
; #define PG8_WAIT_V89() do { if constexpr (SLIVER) PG8_WAIT_V(9); else PG8_WAIT_V(8); } while (0)
; #define PG8_STAGE_S(b, gbase) do { if constexpr (SLIVER) __builtin_amdgcn_global_load_lds((const unsigned*)((const char*)(gbase) + voffS), (PG8_LAS unsigned*)(lds + STAGE_BYTES + (b) * 2048 + wid * 256), 4, 0, 0); } while (0)
; #define PG8_WAIT_L(n) asm volatile("s_waitcnt lgkmcnt(" #n ")" ::: "memory")
; #define PG8_BAR __builtin_amdgcn_s_barrier()
; #define PG8_SCHED __builtin_amdgcn_sched_barrier(0)
; template <class Epi, class Sched, bool ALIGN_EPI = false, bool SP2 = false, bool SLIVER = false>
; __device__ __forceinline__ void gemm_phase(PG8_LAS unsigned char* lds, const Gemm g, const Sched& S, const Epi& E) {
;     ...
;             PG8_WAIT_V89(); PG8_WAIT_L(0); PG8_BAR; PG8_MMA(1, 0, At, B0); PG8_MMA(1, 1, At, B1); PG8_MMA_S(); PG8_BAR; PG8_SCHED;
;             PG8_LDB(B0, 1, 0); PG8_LDB(B1, 1, 1); PG8_SCHED; PG8_LDA(At, 1, 0); PG8_STAGE(PG8_SA(0, 1), a2 + hstep, voffA); PG8_STAGE_S(0, s2);
;             PG8_WAIT_V89(); PG8_WAIT_L(0); PG8_BAR; PG8_MMA(0, 0, At, B0); PG8_MMA(0, 1, At, B1); PG8_BAR; PG8_SCHED;
	v_mfma_f32_16x16x32_bf16 v[62:65], v[146:149], v[138:141], v[62:65]
	v_mfma_f32_16x16x32_bf16 v[58:61], v[154:157], v[138:141], v[58:61]
	v_mfma_f32_16x16x32_bf16 v[54:57], v[146:149], v[196:199], v[54:57]
	v_mfma_f32_16x16x32_bf16 v[50:53], v[154:157], v[196:199], v[50:53]
	v_mfma_f32_16x16x32_bf16 v[46:49], v[146:149], v[220:223], v[46:49]
	v_mfma_f32_16x16x32_bf16 v[42:45], v[154:157], v[220:223], v[42:45]
	v_mfma_f32_16x16x32_bf16 v[38:41], v[146:149], v[228:231], v[38:41]
	v_mfma_f32_16x16x32_bf16 v[34:37], v[154:157], v[228:231], v[34:37]
	v_mfma_f32_16x16x32_bf16 v[62:65], v[150:153], v[142:145], v[62:65]
	v_mfma_f32_16x16x32_bf16 v[58:61], v[158:161], v[142:145], v[58:61]
	v_mfma_f32_16x16x32_bf16 v[54:57], v[150:153], v[200:203], v[54:57]
	v_mfma_f32_16x16x32_bf16 v[50:53], v[158:161], v[200:203], v[50:53]
	v_mfma_f32_16x16x32_bf16 v[46:49], v[150:153], v[224:227], v[46:49]
	v_mfma_f32_16x16x32_bf16 v[42:45], v[158:161], v[224:227], v[42:45]
	v_mfma_f32_16x16x32_bf16 v[38:41], v[150:153], v[232:235], v[38:41]
	v_mfma_f32_16x16x32_bf16 v[34:37], v[158:161], v[232:235], v[34:37]
	s_setprio 0
	s_setprio 1
	v_mfma_f32_16x16x32_bf16 v[30:33], v[166:169], v[138:141], v[30:33]
	v_mfma_f32_16x16x32_bf16 v[26:29], v[174:177], v[138:141], v[26:29]
	v_mfma_f32_16x16x32_bf16 v[22:25], v[166:169], v[196:199], v[22:25]
	v_mfma_f32_16x16x32_bf16 v[18:21], v[174:177], v[196:199], v[18:21]
	v_mfma_f32_16x16x32_bf16 v[14:17], v[166:169], v[220:223], v[14:17]
	v_mfma_f32_16x16x32_bf16 v[10:13], v[174:177], v[220:223], v[10:13]
	v_mfma_f32_16x16x32_bf16 v[6:9], v[166:169], v[228:231], v[6:9]
	v_mfma_f32_16x16x32_bf16 v[2:5], v[174:177], v[228:231], v[2:5]
	v_mfma_f32_16x16x32_bf16 v[30:33], v[170:173], v[142:145], v[30:33]
	v_mfma_f32_16x16x32_bf16 v[26:29], v[162:165], v[142:145], v[26:29]
	v_mfma_f32_16x16x32_bf16 v[22:25], v[170:173], v[200:203], v[22:25]
	v_mfma_f32_16x16x32_bf16 v[18:21], v[162:165], v[200:203], v[18:21]
	v_mfma_f32_16x16x32_bf16 v[14:17], v[170:173], v[224:227], v[14:17]
	v_mfma_f32_16x16x32_bf16 v[10:13], v[162:165], v[224:227], v[10:13]
	v_mfma_f32_16x16x32_bf16 v[6:9], v[170:173], v[232:235], v[6:9]
	v_mfma_f32_16x16x32_bf16 v[2:5], v[162:165], v[232:235], v[2:5]
	s_setprio 0
	s_setprio 1
	v_mfma_f32_16x16x32_bf16 v[138:141], v[166:169], v[180:183], v[82:85]
	v_mfma_f32_16x16x32_bf16 v[142:145], v[174:177], v[180:183], v[94:97]
	v_mfma_f32_16x16x32_bf16 v[138:141], v[170:173], v[184:187], v[138:141]
	v_mfma_f32_16x16x32_bf16 v[142:145], v[162:165], v[184:187], v[142:145]
	s_barrier
	s_setprio 0
	s_add_u32 s68, s62, s80
	s_addc_u32 s69, s63, s81
	s_add_u32 s76, s68, 0x100
	s_addc_u32 s77, s69, 0
	s_and_b64 s[68:69], s[86:87], exec
	s_cselect_b32 s69, s85, s77
	s_cselect_b32 s68, s84, s76
	s_add_i32 s76, 0, 0x18000
	v_add_u32_e32 v82, s76, v239
	s_add_i32 s77, 0, 0x1c000
	ds_read_b128 v[146:149], v82
	ds_read_b128 v[150:153], v82 offset:1024
	ds_read_b128 v[154:157], v82 offset:2048
	ds_read_b128 v[158:161], v82 offset:3072
	v_add_u32_e32 v82, s77, v239
	ds_read_b128 v[166:169], v82
	ds_read_b128 v[170:173], v82 offset:1024
	ds_read_b128 v[174:177], v82 offset:2048
	ds_read_b128 v[162:165], v82 offset:3072
	s_mov_b32 m0, s91
	v_lshl_add_u64 v[208:209], v[194:195], 0, s[24:25]
	ds_read_b128 v[82:85], v242 offset:32768
	ds_read_b128 v[94:97], v242 offset:33792
	ds_read_b128 v[180:183], v242 offset:34816
	ds_read_b128 v[184:187], v242 offset:35840
	ds_read_b128 v[196:199], v242 offset:36864
	ds_read_b128 v[200:203], v242 offset:37888
	ds_read_b128 v[220:223], v242 offset:38912
	ds_read_b128 v[224:227], v242 offset:39936
	global_load_lds_dwordx4 v[208:209], off
	v_lshl_add_u64 v[208:209], v[194:195], 0, s[14:15]
	s_mov_b32 m0, s92
	s_nop 0
	global_load_lds_dwordx4 v[208:209], off
	v_lshl_add_u64 v[208:209], s[68:69], 0, v[214:215]
	s_mov_b32 m0, s93
	s_nop 0
	global_load_lds_dword v[208:209], off
	s_waitcnt vmcnt(9)
	s_waitcnt lgkmcnt(0)
	s_setprio 1
	s_barrier
; #define PG8_SB(B) __builtin_amdgcn_rcpf(1.f + expneg(B))
; #define PG8_SB(B) __builtin_amdgcn_rcpf(1.f + expneg(B))
; #define PG8_STAGE(bufoff, gbase, voff) do { _Pragma("unroll") for (int _i = 0; _i < 2; ++_i) \
;         __builtin_amdgcn_global_load_lds((const unsigned*)((const char*)(gbase) + (size_t)_i * qstep + (voff)[0]), (PG8_LAS unsigned*)(lds + (bufoff) + ldsw + _i * 8192), 16, 0, 0); } while (0)
; #define PG8_LDA(dst, b, h) do { _Pragma("unroll") for (int m = 0; m < 4; ++m) _Pragma("unroll") for (int k = 0; k < 2; ++k) dst[m][k] = *(const PG8_LAS bf16x8*)(lds + PG8_SA(b, h) + aoff + m * 2048 + k * 1024); } while (0)
; #define PG8_MMA(ai, bj, At, Bt) do { __builtin_amdgcn_s_setprio(1); _Pragma("unroll") for (int m = 0; m < 4; ++m) _Pragma("unroll") for (int n = 0; n < 2; ++n) _Pragma("unroll") for (int k = 0; k < 2; ++k) \
;         acc[ai][bj][m][n] = __builtin_amdgcn_mfma_f32_16x16x32_bf16(Bt[n][k], At[m][k], acc[ai][bj][m][n], 0, 0, 0); __builtin_amdgcn_s_setprio(0); } while (0)
; #define PG8_WAIT_V89() do { if constexpr (SLIVER) PG8_WAIT_V(9); else PG8_WAIT_V(8); } while (0)
; #define PG8_LDS_S(b) do { if constexpr (SLIVER) { Sf[0] = *(const PG8_LAS bf16x8*)(lds + STAGE_BYTES + (b) * 2048 + soff0); Sf[1] = *(const PG8_LAS bf16x8*)(lds + STAGE_BYTES + (b) * 2048 + (soff0 ^ 64)); } } while (0)
; #define PG8_WAIT_L(n) asm volatile("s_waitcnt lgkmcnt(" #n ")" ::: "memory")
; #define PG8_BAR __builtin_amdgcn_s_barrier()
; #define PG8_SCHED __builtin_amdgcn_sched_barrier(0)
; template <class Epi, class Sched, bool ALIGN_EPI = false, bool SP2 = false, bool SLIVER = false>
; __device__ __forceinline__ void gemm_phase(PG8_LAS unsigned char* lds, const Gemm g, const Sched& S, const Epi& E) {
;     ...
;             PG8_WAIT_V89(); PG8_WAIT_L(0); PG8_BAR; PG8_MMA(0, 0, At, B0); PG8_MMA(0, 1, At, B1); PG8_BAR; PG8_SCHED;
;             PG8_LDA(At, 1, 1); PG8_LDS_S(1); PG8_STAGE(PG8_SB(1, 0), b3, voffB); PG8_STAGE(PG8_SB(1, 1), b3 + hstep, voffB); PG8_STAGE(PG8_SA(1, 0), a3, voffA);
;             PG8_WAIT_V89(); PG8_WAIT_L(0); PG8_BAR; PG8_MMA(1, 0, At, B0); PG8_MMA(1, 1, At, B1); PG8_MMA_S(); PG8_BAR; PG8_SCHED;
	v_mfma_f32_16x16x32_bf16 v[134:137], v[146:149], v[82:85], v[134:137]
	v_mfma_f32_16x16x32_bf16 v[130:133], v[154:157], v[82:85], v[130:133]
	v_mfma_f32_16x16x32_bf16 v[126:129], v[146:149], v[180:183], v[126:129]
	v_mfma_f32_16x16x32_bf16 v[122:125], v[154:157], v[180:183], v[122:125]
	v_mfma_f32_16x16x32_bf16 v[118:121], v[146:149], v[196:199], v[118:121]
	v_mfma_f32_16x16x32_bf16 v[114:117], v[154:157], v[196:199], v[114:117]
	v_mfma_f32_16x16x32_bf16 v[110:113], v[146:149], v[220:223], v[110:113]
	v_mfma_f32_16x16x32_bf16 v[106:109], v[154:157], v[220:223], v[106:109]
	v_mfma_f32_16x16x32_bf16 v[134:137], v[150:153], v[94:97], v[134:137]
	v_mfma_f32_16x16x32_bf16 v[130:133], v[158:161], v[94:97], v[130:133]
	v_mfma_f32_16x16x32_bf16 v[126:129], v[150:153], v[184:187], v[126:129]
	v_mfma_f32_16x16x32_bf16 v[122:125], v[158:161], v[184:187], v[122:125]
	v_mfma_f32_16x16x32_bf16 v[118:121], v[150:153], v[200:203], v[118:121]
	v_mfma_f32_16x16x32_bf16 v[114:117], v[158:161], v[200:203], v[114:117]
	v_mfma_f32_16x16x32_bf16 v[110:113], v[150:153], v[224:227], v[110:113]
	v_mfma_f32_16x16x32_bf16 v[106:109], v[158:161], v[224:227], v[106:109]
	s_setprio 0
	s_setprio 1
	v_mfma_f32_16x16x32_bf16 v[102:105], v[166:169], v[82:85], v[102:105]
	v_mfma_f32_16x16x32_bf16 v[82:85], v[174:177], v[82:85], v[98:101]
	v_mfma_f32_16x16x32_bf16 v[98:101], v[162:165], v[94:97], v[82:85]
	v_mfma_f32_16x16x32_bf16 v[82:85], v[166:169], v[180:183], v[90:93]
	v_mfma_f32_16x16x32_bf16 v[90:93], v[170:173], v[184:187], v[82:85]
	v_mfma_f32_16x16x32_bf16 v[82:85], v[174:177], v[180:183], v[86:89]
	v_mfma_f32_16x16x32_bf16 v[78:81], v[166:169], v[196:199], v[78:81]
	v_mfma_f32_16x16x32_bf16 v[74:77], v[174:177], v[196:199], v[74:77]
	v_mfma_f32_16x16x32_bf16 v[70:73], v[166:169], v[220:223], v[70:73]
	v_mfma_f32_16x16x32_bf16 v[66:69], v[174:177], v[220:223], v[66:69]
	v_mfma_f32_16x16x32_bf16 v[102:105], v[170:173], v[94:97], v[102:105]
	v_mfma_f32_16x16x32_bf16 v[86:89], v[162:165], v[184:187], v[82:85]
	v_mfma_f32_16x16x32_bf16 v[78:81], v[170:173], v[200:203], v[78:81]
	v_mfma_f32_16x16x32_bf16 v[74:77], v[162:165], v[200:203], v[74:77]
	v_mfma_f32_16x16x32_bf16 v[70:73], v[170:173], v[224:227], v[70:73]
	v_mfma_f32_16x16x32_bf16 v[66:69], v[162:165], v[224:227], v[66:69]
	s_barrier
	s_setprio 0
	s_add_i32 s68, 0, 0x20800
	v_add_u32_e32 v178, s68, v240
	v_add_u32_e32 v184, s68, v241
	s_add_i32 s68, s76, s95
	v_lshl_add_u64 v[208:209], v[192:193], 0, s[26:27]
	s_mov_b32 m0, s68
	ds_read_b128 v[82:85], v242 offset:49152
	ds_read_b128 v[94:97], v242 offset:50176
	ds_read_b128 v[196:199], v242 offset:51200
	ds_read_b128 v[200:203], v242 offset:52224
	ds_read_b128 v[220:223], v242 offset:53248
	ds_read_b128 v[224:227], v242 offset:54272
	ds_read_b128 v[228:231], v242 offset:55296
	ds_read_b128 v[232:235], v242 offset:56320
	ds_read_b128 v[180:183], v178
	ds_read_b128 v[184:187], v184
	global_load_lds_dwordx4 v[208:209], off
	v_lshl_add_u64 v[208:209], v[192:193], 0, s[72:73]
	s_add_i32 m0, s68, 0x2000
	s_add_i32 s68, s77, s95
	global_load_lds_dwordx4 v[208:209], off
	v_lshl_add_u64 v[208:209], v[192:193], 0, s[34:35]
	s_mov_b32 m0, s68
	s_mov_b64 s[76:77], 0x120080
	global_load_lds_dwordx4 v[208:209], off
	v_lshl_add_u64 v[192:193], v[192:193], 0, s[76:77]
	s_add_i32 m0, s68, 0x2000
	s_nop 0
	global_load_lds_dwordx4 v[192:193], off
	v_lshl_add_u64 v[192:193], v[194:195], 0, s[26:27]
	s_mov_b32 m0, s97
	s_nop 0
	global_load_lds_dwordx4 v[192:193], off
	v_lshl_add_u64 v[192:193], v[194:195], 0, s[72:73]
	s_mov_b32 m0, s18
	s_nop 0
	global_load_lds_dwordx4 v[192:193], off
	s_waitcnt vmcnt(9)
	s_waitcnt lgkmcnt(0)
	s_setprio 1
	s_barrier
	v_mfma_f32_16x16x32_bf16 v[62:65], v[146:149], v[82:85], v[62:65]
	v_mfma_f32_16x16x32_bf16 v[58:61], v[154:157], v[82:85], v[58:61]
	v_mfma_f32_16x16x32_bf16 v[54:57], v[146:149], v[196:199], v[54:57]
	v_mfma_f32_16x16x32_bf16 v[50:53], v[154:157], v[196:199], v[50:53]
	v_mfma_f32_16x16x32_bf16 v[46:49], v[146:149], v[220:223], v[46:49]
	v_mfma_f32_16x16x32_bf16 v[42:45], v[154:157], v[220:223], v[42:45]
	v_mfma_f32_16x16x32_bf16 v[38:41], v[146:149], v[228:231], v[38:41]
	v_mfma_f32_16x16x32_bf16 v[34:37], v[154:157], v[228:231], v[34:37]
	v_mfma_f32_16x16x32_bf16 v[62:65], v[150:153], v[94:97], v[62:65]
	v_mfma_f32_16x16x32_bf16 v[58:61], v[158:161], v[94:97], v[58:61]
	v_mfma_f32_16x16x32_bf16 v[54:57], v[150:153], v[200:203], v[54:57]
	v_mfma_f32_16x16x32_bf16 v[50:53], v[158:161], v[200:203], v[50:53]
	v_mfma_f32_16x16x32_bf16 v[46:49], v[150:153], v[224:227], v[46:49]
	v_mfma_f32_16x16x32_bf16 v[42:45], v[158:161], v[224:227], v[42:45]
	v_mfma_f32_16x16x32_bf16 v[38:41], v[150:153], v[232:235], v[38:41]
	v_mfma_f32_16x16x32_bf16 v[34:37], v[158:161], v[232:235], v[34:37]
	s_setprio 0
	s_setprio 1
	v_mfma_f32_16x16x32_bf16 v[30:33], v[166:169], v[82:85], v[30:33]
	v_mfma_f32_16x16x32_bf16 v[26:29], v[174:177], v[82:85], v[26:29]
	v_mfma_f32_16x16x32_bf16 v[22:25], v[166:169], v[196:199], v[22:25]
	v_mfma_f32_16x16x32_bf16 v[18:21], v[174:177], v[196:199], v[18:21]
	v_mfma_f32_16x16x32_bf16 v[14:17], v[166:169], v[220:223], v[14:17]
	v_mfma_f32_16x16x32_bf16 v[10:13], v[174:177], v[220:223], v[10:13]
	v_mfma_f32_16x16x32_bf16 v[6:9], v[166:169], v[228:231], v[6:9]
	v_mfma_f32_16x16x32_bf16 v[2:5], v[174:177], v[228:231], v[2:5]
	v_mfma_f32_16x16x32_bf16 v[30:33], v[170:173], v[94:97], v[30:33]
	v_mfma_f32_16x16x32_bf16 v[26:29], v[162:165], v[94:97], v[26:29]
	v_mfma_f32_16x16x32_bf16 v[22:25], v[170:173], v[200:203], v[22:25]
	v_mfma_f32_16x16x32_bf16 v[18:21], v[162:165], v[200:203], v[18:21]
	v_mfma_f32_16x16x32_bf16 v[14:17], v[170:173], v[224:227], v[14:17]
	v_mfma_f32_16x16x32_bf16 v[10:13], v[162:165], v[224:227], v[10:13]
	v_mfma_f32_16x16x32_bf16 v[6:9], v[170:173], v[232:235], v[6:9]
	v_mfma_f32_16x16x32_bf16 v[2:5], v[162:165], v[232:235], v[2:5]
	s_setprio 0
	s_setprio 1
	v_mfma_f32_16x16x32_bf16 v[82:85], v[166:169], v[180:183], v[138:141]
	v_mfma_f32_16x16x32_bf16 v[94:97], v[174:177], v[180:183], v[142:145]
	v_mfma_f32_16x16x32_bf16 v[82:85], v[170:173], v[184:187], v[82:85]
	v_mfma_f32_16x16x32_bf16 v[94:97], v[162:165], v[184:187], v[94:97]
	s_branch .LBB0_497

; #define PG8_SB(B) __builtin_amdgcn_rcpf(1.f + expneg(B))
; #define PG8_SB(B) __builtin_amdgcn_rcpf(1.f + expneg(B))
; #define PG8_STAGE(bufoff, gbase, voff) do { _Pragma("unroll") for (int _i = 0; _i < 2; ++_i) \
;         __builtin_amdgcn_global_load_lds((const unsigned*)((const char*)(gbase) + (size_t)_i * qstep + (voff)[0]), (PG8_LAS unsigned*)(lds + (bufoff) + ldsw + _i * 8192), 16, 0, 0); } while (0)
; #define PG8_LDA(dst, b, h) do { _Pragma("unroll") for (int m = 0; m < 4; ++m) _Pragma("unroll") for (int k = 0; k < 2; ++k) dst[m][k] = *(const PG8_LAS bf16x8*)(lds + PG8_SA(b, h) + aoff + m * 2048 + k * 1024); } while (0)
; #define PG8_LDB(dst, b, h) do { _Pragma("unroll") for (int n = 0; n < 2; ++n) _Pragma("unroll") for (int k = 0; k < 2; ++k) dst[n][k] = *(const PG8_LAS bf16x8*)(lds + PG8_SB(b, h) + boff + n * 2048 + k * 1024); } while (0)
; #define PG8_WAIT_V89() do { if constexpr (SLIVER) PG8_WAIT_V(9); else PG8_WAIT_V(8); } while (0)
; #define PG8_STAGE_S(b, gbase) do { if constexpr (SLIVER) __builtin_amdgcn_global_load_lds((const unsigned*)((const char*)(gbase) + voffS), (PG8_LAS unsigned*)(lds + STAGE_BYTES + (b) * 2048 + wid * 256), 4, 0, 0); } while (0)
; template <class Epi, class Sched, bool ALIGN_EPI = false, bool SP2 = false, bool SLIVER = false>
; __device__ __forceinline__ void gemm_phase(PG8_LAS unsigned char* lds, const Gemm g, const Sched& S, const Epi& E) {
;     ...
;         for (int t = 0; t < nt; t += 2) {
;             const bool last = (t == nt - 2);
;             const char* a1 = cA + (size_t)(t + 1) * kstep;
;             const char* a2 = last ? nA : cA + (size_t)(t + 2) * kstep; const char* b2 = last ? nB : cB + (size_t)(t + 2) * kstep;
;             const char* a3 = a2 + kstep; const char* b3 = b2 + kstep;
;             const char* s1 = cS + (size_t)(t + 1) * kstep; const char* s2 = last ? nS : cS + (size_t)(t + 2) * kstep;
;             if (last && has_next) S.a_ready(nxt);
;             if constexpr (SP2) {
;             PG8_LDB(B0, 0, 0); PG8_LDB(B1, 0, 1); PG8_SCHED; PG8_LDA(At, 0, 0); PG8_STAGE(PG8_SA(1, 1), a1 + hstep, voffA); PG8_STAGE_S(1, s1);
;             PG8_WAIT_V89(); PG8_WAIT_L(0); PG8_BAR; PG8_MMA(0, 0, At, B0); PG8_MMA(0, 1, At, B1); PG8_BAR; PG8_SCHED;
;             PG8_LDA(At, 0, 1); PG8_LDS_S(0); PG8_STAGE(PG8_SB(0, 0), b2, voffB); PG8_STAGE(PG8_SB(0, 1), b2 + hstep, voffB); PG8_STAGE(PG8_SA(0, 0), a2, voffA);
.LslvB_hdr0:
	s_cmp_eq_u32 s66, s80
	s_cselect_b64 s[86:87], -1, 0
	s_add_u32 s40, s16, s80
	s_addc_u32 s41, s17, s81
	s_add_u32 s68, s40, 0x100
	s_addc_u32 s69, s41, 0
	s_and_b64 s[40:41], s[86:87], exec
	s_cselect_b32 s41, s55, s69
	s_cselect_b32 s40, s54, s68
	s_add_u32 s76, s12, s80
	s_addc_u32 s77, s13, s81
	s_add_i32 s78, 0, 0x10000
	s_and_b64 s[68:69], s[86:87], exec
	v_add_u32_e32 v138, s78, v239
	s_cselect_b32 s69, s83, s77
	s_cselect_b32 s68, s82, s76
	s_add_i32 s76, 0, 0x14000
	ds_read_b128 v[146:149], v138
	ds_read_b128 v[150:153], v138 offset:1024
	ds_read_b128 v[154:157], v138 offset:2048
	ds_read_b128 v[158:161], v138 offset:3072
	v_add_u32_e32 v138, s76, v239
	ds_read_b128 v[166:169], v138
	ds_read_b128 v[170:173], v138 offset:1024
	ds_read_b128 v[174:177], v138 offset:2048
	ds_read_b128 v[162:165], v138 offset:3072
	v_lshl_add_u64 v[208:209], v[188:189], 0, s[80:81]
	v_lshl_add_u64 v[224:225], v[208:209], 0, s[34:35]
	s_add_i32 m0, s96, 0xc000
	s_mov_b64 s[88:89], 0x120080
	ds_read_b128 v[138:141], v242
	ds_read_b128 v[142:145], v242 offset:1024
	ds_read_b128 v[180:183], v242 offset:2048
	ds_read_b128 v[184:187], v242 offset:3072
	ds_read_b128 v[192:195], v242 offset:4096
	ds_read_b128 v[196:199], v242 offset:5120
	ds_read_b128 v[200:203], v242 offset:6144
	ds_read_b128 v[220:223], v242 offset:7168
	global_load_lds_dwordx4 v[224:225], off
	v_lshl_add_u64 v[208:209], v[208:209], 0, s[88:89]
	s_add_i32 m0, s96, 0xe000
	s_nop 0
	global_load_lds_dwordx4 v[208:209], off
	v_lshl_add_u64 v[208:209], v[190:191], 0, s[80:81]
	s_add_i32 m0, s94, 0x20800
	s_nop 0
	global_load_lds_dword v[208:209], off
	s_waitcnt vmcnt(9)
	s_waitcnt lgkmcnt(0)
	s_setprio 1
	s_barrier
	v_mfma_f32_16x16x32_bf16 v[134:137], v[146:149], v[138:141], v[134:137]
	v_mfma_f32_16x16x32_bf16 v[130:133], v[154:157], v[138:141], v[130:133]
	v_mfma_f32_16x16x32_bf16 v[126:129], v[146:149], v[180:183], v[126:129]
	v_mfma_f32_16x16x32_bf16 v[122:125], v[154:157], v[180:183], v[122:125]
	v_mfma_f32_16x16x32_bf16 v[118:121], v[146:149], v[192:195], v[118:121]
	v_mfma_f32_16x16x32_bf16 v[114:117], v[154:157], v[192:195], v[114:117]
	v_mfma_f32_16x16x32_bf16 v[110:113], v[146:149], v[200:203], v[110:113]
	v_mfma_f32_16x16x32_bf16 v[106:109], v[154:157], v[200:203], v[106:109]
	v_mfma_f32_16x16x32_bf16 v[134:137], v[150:153], v[142:145], v[134:137]
	v_mfma_f32_16x16x32_bf16 v[130:133], v[158:161], v[142:145], v[130:133]
	v_mfma_f32_16x16x32_bf16 v[126:129], v[150:153], v[184:187], v[126:129]
	v_mfma_f32_16x16x32_bf16 v[122:125], v[158:161], v[184:187], v[122:125]
	v_mfma_f32_16x16x32_bf16 v[118:121], v[150:153], v[196:199], v[118:121]
	v_mfma_f32_16x16x32_bf16 v[114:117], v[158:161], v[196:199], v[114:117]
	v_mfma_f32_16x16x32_bf16 v[110:113], v[150:153], v[220:223], v[110:113]
	v_mfma_f32_16x16x32_bf16 v[106:109], v[158:161], v[220:223], v[106:109]
	s_setprio 0
	s_setprio 1
	v_mfma_f32_16x16x32_bf16 v[102:105], v[166:169], v[138:141], v[102:105]
	v_mfma_f32_16x16x32_bf16 v[98:101], v[174:177], v[138:141], v[98:101]
	v_mfma_f32_16x16x32_bf16 v[90:93], v[166:169], v[180:183], v[90:93]
	v_mfma_f32_16x16x32_bf16 v[86:89], v[174:177], v[180:183], v[86:89]
	v_mfma_f32_16x16x32_bf16 v[78:81], v[166:169], v[192:195], v[78:81]
	v_mfma_f32_16x16x32_bf16 v[74:77], v[174:177], v[192:195], v[74:77]
	v_mfma_f32_16x16x32_bf16 v[70:73], v[166:169], v[200:203], v[70:73]
	v_mfma_f32_16x16x32_bf16 v[66:69], v[174:177], v[200:203], v[66:69]
	v_mfma_f32_16x16x32_bf16 v[102:105], v[170:173], v[142:145], v[102:105]
	v_mfma_f32_16x16x32_bf16 v[98:101], v[162:165], v[142:145], v[98:101]
	v_mfma_f32_16x16x32_bf16 v[90:93], v[170:173], v[184:187], v[90:93]
	v_mfma_f32_16x16x32_bf16 v[86:89], v[162:165], v[184:187], v[86:89]
	v_mfma_f32_16x16x32_bf16 v[78:81], v[170:173], v[196:199], v[78:81]
	v_mfma_f32_16x16x32_bf16 v[74:77], v[162:165], v[196:199], v[74:77]
	v_mfma_f32_16x16x32_bf16 v[70:73], v[170:173], v[220:223], v[70:73]
	v_mfma_f32_16x16x32_bf16 v[66:69], v[162:165], v[220:223], v[66:69]
	s_barrier
	s_setprio 0
	s_add_i32 s77, 0, 0x20000
	v_lshl_add_u64 v[192:193], s[68:69], 0, v[212:213]
	s_add_i32 s68, s78, s95
	v_add_u32_e32 v178, s77, v240
	v_add_u32_e32 v184, s77, v241
	s_mov_b32 m0, s68
	s_mov_b64 s[88:89], 0x60000
	ds_read_b128 v[138:141], v242 offset:16384
	ds_read_b128 v[142:145], v242 offset:17408
	ds_read_b128 v[196:199], v242 offset:18432
	ds_read_b128 v[200:203], v242 offset:19456
	ds_read_b128 v[220:223], v242 offset:20480
	ds_read_b128 v[224:227], v242 offset:21504
	ds_read_b128 v[228:231], v242 offset:22528
	ds_read_b128 v[232:235], v242 offset:23552
	ds_read_b128 v[180:183], v178
	ds_read_b128 v[184:187], v184
	global_load_lds_dwordx4 v[192:193], off
	v_lshl_add_u64 v[194:195], v[192:193], 0, s[88:89]
	s_add_i32 m0, s68, 0x2000
	s_add_i32 s68, s76, s95
	global_load_lds_dwordx4 v[194:195], off
	v_lshl_add_u64 v[194:195], v[192:193], 0, s[24:25]
	s_mov_b32 m0, s68
	s_nop 0
	global_load_lds_dwordx4 v[194:195], off
	v_lshl_add_u64 v[194:195], v[192:193], 0, s[14:15]
	s_add_i32 m0, s68, 0x2000
	s_nop 0
	global_load_lds_dwordx4 v[194:195], off
	v_lshl_add_u64 v[194:195], s[40:41], 0, v[210:211]
	s_mov_b32 m0, s96
	v_lshl_add_u64 v[208:209], v[194:195], 0, s[88:89]
	global_load_lds_dwordx4 v[194:195], off
	s_mov_b32 m0, s19
	s_nop 0
	global_load_lds_dwordx4 v[208:209], off
	s_waitcnt vmcnt(9)
	s_waitcnt lgkmcnt(0)
	s_setprio 1
	s_barrier
; #define PG8_STAGE(bufoff, gbase, voff) do { _Pragma("unroll") for (int _i = 0; _i < 2; ++_i) \
;         __builtin_amdgcn_global_load_lds((const unsigned*)((const char*)(gbase) + (size_t)_i * qstep + (voff)[0]), (PG8_LAS unsigned*)(lds + (bufoff) + ldsw + _i * 8192), 16, 0, 0); } while (0)
; #define PG8_LDA(dst, b, h) do { _Pragma("unroll") for (int m = 0; m < 4; ++m) _Pragma("unroll") for (int k = 0; k < 2; ++k) dst[m][k] = *(const PG8_LAS bf16x8*)(lds + PG8_SA(b, h) + aoff + m * 2048 + k * 1024); } while (0)
; #define PG8_LDB(dst, b, h) do { _Pragma("unroll") for (int n = 0; n < 2; ++n) _Pragma("unroll") for (int k = 0; k < 2; ++k) dst[n][k] = *(const PG8_LAS bf16x8*)(lds + PG8_SB(b, h) + boff + n * 2048 + k * 1024); } while (0)
; #define PG8_MMA(ai, bj, At, Bt) do { __builtin_amdgcn_s_setprio(1); _Pragma("unroll") for (int m = 0; m < 4; ++m) _Pragma("unroll") for (int n = 0; n < 2; ++n) _Pragma("unroll") for (int k = 0; k < 2; ++k) \
;         acc[ai][bj][m][n] = __builtin_amdgcn_mfma_f32_16x16x32_bf16(Bt[n][k], At[m][k], acc[ai][bj][m][n], 0, 0, 0); __builtin_amdgcn_s_setprio(0); } while (0)
; #define PG8_WAIT_V89() do { if constexpr (SLIVER) PG8_WAIT_V(9); else PG8_WAIT_V(8); } while (0)
; #define PG8_STAGE_S(b, gbase) do { if constexpr (SLIVER) __builtin_amdgcn_global_load_lds((const unsigned*)((const char*)(gbase) + voffS), (PG8_LAS unsigned*)(lds + STAGE_BYTES + (b) * 2048 + wid * 256), 4, 0, 0); } while (0)
; #define PG8_WAIT_L(n) asm volatile("s_waitcnt lgkmcnt(" #n ")" ::: "memory")
; #define PG8_BAR __builtin_amdgcn_s_barrier()
; #define PG8_SCHED __builtin_amdgcn_sched_barrier(0)
; template <class Epi, class Sched, bool ALIGN_EPI = false, bool SP2 = false, bool SLIVER = false>
; __device__ __forceinline__ void gemm_phase(PG8_LAS unsigned char* lds, const Gemm g, const Sched& S, const Epi& E) {
;     ...
;             PG8_WAIT_V89(); PG8_WAIT_L(0); PG8_BAR; PG8_MMA(1, 0, At, B0); PG8_MMA(1, 1, At, B1); PG8_MMA_S(); PG8_BAR; PG8_SCHED;
;             PG8_LDB(B0, 1, 0); PG8_LDB(B1, 1, 1); PG8_SCHED; PG8_LDA(At, 1, 0); PG8_STAGE(PG8_SA(0, 1), a2 + hstep, voffA); PG8_STAGE_S(0, s2);
;             PG8_WAIT_V89(); PG8_WAIT_L(0); PG8_BAR; PG8_MMA(0, 0, At, B0); PG8_MMA(0, 1, At, B1); PG8_BAR; PG8_SCHED;
	v_mfma_f32_16x16x32_bf16 v[62:65], v[146:149], v[138:141], v[62:65]
	v_mfma_f32_16x16x32_bf16 v[58:61], v[154:157], v[138:141], v[58:61]
	v_mfma_f32_16x16x32_bf16 v[54:57], v[146:149], v[196:199], v[54:57]
	v_mfma_f32_16x16x32_bf16 v[50:53], v[154:157], v[196:199], v[50:53]
	v_mfma_f32_16x16x32_bf16 v[46:49], v[146:149], v[220:223], v[46:49]
	v_mfma_f32_16x16x32_bf16 v[42:45], v[154:157], v[220:223], v[42:45]
	v_mfma_f32_16x16x32_bf16 v[38:41], v[146:149], v[228:231], v[38:41]
	v_mfma_f32_16x16x32_bf16 v[34:37], v[154:157], v[228:231], v[34:37]
	v_mfma_f32_16x16x32_bf16 v[62:65], v[150:153], v[142:145], v[62:65]
	v_mfma_f32_16x16x32_bf16 v[58:61], v[158:161], v[142:145], v[58:61]
	v_mfma_f32_16x16x32_bf16 v[54:57], v[150:153], v[200:203], v[54:57]
	v_mfma_f32_16x16x32_bf16 v[50:53], v[158:161], v[200:203], v[50:53]
	v_mfma_f32_16x16x32_bf16 v[46:49], v[150:153], v[224:227], v[46:49]
	v_mfma_f32_16x16x32_bf16 v[42:45], v[158:161], v[224:227], v[42:45]
	v_mfma_f32_16x16x32_bf16 v[38:41], v[150:153], v[232:235], v[38:41]
	v_mfma_f32_16x16x32_bf16 v[34:37], v[158:161], v[232:235], v[34:37]
	s_setprio 0
	s_setprio 1
	v_mfma_f32_16x16x32_bf16 v[30:33], v[166:169], v[138:141], v[30:33]
	v_mfma_f32_16x16x32_bf16 v[26:29], v[174:177], v[138:141], v[26:29]
	v_mfma_f32_16x16x32_bf16 v[22:25], v[166:169], v[196:199], v[22:25]
	v_mfma_f32_16x16x32_bf16 v[18:21], v[174:177], v[196:199], v[18:21]
	v_mfma_f32_16x16x32_bf16 v[14:17], v[166:169], v[220:223], v[14:17]
	v_mfma_f32_16x16x32_bf16 v[10:13], v[174:177], v[220:223], v[10:13]
	v_mfma_f32_16x16x32_bf16 v[6:9], v[166:169], v[228:231], v[6:9]
	v_mfma_f32_16x16x32_bf16 v[2:5], v[174:177], v[228:231], v[2:5]
	v_mfma_f32_16x16x32_bf16 v[30:33], v[170:173], v[142:145], v[30:33]
	v_mfma_f32_16x16x32_bf16 v[26:29], v[162:165], v[142:145], v[26:29]
	v_mfma_f32_16x16x32_bf16 v[22:25], v[170:173], v[200:203], v[22:25]
	v_mfma_f32_16x16x32_bf16 v[18:21], v[162:165], v[200:203], v[18:21]
	v_mfma_f32_16x16x32_bf16 v[14:17], v[170:173], v[224:227], v[14:17]
	v_mfma_f32_16x16x32_bf16 v[10:13], v[162:165], v[224:227], v[10:13]
	v_mfma_f32_16x16x32_bf16 v[6:9], v[170:173], v[232:235], v[6:9]
	v_mfma_f32_16x16x32_bf16 v[2:5], v[162:165], v[232:235], v[2:5]
	s_setprio 0
	s_setprio 1
	v_mfma_f32_16x16x32_bf16 v[82:85], v[146:149], v[180:183], v[82:85]
	v_mfma_f32_16x16x32_bf16 v[138:141], v[150:153], v[184:187], v[82:85]
	v_mfma_f32_16x16x32_bf16 v[82:85], v[154:157], v[180:183], v[94:97]
	v_mfma_f32_16x16x32_bf16 v[142:145], v[158:161], v[184:187], v[82:85]
	s_barrier
	s_setprio 0
	s_add_u32 s68, s62, s80
	s_addc_u32 s69, s63, s81
	s_add_u32 s76, s68, 0x100
	s_addc_u32 s77, s69, 0
	s_and_b64 s[68:69], s[86:87], exec
	s_cselect_b32 s69, s85, s77
	s_cselect_b32 s68, s84, s76
	s_add_i32 s76, 0, 0x18000
	v_add_u32_e32 v82, s76, v239
	s_add_i32 s77, 0, 0x1c000
	ds_read_b128 v[146:149], v82
	ds_read_b128 v[150:153], v82 offset:1024
	ds_read_b128 v[154:157], v82 offset:2048
	ds_read_b128 v[158:161], v82 offset:3072
	v_add_u32_e32 v82, s77, v239
	ds_read_b128 v[166:169], v82
	ds_read_b128 v[170:173], v82 offset:1024
	ds_read_b128 v[174:177], v82 offset:2048
	ds_read_b128 v[162:165], v82 offset:3072
	s_mov_b32 m0, s91
	v_lshl_add_u64 v[208:209], v[194:195], 0, s[24:25]
	ds_read_b128 v[82:85], v242 offset:32768
	ds_read_b128 v[94:97], v242 offset:33792
	ds_read_b128 v[180:183], v242 offset:34816
	ds_read_b128 v[184:187], v242 offset:35840
	ds_read_b128 v[196:199], v242 offset:36864
	ds_read_b128 v[200:203], v242 offset:37888
	ds_read_b128 v[220:223], v242 offset:38912
	ds_read_b128 v[224:227], v242 offset:39936
	global_load_lds_dwordx4 v[208:209], off
	v_lshl_add_u64 v[208:209], v[194:195], 0, s[14:15]
	s_mov_b32 m0, s92
	s_nop 0
	global_load_lds_dwordx4 v[208:209], off
	v_lshl_add_u64 v[208:209], s[68:69], 0, v[214:215]
	s_mov_b32 m0, s93
	s_nop 0
	global_load_lds_dword v[208:209], off
	s_waitcnt vmcnt(9)
	s_waitcnt lgkmcnt(0)
	s_setprio 1
	s_barrier
; #define PG8_SB(B) __builtin_amdgcn_rcpf(1.f + expneg(B))
; #define PG8_SB(B) __builtin_amdgcn_rcpf(1.f + expneg(B))
; #define PG8_STAGE(bufoff, gbase, voff) do { _Pragma("unroll") for (int _i = 0; _i < 2; ++_i) \
;         __builtin_amdgcn_global_load_lds((const unsigned*)((const char*)(gbase) + (size_t)_i * qstep + (voff)[0]), (PG8_LAS unsigned*)(lds + (bufoff) + ldsw + _i * 8192), 16, 0, 0); } while (0)
; #define PG8_LDA(dst, b, h) do { _Pragma("unroll") for (int m = 0; m < 4; ++m) _Pragma("unroll") for (int k = 0; k < 2; ++k) dst[m][k] = *(const PG8_LAS bf16x8*)(lds + PG8_SA(b, h) + aoff + m * 2048 + k * 1024); } while (0)
; #define PG8_MMA(ai, bj, At, Bt) do { __builtin_amdgcn_s_setprio(1); _Pragma("unroll") for (int m = 0; m < 4; ++m) _Pragma("unroll") for (int n = 0; n < 2; ++n) _Pragma("unroll") for (int k = 0; k < 2; ++k) \
;         acc[ai][bj][m][n] = __builtin_amdgcn_mfma_f32_16x16x32_bf16(Bt[n][k], At[m][k], acc[ai][bj][m][n], 0, 0, 0); __builtin_amdgcn_s_setprio(0); } while (0)
; #define PG8_WAIT_V89() do { if constexpr (SLIVER) PG8_WAIT_V(9); else PG8_WAIT_V(8); } while (0)
; #define PG8_LDS_S(b) do { if constexpr (SLIVER) { Sf[0] = *(const PG8_LAS bf16x8*)(lds + STAGE_BYTES + (b) * 2048 + soff0); Sf[1] = *(const PG8_LAS bf16x8*)(lds + STAGE_BYTES + (b) * 2048 + (soff0 ^ 64)); } } while (0)
; #define PG8_WAIT_L(n) asm volatile("s_waitcnt lgkmcnt(" #n ")" ::: "memory")
; #define PG8_BAR __builtin_amdgcn_s_barrier()
; #define PG8_SCHED __builtin_amdgcn_sched_barrier(0)
; template <class Epi, class Sched, bool ALIGN_EPI = false, bool SP2 = false, bool SLIVER = false>
; __device__ __forceinline__ void gemm_phase(PG8_LAS unsigned char* lds, const Gemm g, const Sched& S, const Epi& E) {
;     ...
;             PG8_WAIT_V89(); PG8_WAIT_L(0); PG8_BAR; PG8_MMA(0, 0, At, B0); PG8_MMA(0, 1, At, B1); PG8_BAR; PG8_SCHED;
;             PG8_LDA(At, 1, 1); PG8_LDS_S(1); PG8_STAGE(PG8_SB(1, 0), b3, voffB); PG8_STAGE(PG8_SB(1, 1), b3 + hstep, voffB); PG8_STAGE(PG8_SA(1, 0), a3, voffA);
;             PG8_WAIT_V89(); PG8_WAIT_L(0); PG8_BAR; PG8_MMA(1, 0, At, B0); PG8_MMA(1, 1, At, B1); PG8_MMA_S(); PG8_BAR; PG8_SCHED;
	v_mfma_f32_16x16x32_bf16 v[134:137], v[146:149], v[82:85], v[134:137]
	v_mfma_f32_16x16x32_bf16 v[130:133], v[154:157], v[82:85], v[130:133]
	v_mfma_f32_16x16x32_bf16 v[126:129], v[146:149], v[180:183], v[126:129]
	v_mfma_f32_16x16x32_bf16 v[122:125], v[154:157], v[180:183], v[122:125]
	v_mfma_f32_16x16x32_bf16 v[118:121], v[146:149], v[196:199], v[118:121]
	v_mfma_f32_16x16x32_bf16 v[114:117], v[154:157], v[196:199], v[114:117]
	v_mfma_f32_16x16x32_bf16 v[110:113], v[146:149], v[220:223], v[110:113]
	v_mfma_f32_16x16x32_bf16 v[106:109], v[154:157], v[220:223], v[106:109]
	v_mfma_f32_16x16x32_bf16 v[134:137], v[150:153], v[94:97], v[134:137]
	v_mfma_f32_16x16x32_bf16 v[130:133], v[158:161], v[94:97], v[130:133]
	v_mfma_f32_16x16x32_bf16 v[126:129], v[150:153], v[184:187], v[126:129]
	v_mfma_f32_16x16x32_bf16 v[122:125], v[158:161], v[184:187], v[122:125]
	v_mfma_f32_16x16x32_bf16 v[118:121], v[150:153], v[200:203], v[118:121]
	v_mfma_f32_16x16x32_bf16 v[114:117], v[158:161], v[200:203], v[114:117]
	v_mfma_f32_16x16x32_bf16 v[110:113], v[150:153], v[224:227], v[110:113]
	v_mfma_f32_16x16x32_bf16 v[106:109], v[158:161], v[224:227], v[106:109]
	s_setprio 0
	s_setprio 1
	v_mfma_f32_16x16x32_bf16 v[102:105], v[166:169], v[82:85], v[102:105]
	v_mfma_f32_16x16x32_bf16 v[82:85], v[174:177], v[82:85], v[98:101]
	v_mfma_f32_16x16x32_bf16 v[98:101], v[162:165], v[94:97], v[82:85]
	v_mfma_f32_16x16x32_bf16 v[82:85], v[166:169], v[180:183], v[90:93]
	v_mfma_f32_16x16x32_bf16 v[90:93], v[170:173], v[184:187], v[82:85]
	v_mfma_f32_16x16x32_bf16 v[82:85], v[174:177], v[180:183], v[86:89]
	v_mfma_f32_16x16x32_bf16 v[78:81], v[166:169], v[196:199], v[78:81]
	v_mfma_f32_16x16x32_bf16 v[74:77], v[174:177], v[196:199], v[74:77]
	v_mfma_f32_16x16x32_bf16 v[70:73], v[166:169], v[220:223], v[70:73]
	v_mfma_f32_16x16x32_bf16 v[66:69], v[174:177], v[220:223], v[66:69]
	v_mfma_f32_16x16x32_bf16 v[102:105], v[170:173], v[94:97], v[102:105]
	v_mfma_f32_16x16x32_bf16 v[86:89], v[162:165], v[184:187], v[82:85]
	v_mfma_f32_16x16x32_bf16 v[78:81], v[170:173], v[200:203], v[78:81]
	v_mfma_f32_16x16x32_bf16 v[74:77], v[162:165], v[200:203], v[74:77]
	v_mfma_f32_16x16x32_bf16 v[70:73], v[170:173], v[224:227], v[70:73]
	v_mfma_f32_16x16x32_bf16 v[66:69], v[162:165], v[224:227], v[66:69]
	s_barrier
	s_setprio 0
	s_add_i32 s68, 0, 0x20800
	v_add_u32_e32 v178, s68, v240
	v_add_u32_e32 v184, s68, v241
	s_add_i32 s68, s76, s95
	v_lshl_add_u64 v[208:209], v[192:193], 0, s[26:27]
	s_mov_b32 m0, s68
	ds_read_b128 v[82:85], v242 offset:49152
	ds_read_b128 v[94:97], v242 offset:50176
	ds_read_b128 v[196:199], v242 offset:51200
	ds_read_b128 v[200:203], v242 offset:52224
	ds_read_b128 v[220:223], v242 offset:53248
	ds_read_b128 v[224:227], v242 offset:54272
	ds_read_b128 v[228:231], v242 offset:55296
	ds_read_b128 v[232:235], v242 offset:56320
	ds_read_b128 v[180:183], v178
	ds_read_b128 v[184:187], v184
	global_load_lds_dwordx4 v[208:209], off
	v_lshl_add_u64 v[208:209], v[192:193], 0, s[72:73]
	s_add_i32 m0, s68, 0x2000
	s_add_i32 s68, s77, s95
	global_load_lds_dwordx4 v[208:209], off
	v_lshl_add_u64 v[208:209], v[192:193], 0, s[34:35]
	s_mov_b32 m0, s68
	s_mov_b64 s[76:77], 0x120080
	global_load_lds_dwordx4 v[208:209], off
	v_lshl_add_u64 v[192:193], v[192:193], 0, s[76:77]
	s_add_i32 m0, s68, 0x2000
	s_nop 0
	global_load_lds_dwordx4 v[192:193], off
	v_lshl_add_u64 v[192:193], v[194:195], 0, s[26:27]
	s_mov_b32 m0, s97
	s_nop 0
	global_load_lds_dwordx4 v[192:193], off
	v_lshl_add_u64 v[192:193], v[194:195], 0, s[72:73]
	s_mov_b32 m0, s18
	s_nop 0
	global_load_lds_dwordx4 v[192:193], off
	s_waitcnt vmcnt(9)
	s_waitcnt lgkmcnt(0)
	s_setprio 1
	s_barrier
	v_mfma_f32_16x16x32_bf16 v[62:65], v[146:149], v[82:85], v[62:65]
	v_mfma_f32_16x16x32_bf16 v[58:61], v[154:157], v[82:85], v[58:61]
	v_mfma_f32_16x16x32_bf16 v[54:57], v[146:149], v[196:199], v[54:57]
	v_mfma_f32_16x16x32_bf16 v[50:53], v[154:157], v[196:199], v[50:53]
	v_mfma_f32_16x16x32_bf16 v[46:49], v[146:149], v[220:223], v[46:49]
	v_mfma_f32_16x16x32_bf16 v[42:45], v[154:157], v[220:223], v[42:45]
	v_mfma_f32_16x16x32_bf16 v[38:41], v[146:149], v[228:231], v[38:41]
	v_mfma_f32_16x16x32_bf16 v[34:37], v[154:157], v[228:231], v[34:37]
	v_mfma_f32_16x16x32_bf16 v[62:65], v[150:153], v[94:97], v[62:65]
	v_mfma_f32_16x16x32_bf16 v[58:61], v[158:161], v[94:97], v[58:61]
	v_mfma_f32_16x16x32_bf16 v[54:57], v[150:153], v[200:203], v[54:57]
	v_mfma_f32_16x16x32_bf16 v[50:53], v[158:161], v[200:203], v[50:53]
	v_mfma_f32_16x16x32_bf16 v[46:49], v[150:153], v[224:227], v[46:49]
	v_mfma_f32_16x16x32_bf16 v[42:45], v[158:161], v[224:227], v[42:45]
	v_mfma_f32_16x16x32_bf16 v[38:41], v[150:153], v[232:235], v[38:41]
	v_mfma_f32_16x16x32_bf16 v[34:37], v[158:161], v[232:235], v[34:37]
	s_setprio 0
	s_setprio 1
	v_mfma_f32_16x16x32_bf16 v[30:33], v[166:169], v[82:85], v[30:33]
	v_mfma_f32_16x16x32_bf16 v[26:29], v[174:177], v[82:85], v[26:29]
	v_mfma_f32_16x16x32_bf16 v[22:25], v[166:169], v[196:199], v[22:25]
	v_mfma_f32_16x16x32_bf16 v[18:21], v[174:177], v[196:199], v[18:21]
	v_mfma_f32_16x16x32_bf16 v[14:17], v[166:169], v[220:223], v[14:17]
	v_mfma_f32_16x16x32_bf16 v[10:13], v[174:177], v[220:223], v[10:13]
	v_mfma_f32_16x16x32_bf16 v[6:9], v[166:169], v[228:231], v[6:9]
	v_mfma_f32_16x16x32_bf16 v[2:5], v[174:177], v[228:231], v[2:5]
	v_mfma_f32_16x16x32_bf16 v[30:33], v[170:173], v[94:97], v[30:33]
	v_mfma_f32_16x16x32_bf16 v[26:29], v[162:165], v[94:97], v[26:29]
	v_mfma_f32_16x16x32_bf16 v[22:25], v[170:173], v[200:203], v[22:25]
	v_mfma_f32_16x16x32_bf16 v[18:21], v[162:165], v[200:203], v[18:21]
	v_mfma_f32_16x16x32_bf16 v[14:17], v[170:173], v[224:227], v[14:17]
	v_mfma_f32_16x16x32_bf16 v[10:13], v[162:165], v[224:227], v[10:13]
	v_mfma_f32_16x16x32_bf16 v[6:9], v[170:173], v[232:235], v[6:9]
	v_mfma_f32_16x16x32_bf16 v[2:5], v[162:165], v[232:235], v[2:5]
	s_setprio 0
	s_setprio 1
	v_mfma_f32_16x16x32_bf16 v[82:85], v[146:149], v[180:183], v[138:141]
	v_mfma_f32_16x16x32_bf16 v[94:97], v[154:157], v[180:183], v[142:145]
	v_mfma_f32_16x16x32_bf16 v[82:85], v[150:153], v[184:187], v[82:85]
	v_mfma_f32_16x16x32_bf16 v[94:97], v[158:161], v[184:187], v[94:97]
	s_branch .LslvB_lend0

; template <class Epi, class Sched, bool ALIGN_EPI = false, bool SP2 = false, bool SLIVER = false>
; __device__ __forceinline__ void gemm_phase(PG8_LAS unsigned char* lds, const Gemm g, const Sched& S, const Epi& E) {
;     ...
;         const bool has_next = S.next(ui + 1, nxt);
;         const char* nA = has_next ? (const char*)g.A + (size_t)nxt.pm * tstep + Epi::k0(nxt.seg) * 2 : cA; const char* nB = has_next ? (const char*)g.Bt + (size_t)nxt.pn * tstep + Epi::k0(nxt.seg) * 2 : cB;
;         const char* nS = has_next ? (const char*)g.A + (size_t)S.srow0 * K * 2 + (size_t)nxt.pm * sstep + Epi::k0(nxt.seg) * 2 : cS;
;     ...
;         if (fin) {
; #pragma unroll
;         for (int a = 0; a < 2; ++a)
; #pragma unroll
;             for (int b = 0; b < 2; ++b)
; #pragma unroll
;                 for (int m = 0; m < 4; ++m)
; #pragma unroll
;                     for (int n = 0; n < 2; ++n) acc[a][b][m][n] = (f32x4){0.f, 0.f, 0.f, 0.f};
;         accs[0] = (f32x4){0.f, 0.f, 0.f, 0.f}; accs[1] = (f32x4){0.f, 0.f, 0.f, 0.f};
;         }
;         cur = nxt; cA = nA; cB = nB; cS = nS; nt = Epi::nt(cur.seg, K); ++ui;
.LBB0_596:
	s_ashr_i32 s83, s82, 31
	s_lshl_b64 s[12:13], s[82:83], 20
	v_readlane_b32 s17, v254, 45
	s_add_u32 s86, s17, s12
	v_readlane_b32 s12, v254, 39
	s_addc_u32 s87, s12, s13
	s_and_b64 s[12:13], s[38:39], exec
	s_cselect_b32 s12, s87, s93
	s_cselect_b32 s13, s86, s92
	s_ashr_i32 s55, s54, 31
	s_lshl_b64 s[62:63], s[54:55], 20
	v_readlane_b32 s17, v254, 50
	s_add_u32 s88, s17, s62
	v_readlane_b32 s17, v254, 53
	s_addc_u32 s89, s17, s63
	s_and_b64 s[62:63], s[38:39], exec
	s_cselect_b32 s17, s89, s41
	s_cselect_b32 s55, s88, s40
	s_lshl_b64 s[62:63], s[82:83], 16
	v_readlane_b32 s66, v254, 47
	s_add_u32 s90, s66, s62
	v_readlane_b32 s62, v254, 48
	s_addc_u32 s91, s62, s63
	s_and_b64 s[62:63], s[38:39], exec
	v_lshl_add_u64 v[2:3], s[94:95], 0, v[194:195]
	v_mov_b32_e32 v178, v179
	s_cselect_b32 s66, s91, s95
	s_cselect_b32 s67, s90, s94
	v_lshl_add_u64 v[198:199], v[2:3], 0, s[26:27]
	s_add_u32 s68, s40, 0x100
	v_mov_b32_e32 v180, v179
	v_mov_b32_e32 v181, v179
	v_mov_b32_e32 v10, 0
	v_mov_b64_e32 v[2:3], v[178:179]
	v_mov_b64_e32 v[6:7], v[178:179]
	v_lshl_add_u64 v[200:201], s[92:93], 0, v[196:197]
	s_addc_u32 s69, s41, 0
	s_mov_b32 s76, -2
	s_mov_b64 s[62:63], 0
	v_mov_b64_e32 v[4:5], v[180:181]
	v_mov_b64_e32 v[8:9], v[180:181]
	v_mov_b32_e32 v11, v10
	v_mov_b32_e32 v12, v10
	v_mov_b32_e32 v13, v10
	v_mov_b32_e32 v14, v10
	v_mov_b32_e32 v15, v10
	v_mov_b32_e32 v16, v10
	v_mov_b32_e32 v17, v10
	v_mov_b32_e32 v26, v10
	v_mov_b32_e32 v27, v10
	v_mov_b32_e32 v28, v10
	v_mov_b32_e32 v29, v10
	v_mov_b32_e32 v30, v10
	v_mov_b32_e32 v31, v10
	v_mov_b32_e32 v32, v10
	v_mov_b32_e32 v33, v10
	v_mov_b32_e32 v42, v10
	v_mov_b32_e32 v43, v10
	v_mov_b32_e32 v44, v10
	v_mov_b32_e32 v45, v10
	v_mov_b32_e32 v46, v10
	v_mov_b32_e32 v47, v10
	v_mov_b32_e32 v48, v10
	v_mov_b32_e32 v49, v10
	v_mov_b32_e32 v58, v10
	v_mov_b32_e32 v59, v10
	v_mov_b32_e32 v60, v10
	v_mov_b32_e32 v61, v10
	v_mov_b32_e32 v62, v10
	v_mov_b32_e32 v63, v10
	v_mov_b32_e32 v64, v10
	v_mov_b32_e32 v65, v10
	v_mov_b32_e32 v18, v10
	v_mov_b32_e32 v19, v10
	v_mov_b32_e32 v20, v10
	v_mov_b32_e32 v21, v10
	v_mov_b32_e32 v22, v10
	v_mov_b32_e32 v23, v10
	v_mov_b32_e32 v24, v10
	v_mov_b32_e32 v25, v10
	v_mov_b32_e32 v34, v10
	v_mov_b32_e32 v35, v10
	v_mov_b32_e32 v36, v10
	v_mov_b32_e32 v37, v10
	v_mov_b32_e32 v38, v10
	v_mov_b32_e32 v39, v10
	v_mov_b32_e32 v40, v10
	v_mov_b32_e32 v41, v10
	v_mov_b32_e32 v50, v10
	v_mov_b32_e32 v51, v10
	v_mov_b32_e32 v52, v10
	v_mov_b32_e32 v53, v10
	v_mov_b32_e32 v54, v10
	v_mov_b32_e32 v55, v10
	v_mov_b32_e32 v56, v10
	v_mov_b32_e32 v57, v10
	v_mov_b32_e32 v66, v10
	v_mov_b32_e32 v67, v10
	v_mov_b32_e32 v68, v10
	v_mov_b32_e32 v69, v10
	v_mov_b32_e32 v70, v10
	v_mov_b32_e32 v71, v10
	v_mov_b32_e32 v72, v10
	v_mov_b32_e32 v73, v10
	v_mov_b32_e32 v74, v10
	v_mov_b32_e32 v75, v10
	v_mov_b32_e32 v76, v10
	v_mov_b32_e32 v77, v10
	v_mov_b32_e32 v78, v10
	v_mov_b32_e32 v79, v10
	v_mov_b32_e32 v80, v10
	v_mov_b32_e32 v81, v10
	v_mov_b32_e32 v90, v10
	v_mov_b32_e32 v91, v10
	v_mov_b32_e32 v92, v10
	v_mov_b32_e32 v93, v10
	v_mov_b32_e32 v94, v10
	v_mov_b32_e32 v95, v10
	v_mov_b32_e32 v96, v10
	v_mov_b32_e32 v97, v10
	v_mov_b32_e32 v106, v10
	v_mov_b32_e32 v107, v10
	v_mov_b32_e32 v108, v10
	v_mov_b32_e32 v109, v10
	v_mov_b32_e32 v110, v10
	v_mov_b32_e32 v111, v10
	v_mov_b32_e32 v112, v10
	v_mov_b32_e32 v113, v10
	v_mov_b32_e32 v122, v10
	v_mov_b32_e32 v123, v10
	v_mov_b32_e32 v124, v10
	v_mov_b32_e32 v125, v10
	v_mov_b32_e32 v126, v10
	v_mov_b32_e32 v127, v10
	v_mov_b32_e32 v128, v10
	v_mov_b32_e32 v129, v10
	v_mov_b32_e32 v82, v10
	v_mov_b32_e32 v83, v10
	v_mov_b32_e32 v84, v10
	v_mov_b32_e32 v85, v10
	v_mov_b32_e32 v86, v10
	v_mov_b32_e32 v87, v10
	v_mov_b32_e32 v88, v10
	v_mov_b32_e32 v89, v10
	v_mov_b32_e32 v98, v10
	v_mov_b32_e32 v99, v10
	v_mov_b32_e32 v100, v10
	v_mov_b32_e32 v101, v10
	v_mov_b32_e32 v102, v10
	v_mov_b32_e32 v103, v10
	v_mov_b32_e32 v104, v10
	v_mov_b32_e32 v105, v10
	v_mov_b32_e32 v114, v10
	v_mov_b32_e32 v115, v10
	v_mov_b32_e32 v116, v10
	v_mov_b32_e32 v117, v10
	v_mov_b32_e32 v118, v10
	v_mov_b32_e32 v119, v10
	v_mov_b32_e32 v120, v10
	v_mov_b32_e32 v121, v10
	v_mov_b32_e32 v130, v10
	v_mov_b32_e32 v131, v10
	v_mov_b32_e32 v132, v10
	v_mov_b32_e32 v133, v10
	v_mov_b32_e32 v134, v10
	v_mov_b32_e32 v135, v10
	v_mov_b32_e32 v136, v10
	v_mov_b32_e32 v137, v10
	s_and_b64 vcc, exec, s[52:53]
	s_cbranch_vccz .LslvB_hdr1
	s_branch .LBB0_598

; #define PG8_SB(B) __builtin_amdgcn_rcpf(1.f + expneg(B))
; #define PG8_SB(B) __builtin_amdgcn_rcpf(1.f + expneg(B))
; #define PG8_STAGE(bufoff, gbase, voff) do { _Pragma("unroll") for (int _i = 0; _i < 2; ++_i) \
;         __builtin_amdgcn_global_load_lds((const unsigned*)((const char*)(gbase) + (size_t)_i * qstep + (voff)[0]), (PG8_LAS unsigned*)(lds + (bufoff) + ldsw + _i * 8192), 16, 0, 0); } while (0)
; #define PG8_LDA(dst, b, h) do { _Pragma("unroll") for (int m = 0; m < 4; ++m) _Pragma("unroll") for (int k = 0; k < 2; ++k) dst[m][k] = *(const PG8_LAS bf16x8*)(lds + PG8_SA(b, h) + aoff + m * 2048 + k * 1024); } while (0)
; #define PG8_LDB(dst, b, h) do { _Pragma("unroll") for (int n = 0; n < 2; ++n) _Pragma("unroll") for (int k = 0; k < 2; ++k) dst[n][k] = *(const PG8_LAS bf16x8*)(lds + PG8_SB(b, h) + boff + n * 2048 + k * 1024); } while (0)
; #define PG8_WAIT_V89() do { if constexpr (SLIVER) PG8_WAIT_V(9); else PG8_WAIT_V(8); } while (0)
; #define PG8_STAGE_S(b, gbase) do { if constexpr (SLIVER) __builtin_amdgcn_global_load_lds((const unsigned*)((const char*)(gbase) + voffS), (PG8_LAS unsigned*)(lds + STAGE_BYTES + (b) * 2048 + wid * 256), 4, 0, 0); } while (0)
; template <class Epi, class Sched, bool ALIGN_EPI = false, bool SP2 = false, bool SLIVER = false>
; __device__ __forceinline__ void gemm_phase(PG8_LAS unsigned char* lds, const Gemm g, const Sched& S, const Epi& E) {
;     ...
;         for (int t = 0; t < nt; t += 2) {
;             const bool last = (t == nt - 2);
;             const char* a1 = cA + (size_t)(t + 1) * kstep;
;             const char* a2 = last ? nA : cA + (size_t)(t + 2) * kstep; const char* b2 = last ? nB : cB + (size_t)(t + 2) * kstep;
;             const char* a3 = a2 + kstep; const char* b3 = b2 + kstep;
;             const char* s1 = cS + (size_t)(t + 1) * kstep; const char* s2 = last ? nS : cS + (size_t)(t + 2) * kstep;
;             if (last && has_next) S.a_ready(nxt);
;             if constexpr (SP2) {
;             PG8_LDB(B0, 0, 0); PG8_LDB(B1, 0, 1); PG8_SCHED; PG8_LDA(At, 0, 0); PG8_STAGE(PG8_SA(1, 1), a1 + hstep, voffA); PG8_STAGE_S(1, s1);
;             PG8_WAIT_V89(); PG8_WAIT_L(0); PG8_BAR; PG8_MMA(0, 0, At, B0); PG8_MMA(0, 1, At, B1); PG8_BAR; PG8_SCHED;
;             PG8_LDA(At, 0, 1); PG8_LDS_S(0); PG8_STAGE(PG8_SB(0, 0), b2, voffB); PG8_STAGE(PG8_SB(0, 1), b2 + hstep, voffB); PG8_STAGE(PG8_SA(0, 0), a2, voffA);
.LBB0_598:
	s_add_u32 s40, s92, s62
	s_addc_u32 s41, s93, s63
	s_add_u32 s77, s40, 0x100
	s_addc_u32 s78, s41, 0
	s_add_u32 s83, s68, s62
	s_addc_u32 s79, s69, s63
	s_add_i32 s96, 0, 0x10000
	s_cmpk_eq_i32 s62, 0xf00
	s_cselect_b64 s[80:81], -1, 0
	s_and_b64 s[40:41], s[80:81], exec
	s_cselect_b32 s41, s12, s78
	s_cselect_b32 s40, s13, s77
	v_add_u32_e32 v138, s96, v212
	s_cselect_b32 s79, s17, s79
	s_cselect_b32 s78, s55, s83
	s_add_i32 s77, 0, 0x14000
	ds_read_b128 v[146:149], v138
	ds_read_b128 v[150:153], v138 offset:1024
	ds_read_b128 v[154:157], v138 offset:2048
	ds_read_b128 v[158:161], v138 offset:3072
	v_add_u32_e32 v138, s77, v212
	ds_read_b128 v[166:169], v138
	ds_read_b128 v[170:173], v138 offset:1024
	ds_read_b128 v[174:177], v138 offset:2048
	ds_read_b128 v[162:165], v138 offset:3072
	v_lshl_add_u64 v[202:203], v[200:201], 0, s[62:63]
	v_lshl_add_u64 v[208:209], v[202:203], 0, s[30:31]
	s_add_i32 m0, s85, 0xc000
	ds_read_b128 v[138:141], v215
	ds_read_b128 v[142:145], v215 offset:1024
	ds_read_b128 v[180:183], v215 offset:2048
	ds_read_b128 v[184:187], v215 offset:3072
	ds_read_b128 v[216:219], v215 offset:4096
	ds_read_b128 v[220:223], v215 offset:5120
	ds_read_b128 v[224:227], v215 offset:6144
	ds_read_b128 v[228:231], v215 offset:7168
	global_load_lds_dwordx4 v[208:209], off
	v_lshl_add_u64 v[202:203], v[202:203], 0, s[34:35]
	s_add_i32 m0, s85, 0xe000
	s_nop 0
	global_load_lds_dwordx4 v[202:203], off
	v_lshl_add_u64 v[202:203], v[198:199], 0, s[62:63]
	s_add_i32 m0, s45, 0x20800
	s_nop 0
	global_load_lds_dword v[202:203], off
	s_waitcnt vmcnt(9)
	s_waitcnt lgkmcnt(0)
	s_setprio 1
	s_barrier
	v_mfma_f32_16x16x32_bf16 v[134:137], v[146:149], v[138:141], v[134:137]
	v_mfma_f32_16x16x32_bf16 v[130:133], v[154:157], v[138:141], v[130:133]
	v_mfma_f32_16x16x32_bf16 v[118:121], v[146:149], v[180:183], v[118:121]
	v_mfma_f32_16x16x32_bf16 v[114:117], v[154:157], v[180:183], v[114:117]
	v_mfma_f32_16x16x32_bf16 v[102:105], v[146:149], v[216:219], v[102:105]
	v_mfma_f32_16x16x32_bf16 v[98:101], v[154:157], v[216:219], v[98:101]
	v_mfma_f32_16x16x32_bf16 v[86:89], v[146:149], v[224:227], v[86:89]
	v_mfma_f32_16x16x32_bf16 v[82:85], v[154:157], v[224:227], v[82:85]
	v_mfma_f32_16x16x32_bf16 v[134:137], v[150:153], v[142:145], v[134:137]
	v_mfma_f32_16x16x32_bf16 v[130:133], v[158:161], v[142:145], v[130:133]
	v_mfma_f32_16x16x32_bf16 v[118:121], v[150:153], v[184:187], v[118:121]
	v_mfma_f32_16x16x32_bf16 v[114:117], v[158:161], v[184:187], v[114:117]
	v_mfma_f32_16x16x32_bf16 v[102:105], v[150:153], v[220:223], v[102:105]
	v_mfma_f32_16x16x32_bf16 v[98:101], v[158:161], v[220:223], v[98:101]
	v_mfma_f32_16x16x32_bf16 v[86:89], v[150:153], v[228:231], v[86:89]
	v_mfma_f32_16x16x32_bf16 v[82:85], v[158:161], v[228:231], v[82:85]
	s_setprio 0
	s_setprio 1
	v_mfma_f32_16x16x32_bf16 v[126:129], v[166:169], v[138:141], v[126:129]
	v_mfma_f32_16x16x32_bf16 v[122:125], v[174:177], v[138:141], v[122:125]
	v_mfma_f32_16x16x32_bf16 v[110:113], v[166:169], v[180:183], v[110:113]
	v_mfma_f32_16x16x32_bf16 v[106:109], v[174:177], v[180:183], v[106:109]
	v_mfma_f32_16x16x32_bf16 v[94:97], v[166:169], v[216:219], v[94:97]
	v_mfma_f32_16x16x32_bf16 v[90:93], v[174:177], v[216:219], v[90:93]
	v_mfma_f32_16x16x32_bf16 v[78:81], v[166:169], v[224:227], v[78:81]
	v_mfma_f32_16x16x32_bf16 v[74:77], v[174:177], v[224:227], v[74:77]
	v_mfma_f32_16x16x32_bf16 v[126:129], v[170:173], v[142:145], v[126:129]
	v_mfma_f32_16x16x32_bf16 v[122:125], v[162:165], v[142:145], v[122:125]
	v_mfma_f32_16x16x32_bf16 v[110:113], v[170:173], v[184:187], v[110:113]
	v_mfma_f32_16x16x32_bf16 v[106:109], v[162:165], v[184:187], v[106:109]
	v_mfma_f32_16x16x32_bf16 v[94:97], v[170:173], v[220:223], v[94:97]
	v_mfma_f32_16x16x32_bf16 v[90:93], v[162:165], v[220:223], v[90:93]
	v_mfma_f32_16x16x32_bf16 v[78:81], v[170:173], v[228:231], v[78:81]
	v_mfma_f32_16x16x32_bf16 v[74:77], v[162:165], v[228:231], v[74:77]
	s_barrier
	s_setprio 0
	s_add_i32 s83, 0, 0x20000
	v_lshl_add_u64 v[202:203], s[78:79], 0, v[190:191]
	s_add_i32 s78, s96, s18
	v_add_u32_e32 v178, s83, v213
	v_add_u32_e32 v184, s83, v214
	s_mov_b32 m0, s78
	ds_read_b128 v[138:141], v215 offset:16384
	ds_read_b128 v[142:145], v215 offset:17408
	ds_read_b128 v[216:219], v215 offset:18432
	ds_read_b128 v[220:223], v215 offset:19456
	ds_read_b128 v[224:227], v215 offset:20480
	ds_read_b128 v[228:231], v215 offset:21504
	ds_read_b128 v[232:235], v215 offset:22528
	ds_read_b128 v[240:243], v215 offset:23552
	ds_read_b128 v[180:183], v178
	ds_read_b128 v[184:187], v184
	global_load_lds_dwordx4 v[202:203], off
	v_lshl_add_u64 v[208:209], v[202:203], 0, s[20:21]
	s_add_i32 m0, s78, 0x2000
	s_add_i32 s77, s77, s18
	global_load_lds_dwordx4 v[208:209], off
	v_lshl_add_u64 v[208:209], v[202:203], 0, s[22:23]
	s_mov_b32 m0, s77
	v_lshl_add_u64 v[210:211], s[40:41], 0, v[188:189]
	global_load_lds_dwordx4 v[208:209], off
	v_lshl_add_u64 v[208:209], v[202:203], 0, s[24:25]
	s_add_i32 m0, s77, 0x2000
	s_nop 0
	global_load_lds_dwordx4 v[208:209], off
	s_mov_b32 m0, s85
	v_lshl_add_u64 v[208:209], v[210:211], 0, s[20:21]
	global_load_lds_dwordx4 v[210:211], off
	s_mov_b32 m0, s19
	s_nop 0
	global_load_lds_dwordx4 v[208:209], off
	s_waitcnt vmcnt(9)
	s_waitcnt lgkmcnt(0)
	s_setprio 1
	s_barrier
; #define PG8_STAGE(bufoff, gbase, voff) do { _Pragma("unroll") for (int _i = 0; _i < 2; ++_i) \
;         __builtin_amdgcn_global_load_lds((const unsigned*)((const char*)(gbase) + (size_t)_i * qstep + (voff)[0]), (PG8_LAS unsigned*)(lds + (bufoff) + ldsw + _i * 8192), 16, 0, 0); } while (0)
; #define PG8_LDA(dst, b, h) do { _Pragma("unroll") for (int m = 0; m < 4; ++m) _Pragma("unroll") for (int k = 0; k < 2; ++k) dst[m][k] = *(const PG8_LAS bf16x8*)(lds + PG8_SA(b, h) + aoff + m * 2048 + k * 1024); } while (0)
; #define PG8_LDB(dst, b, h) do { _Pragma("unroll") for (int n = 0; n < 2; ++n) _Pragma("unroll") for (int k = 0; k < 2; ++k) dst[n][k] = *(const PG8_LAS bf16x8*)(lds + PG8_SB(b, h) + boff + n * 2048 + k * 1024); } while (0)
; #define PG8_MMA(ai, bj, At, Bt) do { __builtin_amdgcn_s_setprio(1); _Pragma("unroll") for (int m = 0; m < 4; ++m) _Pragma("unroll") for (int n = 0; n < 2; ++n) _Pragma("unroll") for (int k = 0; k < 2; ++k) \
;         acc[ai][bj][m][n] = __builtin_amdgcn_mfma_f32_16x16x32_bf16(Bt[n][k], At[m][k], acc[ai][bj][m][n], 0, 0, 0); __builtin_amdgcn_s_setprio(0); } while (0)
; #define PG8_WAIT_V89() do { if constexpr (SLIVER) PG8_WAIT_V(9); else PG8_WAIT_V(8); } while (0)
; #define PG8_STAGE_S(b, gbase) do { if constexpr (SLIVER) __builtin_amdgcn_global_load_lds((const unsigned*)((const char*)(gbase) + voffS), (PG8_LAS unsigned*)(lds + STAGE_BYTES + (b) * 2048 + wid * 256), 4, 0, 0); } while (0)
; #define PG8_WAIT_L(n) asm volatile("s_waitcnt lgkmcnt(" #n ")" ::: "memory")
; #define PG8_BAR __builtin_amdgcn_s_barrier()
; #define PG8_SCHED __builtin_amdgcn_sched_barrier(0)
; template <class Epi, class Sched, bool ALIGN_EPI = false, bool SP2 = false, bool SLIVER = false>
; __device__ __forceinline__ void gemm_phase(PG8_LAS unsigned char* lds, const Gemm g, const Sched& S, const Epi& E) {
;     ...
;             PG8_WAIT_V89(); PG8_WAIT_L(0); PG8_BAR; PG8_MMA(1, 0, At, B0); PG8_MMA(1, 1, At, B1); PG8_MMA_S(); PG8_BAR; PG8_SCHED;
;             PG8_LDB(B0, 1, 0); PG8_LDB(B1, 1, 1); PG8_SCHED; PG8_LDA(At, 1, 0); PG8_STAGE(PG8_SA(0, 1), a2 + hstep, voffA); PG8_STAGE_S(0, s2);
;             PG8_WAIT_V89(); PG8_WAIT_L(0); PG8_BAR; PG8_MMA(0, 0, At, B0); PG8_MMA(0, 1, At, B1); PG8_BAR; PG8_SCHED;
	v_mfma_f32_16x16x32_bf16 v[70:73], v[146:149], v[138:141], v[70:73]
	v_mfma_f32_16x16x32_bf16 v[66:69], v[154:157], v[138:141], v[66:69]
	v_mfma_f32_16x16x32_bf16 v[54:57], v[146:149], v[216:219], v[54:57]
	v_mfma_f32_16x16x32_bf16 v[50:53], v[154:157], v[216:219], v[50:53]
	v_mfma_f32_16x16x32_bf16 v[38:41], v[146:149], v[224:227], v[38:41]
	v_mfma_f32_16x16x32_bf16 v[34:37], v[154:157], v[224:227], v[34:37]
	v_mfma_f32_16x16x32_bf16 v[22:25], v[146:149], v[232:235], v[22:25]
	v_mfma_f32_16x16x32_bf16 v[18:21], v[154:157], v[232:235], v[18:21]
	v_mfma_f32_16x16x32_bf16 v[70:73], v[150:153], v[142:145], v[70:73]
	v_mfma_f32_16x16x32_bf16 v[66:69], v[158:161], v[142:145], v[66:69]
	v_mfma_f32_16x16x32_bf16 v[54:57], v[150:153], v[220:223], v[54:57]
	v_mfma_f32_16x16x32_bf16 v[50:53], v[158:161], v[220:223], v[50:53]
	v_mfma_f32_16x16x32_bf16 v[38:41], v[150:153], v[228:231], v[38:41]
	v_mfma_f32_16x16x32_bf16 v[34:37], v[158:161], v[228:231], v[34:37]
	v_mfma_f32_16x16x32_bf16 v[22:25], v[150:153], v[240:243], v[22:25]
	v_mfma_f32_16x16x32_bf16 v[18:21], v[158:161], v[240:243], v[18:21]
	s_setprio 0
	s_setprio 1
	v_mfma_f32_16x16x32_bf16 v[62:65], v[166:169], v[138:141], v[62:65]
	v_mfma_f32_16x16x32_bf16 v[58:61], v[174:177], v[138:141], v[58:61]
	v_mfma_f32_16x16x32_bf16 v[46:49], v[166:169], v[216:219], v[46:49]
	v_mfma_f32_16x16x32_bf16 v[42:45], v[174:177], v[216:219], v[42:45]
	v_mfma_f32_16x16x32_bf16 v[30:33], v[166:169], v[224:227], v[30:33]
	v_mfma_f32_16x16x32_bf16 v[26:29], v[174:177], v[224:227], v[26:29]
	v_mfma_f32_16x16x32_bf16 v[14:17], v[166:169], v[232:235], v[14:17]
	v_mfma_f32_16x16x32_bf16 v[10:13], v[174:177], v[232:235], v[10:13]
	v_mfma_f32_16x16x32_bf16 v[62:65], v[170:173], v[142:145], v[62:65]
	v_mfma_f32_16x16x32_bf16 v[58:61], v[162:165], v[142:145], v[58:61]
	v_mfma_f32_16x16x32_bf16 v[46:49], v[170:173], v[220:223], v[46:49]
	v_mfma_f32_16x16x32_bf16 v[42:45], v[162:165], v[220:223], v[42:45]
	v_mfma_f32_16x16x32_bf16 v[30:33], v[170:173], v[228:231], v[30:33]
	v_mfma_f32_16x16x32_bf16 v[26:29], v[162:165], v[228:231], v[26:29]
	v_mfma_f32_16x16x32_bf16 v[14:17], v[170:173], v[240:243], v[14:17]
	v_mfma_f32_16x16x32_bf16 v[10:13], v[162:165], v[240:243], v[10:13]
	s_setprio 0
	s_setprio 1
	v_mfma_f32_16x16x32_bf16 v[138:141], v[166:169], v[180:183], v[6:9]
	v_mfma_f32_16x16x32_bf16 v[142:145], v[174:177], v[180:183], v[2:5]
	v_mfma_f32_16x16x32_bf16 v[138:141], v[170:173], v[184:187], v[138:141]
	v_mfma_f32_16x16x32_bf16 v[142:145], v[162:165], v[184:187], v[142:145]
	s_barrier
	s_setprio 0
	s_add_u32 s77, s94, s62
	s_addc_u32 s78, s95, s63
	s_add_u32 s77, s77, 0x100
	s_addc_u32 s83, s78, 0
	s_and_b64 s[78:79], s[80:81], exec
	s_cselect_b32 s79, s66, s83
	s_cselect_b32 s78, s67, s77
	s_add_i32 s77, 0, 0x18000
	v_add_u32_e32 v2, s77, v212
	s_add_i32 s80, 0, 0x1c000
	ds_read_b128 v[146:149], v2
	ds_read_b128 v[150:153], v2 offset:1024
	ds_read_b128 v[154:157], v2 offset:2048
	ds_read_b128 v[158:161], v2 offset:3072
	v_add_u32_e32 v2, s80, v212
	ds_read_b128 v[166:169], v2
	ds_read_b128 v[170:173], v2 offset:1024
	ds_read_b128 v[174:177], v2 offset:2048
	ds_read_b128 v[162:165], v2 offset:3072
	s_mov_b32 m0, s49
	v_lshl_add_u64 v[208:209], v[210:211], 0, s[22:23]
	ds_read_b128 v[2:5], v215 offset:32768
	ds_read_b128 v[6:9], v215 offset:33792
	ds_read_b128 v[180:183], v215 offset:34816
	ds_read_b128 v[184:187], v215 offset:35840
	ds_read_b128 v[216:219], v215 offset:36864
	ds_read_b128 v[220:223], v215 offset:37888
	ds_read_b128 v[224:227], v215 offset:38912
	ds_read_b128 v[228:231], v215 offset:39936
	global_load_lds_dwordx4 v[208:209], off
	v_lshl_add_u64 v[208:209], v[210:211], 0, s[24:25]
	s_mov_b32 m0, s50
	s_nop 0
	global_load_lds_dwordx4 v[208:209], off
	v_lshl_add_u64 v[208:209], s[78:79], 0, v[192:193]
	s_mov_b32 m0, s51
	s_nop 0
	global_load_lds_dword v[208:209], off
	s_waitcnt vmcnt(9)
	s_waitcnt lgkmcnt(0)
	s_setprio 1
	s_barrier
; #define PG8_SB(B) __builtin_amdgcn_rcpf(1.f + expneg(B))
; #define PG8_SB(B) __builtin_amdgcn_rcpf(1.f + expneg(B))
; #define PG8_STAGE(bufoff, gbase, voff) do { _Pragma("unroll") for (int _i = 0; _i < 2; ++_i) \
;         __builtin_amdgcn_global_load_lds((const unsigned*)((const char*)(gbase) + (size_t)_i * qstep + (voff)[0]), (PG8_LAS unsigned*)(lds + (bufoff) + ldsw + _i * 8192), 16, 0, 0); } while (0)
; #define PG8_LDA(dst, b, h) do { _Pragma("unroll") for (int m = 0; m < 4; ++m) _Pragma("unroll") for (int k = 0; k < 2; ++k) dst[m][k] = *(const PG8_LAS bf16x8*)(lds + PG8_SA(b, h) + aoff + m * 2048 + k * 1024); } while (0)
; #define PG8_MMA(ai, bj, At, Bt) do { __builtin_amdgcn_s_setprio(1); _Pragma("unroll") for (int m = 0; m < 4; ++m) _Pragma("unroll") for (int n = 0; n < 2; ++n) _Pragma("unroll") for (int k = 0; k < 2; ++k) \
;         acc[ai][bj][m][n] = __builtin_amdgcn_mfma_f32_16x16x32_bf16(Bt[n][k], At[m][k], acc[ai][bj][m][n], 0, 0, 0); __builtin_amdgcn_s_setprio(0); } while (0)
; #define PG8_WAIT_V89() do { if constexpr (SLIVER) PG8_WAIT_V(9); else PG8_WAIT_V(8); } while (0)
; #define PG8_LDS_S(b) do { if constexpr (SLIVER) { Sf[0] = *(const PG8_LAS bf16x8*)(lds + STAGE_BYTES + (b) * 2048 + soff0); Sf[1] = *(const PG8_LAS bf16x8*)(lds + STAGE_BYTES + (b) * 2048 + (soff0 ^ 64)); } } while (0)
; #define PG8_WAIT_L(n) asm volatile("s_waitcnt lgkmcnt(" #n ")" ::: "memory")
; #define PG8_BAR __builtin_amdgcn_s_barrier()
; #define PG8_SCHED __builtin_amdgcn_sched_barrier(0)
; template <class Epi, class Sched, bool ALIGN_EPI = false, bool SP2 = false, bool SLIVER = false>
; __device__ __forceinline__ void gemm_phase(PG8_LAS unsigned char* lds, const Gemm g, const Sched& S, const Epi& E) {
;     ...
;             PG8_WAIT_V89(); PG8_WAIT_L(0); PG8_BAR; PG8_MMA(0, 0, At, B0); PG8_MMA(0, 1, At, B1); PG8_BAR; PG8_SCHED;
;             PG8_LDA(At, 1, 1); PG8_LDS_S(1); PG8_STAGE(PG8_SB(1, 0), b3, voffB); PG8_STAGE(PG8_SB(1, 1), b3 + hstep, voffB); PG8_STAGE(PG8_SA(1, 0), a3, voffA);
;             PG8_WAIT_V89(); PG8_WAIT_L(0); PG8_BAR; PG8_MMA(1, 0, At, B0); PG8_MMA(1, 1, At, B1); PG8_MMA_S(); PG8_BAR; PG8_SCHED;
	v_mfma_f32_16x16x32_bf16 v[134:137], v[146:149], v[2:5], v[134:137]
	v_mfma_f32_16x16x32_bf16 v[130:133], v[154:157], v[2:5], v[130:133]
	v_mfma_f32_16x16x32_bf16 v[118:121], v[146:149], v[180:183], v[118:121]
	v_mfma_f32_16x16x32_bf16 v[114:117], v[154:157], v[180:183], v[114:117]
	v_mfma_f32_16x16x32_bf16 v[102:105], v[146:149], v[216:219], v[102:105]
	v_mfma_f32_16x16x32_bf16 v[98:101], v[154:157], v[216:219], v[98:101]
	v_mfma_f32_16x16x32_bf16 v[86:89], v[146:149], v[224:227], v[86:89]
	v_mfma_f32_16x16x32_bf16 v[82:85], v[154:157], v[224:227], v[82:85]
	v_mfma_f32_16x16x32_bf16 v[134:137], v[150:153], v[6:9], v[134:137]
	v_mfma_f32_16x16x32_bf16 v[130:133], v[158:161], v[6:9], v[130:133]
	v_mfma_f32_16x16x32_bf16 v[118:121], v[150:153], v[184:187], v[118:121]
	v_mfma_f32_16x16x32_bf16 v[114:117], v[158:161], v[184:187], v[114:117]
	v_mfma_f32_16x16x32_bf16 v[102:105], v[150:153], v[220:223], v[102:105]
	v_mfma_f32_16x16x32_bf16 v[98:101], v[158:161], v[220:223], v[98:101]
	v_mfma_f32_16x16x32_bf16 v[86:89], v[150:153], v[228:231], v[86:89]
	v_mfma_f32_16x16x32_bf16 v[82:85], v[158:161], v[228:231], v[82:85]
	s_setprio 0
	s_setprio 1
	v_mfma_f32_16x16x32_bf16 v[126:129], v[166:169], v[2:5], v[126:129]
	v_mfma_f32_16x16x32_bf16 v[2:5], v[174:177], v[2:5], v[122:125]
	v_mfma_f32_16x16x32_bf16 v[122:125], v[162:165], v[6:9], v[2:5]
	v_mfma_f32_16x16x32_bf16 v[2:5], v[166:169], v[180:183], v[110:113]
	v_mfma_f32_16x16x32_bf16 v[110:113], v[170:173], v[184:187], v[2:5]
	v_mfma_f32_16x16x32_bf16 v[2:5], v[174:177], v[180:183], v[106:109]
	v_mfma_f32_16x16x32_bf16 v[106:109], v[162:165], v[184:187], v[2:5]
	v_mfma_f32_16x16x32_bf16 v[2:5], v[166:169], v[216:219], v[94:97]
	v_mfma_f32_16x16x32_bf16 v[94:97], v[170:173], v[220:223], v[2:5]
	v_mfma_f32_16x16x32_bf16 v[2:5], v[174:177], v[216:219], v[90:93]
	v_mfma_f32_16x16x32_bf16 v[90:93], v[162:165], v[220:223], v[2:5]
	v_mfma_f32_16x16x32_bf16 v[2:5], v[166:169], v[224:227], v[78:81]
	v_mfma_f32_16x16x32_bf16 v[78:81], v[170:173], v[228:231], v[2:5]
	v_mfma_f32_16x16x32_bf16 v[2:5], v[174:177], v[224:227], v[74:77]
	v_mfma_f32_16x16x32_bf16 v[126:129], v[170:173], v[6:9], v[126:129]
	v_mfma_f32_16x16x32_bf16 v[74:77], v[162:165], v[228:231], v[2:5]
	s_barrier
	s_setprio 0
	s_add_i32 s78, 0, 0x20800
	s_add_i32 s77, s77, s18
	v_add_u32_e32 v178, s78, v213
	v_add_u32_e32 v184, s78, v214
	v_lshl_add_u64 v[208:209], v[202:203], 0, s[26:27]
	s_mov_b32 m0, s77
	ds_read_b128 v[2:5], v215 offset:49152
	ds_read_b128 v[6:9], v215 offset:50176
	ds_read_b128 v[216:219], v215 offset:51200
	ds_read_b128 v[220:223], v215 offset:52224
	ds_read_b128 v[224:227], v215 offset:53248
	ds_read_b128 v[228:231], v215 offset:54272
	ds_read_b128 v[232:235], v215 offset:55296
	ds_read_b128 v[240:243], v215 offset:56320
	ds_read_b128 v[180:183], v178
	ds_read_b128 v[184:187], v184
	global_load_lds_dwordx4 v[208:209], off
	v_lshl_add_u64 v[208:209], v[202:203], 0, s[28:29]
	s_add_i32 m0, s77, 0x2000
	s_add_i32 s77, s80, s18
	global_load_lds_dwordx4 v[208:209], off
	v_lshl_add_u64 v[208:209], v[202:203], 0, s[30:31]
	s_mov_b32 m0, s77
	v_lshl_add_u64 v[202:203], v[202:203], 0, s[34:35]
	global_load_lds_dwordx4 v[208:209], off
	s_add_i32 m0, s77, 0x2000
	s_nop 0
	global_load_lds_dwordx4 v[202:203], off
	v_lshl_add_u64 v[202:203], v[210:211], 0, s[26:27]
	s_mov_b32 m0, s10
	s_nop 0
	global_load_lds_dwordx4 v[202:203], off
	v_lshl_add_u64 v[202:203], v[210:211], 0, s[28:29]
	s_mov_b32 m0, s2
	s_nop 0
	global_load_lds_dwordx4 v[202:203], off
	s_waitcnt vmcnt(9)
	s_waitcnt lgkmcnt(0)
	s_setprio 1
	s_barrier
	v_mfma_f32_16x16x32_bf16 v[70:73], v[146:149], v[2:5], v[70:73]
	v_mfma_f32_16x16x32_bf16 v[66:69], v[154:157], v[2:5], v[66:69]
	v_mfma_f32_16x16x32_bf16 v[54:57], v[146:149], v[216:219], v[54:57]
	v_mfma_f32_16x16x32_bf16 v[50:53], v[154:157], v[216:219], v[50:53]
	v_mfma_f32_16x16x32_bf16 v[38:41], v[146:149], v[224:227], v[38:41]
	v_mfma_f32_16x16x32_bf16 v[34:37], v[154:157], v[224:227], v[34:37]
	v_mfma_f32_16x16x32_bf16 v[22:25], v[146:149], v[232:235], v[22:25]
	v_mfma_f32_16x16x32_bf16 v[18:21], v[154:157], v[232:235], v[18:21]
	v_mfma_f32_16x16x32_bf16 v[70:73], v[150:153], v[6:9], v[70:73]
	v_mfma_f32_16x16x32_bf16 v[66:69], v[158:161], v[6:9], v[66:69]
	v_mfma_f32_16x16x32_bf16 v[54:57], v[150:153], v[220:223], v[54:57]
	v_mfma_f32_16x16x32_bf16 v[50:53], v[158:161], v[220:223], v[50:53]
	v_mfma_f32_16x16x32_bf16 v[38:41], v[150:153], v[228:231], v[38:41]
	v_mfma_f32_16x16x32_bf16 v[34:37], v[158:161], v[228:231], v[34:37]
	v_mfma_f32_16x16x32_bf16 v[22:25], v[150:153], v[240:243], v[22:25]
	v_mfma_f32_16x16x32_bf16 v[18:21], v[158:161], v[240:243], v[18:21]
	s_setprio 0
	s_setprio 1
	v_mfma_f32_16x16x32_bf16 v[62:65], v[166:169], v[2:5], v[62:65]
	v_mfma_f32_16x16x32_bf16 v[2:5], v[174:177], v[2:5], v[58:61]
	v_mfma_f32_16x16x32_bf16 v[58:61], v[162:165], v[6:9], v[2:5]
	v_mfma_f32_16x16x32_bf16 v[2:5], v[166:169], v[216:219], v[46:49]
	v_mfma_f32_16x16x32_bf16 v[46:49], v[170:173], v[220:223], v[2:5]
	v_mfma_f32_16x16x32_bf16 v[2:5], v[174:177], v[216:219], v[42:45]
	v_mfma_f32_16x16x32_bf16 v[42:45], v[162:165], v[220:223], v[2:5]
	v_mfma_f32_16x16x32_bf16 v[2:5], v[166:169], v[224:227], v[30:33]
	v_mfma_f32_16x16x32_bf16 v[30:33], v[170:173], v[228:231], v[2:5]
	v_mfma_f32_16x16x32_bf16 v[2:5], v[174:177], v[224:227], v[26:29]
	v_mfma_f32_16x16x32_bf16 v[26:29], v[162:165], v[228:231], v[2:5]
	v_mfma_f32_16x16x32_bf16 v[2:5], v[166:169], v[232:235], v[14:17]
	v_mfma_f32_16x16x32_bf16 v[14:17], v[170:173], v[240:243], v[2:5]
	v_mfma_f32_16x16x32_bf16 v[2:5], v[174:177], v[232:235], v[10:13]
	v_mfma_f32_16x16x32_bf16 v[62:65], v[170:173], v[6:9], v[62:65]
	v_mfma_f32_16x16x32_bf16 v[10:13], v[162:165], v[240:243], v[2:5]
	s_setprio 0
	s_setprio 1
	v_mfma_f32_16x16x32_bf16 v[2:5], v[166:169], v[180:183], v[138:141]
	v_mfma_f32_16x16x32_bf16 v[6:9], v[170:173], v[184:187], v[2:5]
	v_mfma_f32_16x16x32_bf16 v[2:5], v[174:177], v[180:183], v[142:145]
	v_mfma_f32_16x16x32_bf16 v[2:5], v[162:165], v[184:187], v[2:5]
	s_branch .LBB0_597

; #define PG8_SB(B) __builtin_amdgcn_rcpf(1.f + expneg(B))
; #define PG8_SB(B) __builtin_amdgcn_rcpf(1.f + expneg(B))
; #define PG8_STAGE(bufoff, gbase, voff) do { _Pragma("unroll") for (int _i = 0; _i < 2; ++_i) \
;         __builtin_amdgcn_global_load_lds((const unsigned*)((const char*)(gbase) + (size_t)_i * qstep + (voff)[0]), (PG8_LAS unsigned*)(lds + (bufoff) + ldsw + _i * 8192), 16, 0, 0); } while (0)
; #define PG8_LDA(dst, b, h) do { _Pragma("unroll") for (int m = 0; m < 4; ++m) _Pragma("unroll") for (int k = 0; k < 2; ++k) dst[m][k] = *(const PG8_LAS bf16x8*)(lds + PG8_SA(b, h) + aoff + m * 2048 + k * 1024); } while (0)
; #define PG8_LDB(dst, b, h) do { _Pragma("unroll") for (int n = 0; n < 2; ++n) _Pragma("unroll") for (int k = 0; k < 2; ++k) dst[n][k] = *(const PG8_LAS bf16x8*)(lds + PG8_SB(b, h) + boff + n * 2048 + k * 1024); } while (0)
; #define PG8_WAIT_V89() do { if constexpr (SLIVER) PG8_WAIT_V(9); else PG8_WAIT_V(8); } while (0)
; #define PG8_STAGE_S(b, gbase) do { if constexpr (SLIVER) __builtin_amdgcn_global_load_lds((const unsigned*)((const char*)(gbase) + voffS), (PG8_LAS unsigned*)(lds + STAGE_BYTES + (b) * 2048 + wid * 256), 4, 0, 0); } while (0)
; template <class Epi, class Sched, bool ALIGN_EPI = false, bool SP2 = false, bool SLIVER = false>
; __device__ __forceinline__ void gemm_phase(PG8_LAS unsigned char* lds, const Gemm g, const Sched& S, const Epi& E) {
;     ...
;         for (int t = 0; t < nt; t += 2) {
;             const bool last = (t == nt - 2);
;             const char* a1 = cA + (size_t)(t + 1) * kstep;
;             const char* a2 = last ? nA : cA + (size_t)(t + 2) * kstep; const char* b2 = last ? nB : cB + (size_t)(t + 2) * kstep;
;             const char* a3 = a2 + kstep; const char* b3 = b2 + kstep;
;             const char* s1 = cS + (size_t)(t + 1) * kstep; const char* s2 = last ? nS : cS + (size_t)(t + 2) * kstep;
;             if (last && has_next) S.a_ready(nxt);
;             if constexpr (SP2) {
;             PG8_LDB(B0, 0, 0); PG8_LDB(B1, 0, 1); PG8_SCHED; PG8_LDA(At, 0, 0); PG8_STAGE(PG8_SA(1, 1), a1 + hstep, voffA); PG8_STAGE_S(1, s1);
;             PG8_WAIT_V89(); PG8_WAIT_L(0); PG8_BAR; PG8_MMA(0, 0, At, B0); PG8_MMA(0, 1, At, B1); PG8_BAR; PG8_SCHED;
;             PG8_LDA(At, 0, 1); PG8_LDS_S(0); PG8_STAGE(PG8_SB(0, 0), b2, voffB); PG8_STAGE(PG8_SB(0, 1), b2 + hstep, voffB); PG8_STAGE(PG8_SA(0, 0), a2, voffA);
.LslvB_hdr1:
	s_add_u32 s40, s92, s62
	s_addc_u32 s41, s93, s63
	s_add_u32 s77, s40, 0x100
	s_addc_u32 s78, s41, 0
	s_add_u32 s83, s68, s62
	s_addc_u32 s79, s69, s63
	s_add_i32 s96, 0, 0x10000
	s_cmpk_eq_i32 s62, 0xf00
	s_cselect_b64 s[80:81], -1, 0
	s_and_b64 s[40:41], s[80:81], exec
	s_cselect_b32 s41, s12, s78
	s_cselect_b32 s40, s13, s77
	v_add_u32_e32 v138, s96, v212
	s_cselect_b32 s79, s17, s79
	s_cselect_b32 s78, s55, s83
	s_add_i32 s77, 0, 0x14000
	ds_read_b128 v[146:149], v138
	ds_read_b128 v[150:153], v138 offset:1024
	ds_read_b128 v[154:157], v138 offset:2048
	ds_read_b128 v[158:161], v138 offset:3072
	v_add_u32_e32 v138, s77, v212
	ds_read_b128 v[166:169], v138
	ds_read_b128 v[170:173], v138 offset:1024
	ds_read_b128 v[174:177], v138 offset:2048
	ds_read_b128 v[162:165], v138 offset:3072
	v_lshl_add_u64 v[202:203], v[200:201], 0, s[62:63]
	v_lshl_add_u64 v[208:209], v[202:203], 0, s[30:31]
	s_add_i32 m0, s85, 0xc000
	ds_read_b128 v[138:141], v215
	ds_read_b128 v[142:145], v215 offset:1024
	ds_read_b128 v[180:183], v215 offset:2048
	ds_read_b128 v[184:187], v215 offset:3072
	ds_read_b128 v[216:219], v215 offset:4096
	ds_read_b128 v[220:223], v215 offset:5120
	ds_read_b128 v[224:227], v215 offset:6144
	ds_read_b128 v[228:231], v215 offset:7168
	global_load_lds_dwordx4 v[208:209], off
	v_lshl_add_u64 v[202:203], v[202:203], 0, s[34:35]
	s_add_i32 m0, s85, 0xe000
	s_nop 0
	global_load_lds_dwordx4 v[202:203], off
	v_lshl_add_u64 v[202:203], v[198:199], 0, s[62:63]
	s_add_i32 m0, s45, 0x20800
	s_nop 0
	global_load_lds_dword v[202:203], off
	s_waitcnt vmcnt(9)
	s_waitcnt lgkmcnt(0)
	s_setprio 1
	s_barrier
	v_mfma_f32_16x16x32_bf16 v[134:137], v[146:149], v[138:141], v[134:137]
	v_mfma_f32_16x16x32_bf16 v[130:133], v[154:157], v[138:141], v[130:133]
	v_mfma_f32_16x16x32_bf16 v[118:121], v[146:149], v[180:183], v[118:121]
	v_mfma_f32_16x16x32_bf16 v[114:117], v[154:157], v[180:183], v[114:117]
	v_mfma_f32_16x16x32_bf16 v[102:105], v[146:149], v[216:219], v[102:105]
	v_mfma_f32_16x16x32_bf16 v[98:101], v[154:157], v[216:219], v[98:101]
	v_mfma_f32_16x16x32_bf16 v[86:89], v[146:149], v[224:227], v[86:89]
	v_mfma_f32_16x16x32_bf16 v[82:85], v[154:157], v[224:227], v[82:85]
	v_mfma_f32_16x16x32_bf16 v[134:137], v[150:153], v[142:145], v[134:137]
	v_mfma_f32_16x16x32_bf16 v[130:133], v[158:161], v[142:145], v[130:133]
	v_mfma_f32_16x16x32_bf16 v[118:121], v[150:153], v[184:187], v[118:121]
	v_mfma_f32_16x16x32_bf16 v[114:117], v[158:161], v[184:187], v[114:117]
	v_mfma_f32_16x16x32_bf16 v[102:105], v[150:153], v[220:223], v[102:105]
	v_mfma_f32_16x16x32_bf16 v[98:101], v[158:161], v[220:223], v[98:101]
	v_mfma_f32_16x16x32_bf16 v[86:89], v[150:153], v[228:231], v[86:89]
	v_mfma_f32_16x16x32_bf16 v[82:85], v[158:161], v[228:231], v[82:85]
	s_setprio 0
	s_setprio 1
	v_mfma_f32_16x16x32_bf16 v[126:129], v[166:169], v[138:141], v[126:129]
	v_mfma_f32_16x16x32_bf16 v[122:125], v[174:177], v[138:141], v[122:125]
	v_mfma_f32_16x16x32_bf16 v[110:113], v[166:169], v[180:183], v[110:113]
	v_mfma_f32_16x16x32_bf16 v[106:109], v[174:177], v[180:183], v[106:109]
	v_mfma_f32_16x16x32_bf16 v[94:97], v[166:169], v[216:219], v[94:97]
	v_mfma_f32_16x16x32_bf16 v[90:93], v[174:177], v[216:219], v[90:93]
	v_mfma_f32_16x16x32_bf16 v[78:81], v[166:169], v[224:227], v[78:81]
	v_mfma_f32_16x16x32_bf16 v[74:77], v[174:177], v[224:227], v[74:77]
	v_mfma_f32_16x16x32_bf16 v[126:129], v[170:173], v[142:145], v[126:129]
	v_mfma_f32_16x16x32_bf16 v[122:125], v[162:165], v[142:145], v[122:125]
	v_mfma_f32_16x16x32_bf16 v[110:113], v[170:173], v[184:187], v[110:113]
	v_mfma_f32_16x16x32_bf16 v[106:109], v[162:165], v[184:187], v[106:109]
	v_mfma_f32_16x16x32_bf16 v[94:97], v[170:173], v[220:223], v[94:97]
	v_mfma_f32_16x16x32_bf16 v[90:93], v[162:165], v[220:223], v[90:93]
	v_mfma_f32_16x16x32_bf16 v[78:81], v[170:173], v[228:231], v[78:81]
	v_mfma_f32_16x16x32_bf16 v[74:77], v[162:165], v[228:231], v[74:77]
	s_barrier
	s_setprio 0
	s_add_i32 s83, 0, 0x20000
	v_lshl_add_u64 v[202:203], s[78:79], 0, v[190:191]
	s_add_i32 s78, s96, s18
	v_add_u32_e32 v178, s83, v213
	v_add_u32_e32 v184, s83, v214
	s_mov_b32 m0, s78
	ds_read_b128 v[138:141], v215 offset:16384
	ds_read_b128 v[142:145], v215 offset:17408
	ds_read_b128 v[216:219], v215 offset:18432
	ds_read_b128 v[220:223], v215 offset:19456
	ds_read_b128 v[224:227], v215 offset:20480
	ds_read_b128 v[228:231], v215 offset:21504
	ds_read_b128 v[232:235], v215 offset:22528
	ds_read_b128 v[240:243], v215 offset:23552
	ds_read_b128 v[180:183], v178
	ds_read_b128 v[184:187], v184
	global_load_lds_dwordx4 v[202:203], off
	v_lshl_add_u64 v[208:209], v[202:203], 0, s[20:21]
	s_add_i32 m0, s78, 0x2000
	s_add_i32 s77, s77, s18
	global_load_lds_dwordx4 v[208:209], off
	v_lshl_add_u64 v[208:209], v[202:203], 0, s[22:23]
	s_mov_b32 m0, s77
	v_lshl_add_u64 v[210:211], s[40:41], 0, v[188:189]
	global_load_lds_dwordx4 v[208:209], off
	v_lshl_add_u64 v[208:209], v[202:203], 0, s[24:25]
	s_add_i32 m0, s77, 0x2000
	s_nop 0
	global_load_lds_dwordx4 v[208:209], off
	s_mov_b32 m0, s85
	v_lshl_add_u64 v[208:209], v[210:211], 0, s[20:21]
	global_load_lds_dwordx4 v[210:211], off
	s_mov_b32 m0, s19
	s_nop 0
	global_load_lds_dwordx4 v[208:209], off
	s_waitcnt vmcnt(9)
	s_waitcnt lgkmcnt(0)
	s_setprio 1
	s_barrier
; #define PG8_STAGE(bufoff, gbase, voff) do { _Pragma("unroll") for (int _i = 0; _i < 2; ++_i) \
;         __builtin_amdgcn_global_load_lds((const unsigned*)((const char*)(gbase) + (size_t)_i * qstep + (voff)[0]), (PG8_LAS unsigned*)(lds + (bufoff) + ldsw + _i * 8192), 16, 0, 0); } while (0)
; #define PG8_LDA(dst, b, h) do { _Pragma("unroll") for (int m = 0; m < 4; ++m) _Pragma("unroll") for (int k = 0; k < 2; ++k) dst[m][k] = *(const PG8_LAS bf16x8*)(lds + PG8_SA(b, h) + aoff + m * 2048 + k * 1024); } while (0)
; #define PG8_LDB(dst, b, h) do { _Pragma("unroll") for (int n = 0; n < 2; ++n) _Pragma("unroll") for (int k = 0; k < 2; ++k) dst[n][k] = *(const PG8_LAS bf16x8*)(lds + PG8_SB(b, h) + boff + n * 2048 + k * 1024); } while (0)
; #define PG8_MMA(ai, bj, At, Bt) do { __builtin_amdgcn_s_setprio(1); _Pragma("unroll") for (int m = 0; m < 4; ++m) _Pragma("unroll") for (int n = 0; n < 2; ++n) _Pragma("unroll") for (int k = 0; k < 2; ++k) \
;         acc[ai][bj][m][n] = __builtin_amdgcn_mfma_f32_16x16x32_bf16(Bt[n][k], At[m][k], acc[ai][bj][m][n], 0, 0, 0); __builtin_amdgcn_s_setprio(0); } while (0)
; #define PG8_WAIT_V89() do { if constexpr (SLIVER) PG8_WAIT_V(9); else PG8_WAIT_V(8); } while (0)
; #define PG8_STAGE_S(b, gbase) do { if constexpr (SLIVER) __builtin_amdgcn_global_load_lds((const unsigned*)((const char*)(gbase) + voffS), (PG8_LAS unsigned*)(lds + STAGE_BYTES + (b) * 2048 + wid * 256), 4, 0, 0); } while (0)
; #define PG8_WAIT_L(n) asm volatile("s_waitcnt lgkmcnt(" #n ")" ::: "memory")
; #define PG8_BAR __builtin_amdgcn_s_barrier()
; #define PG8_SCHED __builtin_amdgcn_sched_barrier(0)
; template <class Epi, class Sched, bool ALIGN_EPI = false, bool SP2 = false, bool SLIVER = false>
; __device__ __forceinline__ void gemm_phase(PG8_LAS unsigned char* lds, const Gemm g, const Sched& S, const Epi& E) {
;     ...
;             PG8_WAIT_V89(); PG8_WAIT_L(0); PG8_BAR; PG8_MMA(1, 0, At, B0); PG8_MMA(1, 1, At, B1); PG8_MMA_S(); PG8_BAR; PG8_SCHED;
;             PG8_LDB(B0, 1, 0); PG8_LDB(B1, 1, 1); PG8_SCHED; PG8_LDA(At, 1, 0); PG8_STAGE(PG8_SA(0, 1), a2 + hstep, voffA); PG8_STAGE_S(0, s2);
;             PG8_WAIT_V89(); PG8_WAIT_L(0); PG8_BAR; PG8_MMA(0, 0, At, B0); PG8_MMA(0, 1, At, B1); PG8_BAR; PG8_SCHED;
	v_mfma_f32_16x16x32_bf16 v[70:73], v[146:149], v[138:141], v[70:73]
	v_mfma_f32_16x16x32_bf16 v[66:69], v[154:157], v[138:141], v[66:69]
	v_mfma_f32_16x16x32_bf16 v[54:57], v[146:149], v[216:219], v[54:57]
	v_mfma_f32_16x16x32_bf16 v[50:53], v[154:157], v[216:219], v[50:53]
	v_mfma_f32_16x16x32_bf16 v[38:41], v[146:149], v[224:227], v[38:41]
	v_mfma_f32_16x16x32_bf16 v[34:37], v[154:157], v[224:227], v[34:37]
	v_mfma_f32_16x16x32_bf16 v[22:25], v[146:149], v[232:235], v[22:25]
	v_mfma_f32_16x16x32_bf16 v[18:21], v[154:157], v[232:235], v[18:21]
	v_mfma_f32_16x16x32_bf16 v[70:73], v[150:153], v[142:145], v[70:73]
	v_mfma_f32_16x16x32_bf16 v[66:69], v[158:161], v[142:145], v[66:69]
	v_mfma_f32_16x16x32_bf16 v[54:57], v[150:153], v[220:223], v[54:57]
	v_mfma_f32_16x16x32_bf16 v[50:53], v[158:161], v[220:223], v[50:53]
	v_mfma_f32_16x16x32_bf16 v[38:41], v[150:153], v[228:231], v[38:41]
	v_mfma_f32_16x16x32_bf16 v[34:37], v[158:161], v[228:231], v[34:37]
	v_mfma_f32_16x16x32_bf16 v[22:25], v[150:153], v[240:243], v[22:25]
	v_mfma_f32_16x16x32_bf16 v[18:21], v[158:161], v[240:243], v[18:21]
	s_setprio 0
	s_setprio 1
	v_mfma_f32_16x16x32_bf16 v[62:65], v[166:169], v[138:141], v[62:65]
	v_mfma_f32_16x16x32_bf16 v[58:61], v[174:177], v[138:141], v[58:61]
	v_mfma_f32_16x16x32_bf16 v[46:49], v[166:169], v[216:219], v[46:49]
	v_mfma_f32_16x16x32_bf16 v[42:45], v[174:177], v[216:219], v[42:45]
	v_mfma_f32_16x16x32_bf16 v[30:33], v[166:169], v[224:227], v[30:33]
	v_mfma_f32_16x16x32_bf16 v[26:29], v[174:177], v[224:227], v[26:29]
	v_mfma_f32_16x16x32_bf16 v[14:17], v[166:169], v[232:235], v[14:17]
	v_mfma_f32_16x16x32_bf16 v[10:13], v[174:177], v[232:235], v[10:13]
	v_mfma_f32_16x16x32_bf16 v[62:65], v[170:173], v[142:145], v[62:65]
	v_mfma_f32_16x16x32_bf16 v[58:61], v[162:165], v[142:145], v[58:61]
	v_mfma_f32_16x16x32_bf16 v[46:49], v[170:173], v[220:223], v[46:49]
	v_mfma_f32_16x16x32_bf16 v[42:45], v[162:165], v[220:223], v[42:45]
	v_mfma_f32_16x16x32_bf16 v[30:33], v[170:173], v[228:231], v[30:33]
	v_mfma_f32_16x16x32_bf16 v[26:29], v[162:165], v[228:231], v[26:29]
	v_mfma_f32_16x16x32_bf16 v[14:17], v[170:173], v[240:243], v[14:17]
	v_mfma_f32_16x16x32_bf16 v[10:13], v[162:165], v[240:243], v[10:13]
	s_setprio 0
	s_setprio 1
	v_mfma_f32_16x16x32_bf16 v[6:9], v[146:149], v[180:183], v[6:9]
	v_mfma_f32_16x16x32_bf16 v[2:5], v[154:157], v[180:183], v[2:5]
	v_mfma_f32_16x16x32_bf16 v[138:141], v[150:153], v[184:187], v[6:9]
	v_mfma_f32_16x16x32_bf16 v[142:145], v[158:161], v[184:187], v[2:5]
	s_barrier
	s_setprio 0
	s_add_u32 s77, s94, s62
	s_addc_u32 s78, s95, s63
	s_add_u32 s77, s77, 0x100
	s_addc_u32 s83, s78, 0
	s_and_b64 s[78:79], s[80:81], exec
	s_cselect_b32 s79, s66, s83
	s_cselect_b32 s78, s67, s77
	s_add_i32 s77, 0, 0x18000
	v_add_u32_e32 v2, s77, v212
	s_add_i32 s80, 0, 0x1c000
	ds_read_b128 v[146:149], v2
	ds_read_b128 v[150:153], v2 offset:1024
	ds_read_b128 v[154:157], v2 offset:2048
	ds_read_b128 v[158:161], v2 offset:3072
	v_add_u32_e32 v2, s80, v212
	ds_read_b128 v[166:169], v2
	ds_read_b128 v[170:173], v2 offset:1024
	ds_read_b128 v[174:177], v2 offset:2048
	ds_read_b128 v[162:165], v2 offset:3072
	s_mov_b32 m0, s49
	v_lshl_add_u64 v[208:209], v[210:211], 0, s[22:23]
	ds_read_b128 v[2:5], v215 offset:32768
	ds_read_b128 v[6:9], v215 offset:33792
	ds_read_b128 v[180:183], v215 offset:34816
	ds_read_b128 v[184:187], v215 offset:35840
	ds_read_b128 v[216:219], v215 offset:36864
	ds_read_b128 v[220:223], v215 offset:37888
	ds_read_b128 v[224:227], v215 offset:38912
	ds_read_b128 v[228:231], v215 offset:39936
	global_load_lds_dwordx4 v[208:209], off
	v_lshl_add_u64 v[208:209], v[210:211], 0, s[24:25]
	s_mov_b32 m0, s50
	s_nop 0
	global_load_lds_dwordx4 v[208:209], off
	v_lshl_add_u64 v[208:209], s[78:79], 0, v[192:193]
	s_mov_b32 m0, s51
	s_nop 0
	global_load_lds_dword v[208:209], off
	s_waitcnt vmcnt(9)
	s_waitcnt lgkmcnt(0)
	s_setprio 1
	s_barrier
; #define PG8_SB(B) __builtin_amdgcn_rcpf(1.f + expneg(B))
; #define PG8_SB(B) __builtin_amdgcn_rcpf(1.f + expneg(B))
; #define PG8_STAGE(bufoff, gbase, voff) do { _Pragma("unroll") for (int _i = 0; _i < 2; ++_i) \
;         __builtin_amdgcn_global_load_lds((const unsigned*)((const char*)(gbase) + (size_t)_i * qstep + (voff)[0]), (PG8_LAS unsigned*)(lds + (bufoff) + ldsw + _i * 8192), 16, 0, 0); } while (0)
; #define PG8_LDA(dst, b, h) do { _Pragma("unroll") for (int m = 0; m < 4; ++m) _Pragma("unroll") for (int k = 0; k < 2; ++k) dst[m][k] = *(const PG8_LAS bf16x8*)(lds + PG8_SA(b, h) + aoff + m * 2048 + k * 1024); } while (0)
; #define PG8_MMA(ai, bj, At, Bt) do { __builtin_amdgcn_s_setprio(1); _Pragma("unroll") for (int m = 0; m < 4; ++m) _Pragma("unroll") for (int n = 0; n < 2; ++n) _Pragma("unroll") for (int k = 0; k < 2; ++k) \
;         acc[ai][bj][m][n] = __builtin_amdgcn_mfma_f32_16x16x32_bf16(Bt[n][k], At[m][k], acc[ai][bj][m][n], 0, 0, 0); __builtin_amdgcn_s_setprio(0); } while (0)
; #define PG8_WAIT_V89() do { if constexpr (SLIVER) PG8_WAIT_V(9); else PG8_WAIT_V(8); } while (0)
; #define PG8_LDS_S(b) do { if constexpr (SLIVER) { Sf[0] = *(const PG8_LAS bf16x8*)(lds + STAGE_BYTES + (b) * 2048 + soff0); Sf[1] = *(const PG8_LAS bf16x8*)(lds + STAGE_BYTES + (b) * 2048 + (soff0 ^ 64)); } } while (0)
; #define PG8_WAIT_L(n) asm volatile("s_waitcnt lgkmcnt(" #n ")" ::: "memory")
; #define PG8_BAR __builtin_amdgcn_s_barrier()
; #define PG8_SCHED __builtin_amdgcn_sched_barrier(0)
; template <class Epi, class Sched, bool ALIGN_EPI = false, bool SP2 = false, bool SLIVER = false>
; __device__ __forceinline__ void gemm_phase(PG8_LAS unsigned char* lds, const Gemm g, const Sched& S, const Epi& E) {
;     ...
;             PG8_WAIT_V89(); PG8_WAIT_L(0); PG8_BAR; PG8_MMA(0, 0, At, B0); PG8_MMA(0, 1, At, B1); PG8_BAR; PG8_SCHED;
;             PG8_LDA(At, 1, 1); PG8_LDS_S(1); PG8_STAGE(PG8_SB(1, 0), b3, voffB); PG8_STAGE(PG8_SB(1, 1), b3 + hstep, voffB); PG8_STAGE(PG8_SA(1, 0), a3, voffA);
;             PG8_WAIT_V89(); PG8_WAIT_L(0); PG8_BAR; PG8_MMA(1, 0, At, B0); PG8_MMA(1, 1, At, B1); PG8_MMA_S(); PG8_BAR; PG8_SCHED;
	v_mfma_f32_16x16x32_bf16 v[134:137], v[146:149], v[2:5], v[134:137]
	v_mfma_f32_16x16x32_bf16 v[130:133], v[154:157], v[2:5], v[130:133]
	v_mfma_f32_16x16x32_bf16 v[118:121], v[146:149], v[180:183], v[118:121]
	v_mfma_f32_16x16x32_bf16 v[114:117], v[154:157], v[180:183], v[114:117]
	v_mfma_f32_16x16x32_bf16 v[102:105], v[146:149], v[216:219], v[102:105]
	v_mfma_f32_16x16x32_bf16 v[98:101], v[154:157], v[216:219], v[98:101]
	v_mfma_f32_16x16x32_bf16 v[86:89], v[146:149], v[224:227], v[86:89]
	v_mfma_f32_16x16x32_bf16 v[82:85], v[154:157], v[224:227], v[82:85]
	v_mfma_f32_16x16x32_bf16 v[134:137], v[150:153], v[6:9], v[134:137]
	v_mfma_f32_16x16x32_bf16 v[130:133], v[158:161], v[6:9], v[130:133]
	v_mfma_f32_16x16x32_bf16 v[118:121], v[150:153], v[184:187], v[118:121]
	v_mfma_f32_16x16x32_bf16 v[114:117], v[158:161], v[184:187], v[114:117]
	v_mfma_f32_16x16x32_bf16 v[102:105], v[150:153], v[220:223], v[102:105]
	v_mfma_f32_16x16x32_bf16 v[98:101], v[158:161], v[220:223], v[98:101]
	v_mfma_f32_16x16x32_bf16 v[86:89], v[150:153], v[228:231], v[86:89]
	v_mfma_f32_16x16x32_bf16 v[82:85], v[158:161], v[228:231], v[82:85]
	s_setprio 0
	s_setprio 1
	v_mfma_f32_16x16x32_bf16 v[126:129], v[166:169], v[2:5], v[126:129]
	v_mfma_f32_16x16x32_bf16 v[2:5], v[174:177], v[2:5], v[122:125]
	v_mfma_f32_16x16x32_bf16 v[122:125], v[162:165], v[6:9], v[2:5]
	v_mfma_f32_16x16x32_bf16 v[2:5], v[166:169], v[180:183], v[110:113]
	v_mfma_f32_16x16x32_bf16 v[110:113], v[170:173], v[184:187], v[2:5]
	v_mfma_f32_16x16x32_bf16 v[2:5], v[174:177], v[180:183], v[106:109]
	v_mfma_f32_16x16x32_bf16 v[106:109], v[162:165], v[184:187], v[2:5]
	v_mfma_f32_16x16x32_bf16 v[2:5], v[166:169], v[216:219], v[94:97]
	v_mfma_f32_16x16x32_bf16 v[94:97], v[170:173], v[220:223], v[2:5]
	v_mfma_f32_16x16x32_bf16 v[2:5], v[174:177], v[216:219], v[90:93]
	v_mfma_f32_16x16x32_bf16 v[90:93], v[162:165], v[220:223], v[2:5]
	v_mfma_f32_16x16x32_bf16 v[2:5], v[166:169], v[224:227], v[78:81]
	v_mfma_f32_16x16x32_bf16 v[78:81], v[170:173], v[228:231], v[2:5]
	v_mfma_f32_16x16x32_bf16 v[2:5], v[174:177], v[224:227], v[74:77]
	v_mfma_f32_16x16x32_bf16 v[126:129], v[170:173], v[6:9], v[126:129]
	v_mfma_f32_16x16x32_bf16 v[74:77], v[162:165], v[228:231], v[2:5]
	s_barrier
	s_setprio 0
	s_add_i32 s78, 0, 0x20800
	s_add_i32 s77, s77, s18
	v_add_u32_e32 v178, s78, v213
	v_add_u32_e32 v184, s78, v214
	v_lshl_add_u64 v[208:209], v[202:203], 0, s[26:27]
	s_mov_b32 m0, s77
	ds_read_b128 v[2:5], v215 offset:49152
	ds_read_b128 v[6:9], v215 offset:50176
	ds_read_b128 v[216:219], v215 offset:51200
	ds_read_b128 v[220:223], v215 offset:52224
	ds_read_b128 v[224:227], v215 offset:53248
	ds_read_b128 v[228:231], v215 offset:54272
	ds_read_b128 v[232:235], v215 offset:55296
	ds_read_b128 v[240:243], v215 offset:56320
	ds_read_b128 v[180:183], v178
	ds_read_b128 v[184:187], v184
	global_load_lds_dwordx4 v[208:209], off
	v_lshl_add_u64 v[208:209], v[202:203], 0, s[28:29]
	s_add_i32 m0, s77, 0x2000
	s_add_i32 s77, s80, s18
	global_load_lds_dwordx4 v[208:209], off
	v_lshl_add_u64 v[208:209], v[202:203], 0, s[30:31]
	s_mov_b32 m0, s77
	v_lshl_add_u64 v[202:203], v[202:203], 0, s[34:35]
	global_load_lds_dwordx4 v[208:209], off
	s_add_i32 m0, s77, 0x2000
	s_nop 0
	global_load_lds_dwordx4 v[202:203], off
	v_lshl_add_u64 v[202:203], v[210:211], 0, s[26:27]
	s_mov_b32 m0, s10
	s_nop 0
	global_load_lds_dwordx4 v[202:203], off
	v_lshl_add_u64 v[202:203], v[210:211], 0, s[28:29]
	s_mov_b32 m0, s2
	s_nop 0
	global_load_lds_dwordx4 v[202:203], off
	s_waitcnt vmcnt(9)
	s_waitcnt lgkmcnt(0)
	s_setprio 1
	s_barrier
	v_mfma_f32_16x16x32_bf16 v[70:73], v[146:149], v[2:5], v[70:73]
	v_mfma_f32_16x16x32_bf16 v[66:69], v[154:157], v[2:5], v[66:69]
	v_mfma_f32_16x16x32_bf16 v[54:57], v[146:149], v[216:219], v[54:57]
	v_mfma_f32_16x16x32_bf16 v[50:53], v[154:157], v[216:219], v[50:53]
	v_mfma_f32_16x16x32_bf16 v[38:41], v[146:149], v[224:227], v[38:41]
	v_mfma_f32_16x16x32_bf16 v[34:37], v[154:157], v[224:227], v[34:37]
	v_mfma_f32_16x16x32_bf16 v[22:25], v[146:149], v[232:235], v[22:25]
	v_mfma_f32_16x16x32_bf16 v[18:21], v[154:157], v[232:235], v[18:21]
	v_mfma_f32_16x16x32_bf16 v[70:73], v[150:153], v[6:9], v[70:73]
	v_mfma_f32_16x16x32_bf16 v[66:69], v[158:161], v[6:9], v[66:69]
	v_mfma_f32_16x16x32_bf16 v[54:57], v[150:153], v[220:223], v[54:57]
	v_mfma_f32_16x16x32_bf16 v[50:53], v[158:161], v[220:223], v[50:53]
	v_mfma_f32_16x16x32_bf16 v[38:41], v[150:153], v[228:231], v[38:41]
	v_mfma_f32_16x16x32_bf16 v[34:37], v[158:161], v[228:231], v[34:37]
	v_mfma_f32_16x16x32_bf16 v[22:25], v[150:153], v[240:243], v[22:25]
	v_mfma_f32_16x16x32_bf16 v[18:21], v[158:161], v[240:243], v[18:21]
	s_setprio 0
	s_setprio 1
	v_mfma_f32_16x16x32_bf16 v[62:65], v[166:169], v[2:5], v[62:65]
	v_mfma_f32_16x16x32_bf16 v[2:5], v[174:177], v[2:5], v[58:61]
	v_mfma_f32_16x16x32_bf16 v[58:61], v[162:165], v[6:9], v[2:5]
	v_mfma_f32_16x16x32_bf16 v[2:5], v[166:169], v[216:219], v[46:49]
	v_mfma_f32_16x16x32_bf16 v[46:49], v[170:173], v[220:223], v[2:5]
	v_mfma_f32_16x16x32_bf16 v[2:5], v[174:177], v[216:219], v[42:45]
	v_mfma_f32_16x16x32_bf16 v[42:45], v[162:165], v[220:223], v[2:5]
	v_mfma_f32_16x16x32_bf16 v[2:5], v[166:169], v[224:227], v[30:33]
	v_mfma_f32_16x16x32_bf16 v[30:33], v[170:173], v[228:231], v[2:5]
	v_mfma_f32_16x16x32_bf16 v[2:5], v[174:177], v[224:227], v[26:29]
	v_mfma_f32_16x16x32_bf16 v[26:29], v[162:165], v[228:231], v[2:5]
	v_mfma_f32_16x16x32_bf16 v[2:5], v[166:169], v[232:235], v[14:17]
	v_mfma_f32_16x16x32_bf16 v[14:17], v[170:173], v[240:243], v[2:5]
	v_mfma_f32_16x16x32_bf16 v[2:5], v[174:177], v[232:235], v[10:13]
	v_mfma_f32_16x16x32_bf16 v[62:65], v[170:173], v[6:9], v[62:65]
	v_mfma_f32_16x16x32_bf16 v[10:13], v[162:165], v[240:243], v[2:5]
	s_setprio 0
	s_setprio 1
	v_mfma_f32_16x16x32_bf16 v[2:5], v[146:149], v[180:183], v[138:141]
	v_mfma_f32_16x16x32_bf16 v[6:9], v[150:153], v[184:187], v[2:5]
	v_mfma_f32_16x16x32_bf16 v[2:5], v[154:157], v[180:183], v[142:145]
	v_mfma_f32_16x16x32_bf16 v[2:5], v[158:161], v[184:187], v[2:5]
	s_branch .LslvB_lend1

; template <class Epi, class Sched, bool ALIGN_EPI = false, bool SP2 = false, bool SLIVER = false>
; __device__ __forceinline__ void gemm_phase(PG8_LAS unsigned char* lds, const Gemm g, const Sched& S, const Epi& E) {
;     ...
;         if (fin) {
; #pragma unroll
;         for (int a = 0; a < 2; ++a)
; #pragma unroll
;             for (int b = 0; b < 2; ++b)
; #pragma unroll
;                 for (int m = 0; m < 4; ++m)
; #pragma unroll
;                     for (int n = 0; n < 2; ++n) acc[a][b][m][n] = (f32x4){0.f, 0.f, 0.f, 0.f};
;         accs[0] = (f32x4){0.f, 0.f, 0.f, 0.f}; accs[1] = (f32x4){0.f, 0.f, 0.f, 0.f};
;         }
;         cur = nxt; cA = nA; cB = nB; cS = nS; nt = Epi::nt(cur.seg, K); ++ui;
.LBB0_809:
	v_lshl_add_u64 v[2:3], s[92:93], 0, v[202:203]
	v_mov_b32_e32 v178, v179
	v_lshl_add_u64 v[212:213], v[2:3], 0, s[26:27]
	s_add_u32 s2, s62, 0x100
	v_mov_b32_e32 v180, v179
	v_mov_b32_e32 v181, v179
	v_mov_b32_e32 v10, 0
	v_mov_b64_e32 v[2:3], v[178:179]
	v_mov_b64_e32 v[6:7], v[178:179]
	v_lshl_add_u64 v[214:215], s[90:91], 0, v[210:211]
	s_addc_u32 s3, s63, 0
	s_mov_b32 s12, -2
	s_mov_b64 s[62:63], 0
	v_mov_b64_e32 v[4:5], v[180:181]
	v_mov_b64_e32 v[8:9], v[180:181]
	v_mov_b32_e32 v11, v10
	v_mov_b32_e32 v12, v10
	v_mov_b32_e32 v13, v10
	v_mov_b32_e32 v14, v10
	v_mov_b32_e32 v15, v10
	v_mov_b32_e32 v16, v10
	v_mov_b32_e32 v17, v10
	v_mov_b32_e32 v26, v10
	v_mov_b32_e32 v27, v10
	v_mov_b32_e32 v28, v10
	v_mov_b32_e32 v29, v10
	v_mov_b32_e32 v30, v10
	v_mov_b32_e32 v31, v10
	v_mov_b32_e32 v32, v10
	v_mov_b32_e32 v33, v10
	v_mov_b32_e32 v42, v10
	v_mov_b32_e32 v43, v10
	v_mov_b32_e32 v44, v10
	v_mov_b32_e32 v45, v10
	v_mov_b32_e32 v46, v10
	v_mov_b32_e32 v47, v10
	v_mov_b32_e32 v48, v10
	v_mov_b32_e32 v49, v10
	v_mov_b32_e32 v58, v10
	v_mov_b32_e32 v59, v10
	v_mov_b32_e32 v60, v10
	v_mov_b32_e32 v61, v10
	v_mov_b32_e32 v62, v10
	v_mov_b32_e32 v63, v10
	v_mov_b32_e32 v64, v10
	v_mov_b32_e32 v65, v10
	v_mov_b32_e32 v18, v10
	v_mov_b32_e32 v19, v10
	v_mov_b32_e32 v20, v10
	v_mov_b32_e32 v21, v10
	v_mov_b32_e32 v22, v10
	v_mov_b32_e32 v23, v10
	v_mov_b32_e32 v24, v10
	v_mov_b32_e32 v25, v10
	v_mov_b32_e32 v34, v10
	v_mov_b32_e32 v35, v10
	v_mov_b32_e32 v36, v10
	v_mov_b32_e32 v37, v10
	v_mov_b32_e32 v38, v10
	v_mov_b32_e32 v39, v10
	v_mov_b32_e32 v40, v10
	v_mov_b32_e32 v41, v10
	v_mov_b32_e32 v50, v10
	v_mov_b32_e32 v51, v10
	v_mov_b32_e32 v52, v10
	v_mov_b32_e32 v53, v10
	v_mov_b32_e32 v54, v10
	v_mov_b32_e32 v55, v10
	v_mov_b32_e32 v56, v10
	v_mov_b32_e32 v57, v10
	v_mov_b32_e32 v82, v10
	v_mov_b32_e32 v83, v10
	v_mov_b32_e32 v84, v10
	v_mov_b32_e32 v85, v10
	v_mov_b32_e32 v86, v10
	v_mov_b32_e32 v87, v10
	v_mov_b32_e32 v88, v10
	v_mov_b32_e32 v89, v10
	v_mov_b32_e32 v90, v10
	v_mov_b32_e32 v91, v10
	v_mov_b32_e32 v92, v10
	v_mov_b32_e32 v93, v10
	v_mov_b32_e32 v94, v10
	v_mov_b32_e32 v95, v10
	v_mov_b32_e32 v96, v10
	v_mov_b32_e32 v97, v10
	v_mov_b32_e32 v106, v10
	v_mov_b32_e32 v107, v10
	v_mov_b32_e32 v108, v10
	v_mov_b32_e32 v109, v10
	v_mov_b32_e32 v110, v10
	v_mov_b32_e32 v111, v10
	v_mov_b32_e32 v112, v10
	v_mov_b32_e32 v113, v10
	v_mov_b32_e32 v122, v10
	v_mov_b32_e32 v123, v10
	v_mov_b32_e32 v124, v10
	v_mov_b32_e32 v125, v10
	v_mov_b32_e32 v126, v10
	v_mov_b32_e32 v127, v10
	v_mov_b32_e32 v128, v10
	v_mov_b32_e32 v129, v10
	v_mov_b32_e32 v138, v10
	v_mov_b32_e32 v139, v10
	v_mov_b32_e32 v140, v10
	v_mov_b32_e32 v141, v10
	v_mov_b32_e32 v142, v10
	v_mov_b32_e32 v143, v10
	v_mov_b32_e32 v144, v10
	v_mov_b32_e32 v145, v10
	v_mov_b32_e32 v98, v10
	v_mov_b32_e32 v99, v10
	v_mov_b32_e32 v100, v10
	v_mov_b32_e32 v101, v10
	v_mov_b32_e32 v102, v10
	v_mov_b32_e32 v103, v10
	v_mov_b32_e32 v104, v10
	v_mov_b32_e32 v105, v10
	v_mov_b32_e32 v114, v10
	v_mov_b32_e32 v115, v10
	v_mov_b32_e32 v116, v10
	v_mov_b32_e32 v117, v10
	v_mov_b32_e32 v118, v10
	v_mov_b32_e32 v119, v10
	v_mov_b32_e32 v120, v10
	v_mov_b32_e32 v121, v10
	v_mov_b32_e32 v130, v10
	v_mov_b32_e32 v131, v10
	v_mov_b32_e32 v132, v10
	v_mov_b32_e32 v133, v10
	v_mov_b32_e32 v134, v10
	v_mov_b32_e32 v135, v10
	v_mov_b32_e32 v136, v10
	v_mov_b32_e32 v137, v10
	v_mov_b32_e32 v166, v10
	v_mov_b32_e32 v167, v10
	v_mov_b32_e32 v168, v10
	v_mov_b32_e32 v169, v10
	v_mov_b32_e32 v170, v10
	v_mov_b32_e32 v171, v10
	v_mov_b32_e32 v172, v10
	v_mov_b32_e32 v173, v10
	s_and_b64 vcc, exec, s[82:83]
	s_cbranch_vccz .LslvB_hdr2
	s_branch .LBB0_811

; #define PG8_SB(B) __builtin_amdgcn_rcpf(1.f + expneg(B))
; #define PG8_SB(B) __builtin_amdgcn_rcpf(1.f + expneg(B))
; #define PG8_STAGE(bufoff, gbase, voff) do { _Pragma("unroll") for (int _i = 0; _i < 2; ++_i) \
;         __builtin_amdgcn_global_load_lds((const unsigned*)((const char*)(gbase) + (size_t)_i * qstep + (voff)[0]), (PG8_LAS unsigned*)(lds + (bufoff) + ldsw + _i * 8192), 16, 0, 0); } while (0)
; #define PG8_LDA(dst, b, h) do { _Pragma("unroll") for (int m = 0; m < 4; ++m) _Pragma("unroll") for (int k = 0; k < 2; ++k) dst[m][k] = *(const PG8_LAS bf16x8*)(lds + PG8_SA(b, h) + aoff + m * 2048 + k * 1024); } while (0)
; #define PG8_LDB(dst, b, h) do { _Pragma("unroll") for (int n = 0; n < 2; ++n) _Pragma("unroll") for (int k = 0; k < 2; ++k) dst[n][k] = *(const PG8_LAS bf16x8*)(lds + PG8_SB(b, h) + boff + n * 2048 + k * 1024); } while (0)
; #define PG8_WAIT_V89() do { if constexpr (SLIVER) PG8_WAIT_V(9); else PG8_WAIT_V(8); } while (0)
; #define PG8_STAGE_S(b, gbase) do { if constexpr (SLIVER) __builtin_amdgcn_global_load_lds((const unsigned*)((const char*)(gbase) + voffS), (PG8_LAS unsigned*)(lds + STAGE_BYTES + (b) * 2048 + wid * 256), 4, 0, 0); } while (0)
; template <class Epi, class Sched, bool ALIGN_EPI = false, bool SP2 = false, bool SLIVER = false>
; __device__ __forceinline__ void gemm_phase(PG8_LAS unsigned char* lds, const Gemm g, const Sched& S, const Epi& E) {
;     ...
;         for (int t = 0; t < nt; t += 2) {
;             const bool last = (t == nt - 2);
;             const char* a1 = cA + (size_t)(t + 1) * kstep;
;             const char* a2 = last ? nA : cA + (size_t)(t + 2) * kstep; const char* b2 = last ? nB : cB + (size_t)(t + 2) * kstep;
;             const char* a3 = a2 + kstep; const char* b3 = b2 + kstep;
;             const char* s1 = cS + (size_t)(t + 1) * kstep; const char* s2 = last ? nS : cS + (size_t)(t + 2) * kstep;
;             if (last && has_next) S.a_ready(nxt);
;             if constexpr (SP2) {
;             PG8_LDB(B0, 0, 0); PG8_LDB(B1, 0, 1); PG8_SCHED; PG8_LDA(At, 0, 0); PG8_STAGE(PG8_SA(1, 1), a1 + hstep, voffA); PG8_STAGE_S(1, s1);
;             PG8_WAIT_V89(); PG8_WAIT_L(0); PG8_BAR; PG8_MMA(0, 0, At, B0); PG8_MMA(0, 1, At, B1); PG8_BAR; PG8_SCHED;
;             PG8_LDA(At, 0, 1); PG8_LDS_S(0); PG8_STAGE(PG8_SB(0, 0), b2, voffB); PG8_STAGE(PG8_SB(0, 1), b2 + hstep, voffB); PG8_STAGE(PG8_SA(0, 0), a2, voffA);
.LBB0_811:
	s_add_u32 s13, s90, s62
	s_addc_u32 s40, s91, s63
	s_add_u32 s13, s13, 0x100
	s_addc_u32 s66, s40, 0
	s_add_u32 s68, s2, s62
	s_addc_u32 s67, s3, s63
	s_add_i32 s69, 0, 0x10000
	s_cmpk_eq_i32 s62, 0x2b00
	s_cselect_b64 s[80:81], -1, 0
	s_and_b64 s[40:41], s[80:81], exec
	s_cselect_b32 s41, s85, s66
	s_cselect_b32 s40, s84, s13
	v_add_u32_e32 v66, s69, v220
	s_cselect_b32 s67, s87, s67
	s_cselect_b32 s66, s86, s68
	s_add_i32 s13, 0, 0x14000
	ds_read_b128 v[154:157], v66
	ds_read_b128 v[158:161], v66 offset:1024
	ds_read_b128 v[162:165], v66 offset:2048
	ds_read_b128 v[174:177], v66 offset:3072
	v_add_u32_e32 v66, s13, v220
	ds_read_b128 v[184:187], v66
	ds_read_b128 v[188:191], v66 offset:1024
	ds_read_b128 v[192:195], v66 offset:2048
	ds_read_b128 v[180:183], v66 offset:3072
	v_lshl_add_u64 v[146:147], v[214:215], 0, s[62:63]
	v_lshl_add_u64 v[148:149], v[146:147], 0, s[8:9]
	s_add_i32 m0, s19, 0xc000
	s_mov_b64 s[94:95], 0x210080
	ds_read_b128 v[66:69], v223
	ds_read_b128 v[70:73], v223 offset:1024
	ds_read_b128 v[74:77], v223 offset:2048
	ds_read_b128 v[78:81], v223 offset:3072
	ds_read_b128 v[216:219], v223 offset:4096
	ds_read_b128 v[224:227], v223 offset:5120
	ds_read_b128 v[228:231], v223 offset:6144
	ds_read_b128 v[232:235], v223 offset:7168
	global_load_lds_dwordx4 v[148:149], off
	v_lshl_add_u64 v[146:147], v[146:147], 0, s[94:95]
	s_add_i32 m0, s19, 0xe000
	s_nop 0
	global_load_lds_dwordx4 v[146:147], off
	v_lshl_add_u64 v[146:147], v[212:213], 0, s[62:63]
	s_add_i32 m0, s96, 0x20800
	s_nop 0
	global_load_lds_dword v[146:147], off
	s_waitcnt vmcnt(9)
	s_waitcnt lgkmcnt(0)
	s_setprio 1
	s_barrier
	v_mfma_f32_16x16x32_bf16 v[146:149], v[154:157], v[66:69], v[170:173]
	v_mfma_f32_16x16x32_bf16 v[150:153], v[162:165], v[66:69], v[166:169]
	v_mfma_f32_16x16x32_bf16 v[134:137], v[154:157], v[74:77], v[134:137]
	v_mfma_f32_16x16x32_bf16 v[130:133], v[162:165], v[74:77], v[130:133]
	v_mfma_f32_16x16x32_bf16 v[118:121], v[154:157], v[216:219], v[118:121]
	v_mfma_f32_16x16x32_bf16 v[114:117], v[162:165], v[216:219], v[114:117]
	v_mfma_f32_16x16x32_bf16 v[102:105], v[154:157], v[228:231], v[102:105]
	v_mfma_f32_16x16x32_bf16 v[98:101], v[162:165], v[228:231], v[98:101]
	v_mfma_f32_16x16x32_bf16 v[146:149], v[158:161], v[70:73], v[146:149]
	v_mfma_f32_16x16x32_bf16 v[150:153], v[174:177], v[70:73], v[150:153]
	v_mfma_f32_16x16x32_bf16 v[134:137], v[158:161], v[78:81], v[134:137]
	v_mfma_f32_16x16x32_bf16 v[130:133], v[174:177], v[78:81], v[130:133]
	v_mfma_f32_16x16x32_bf16 v[118:121], v[158:161], v[224:227], v[118:121]
	v_mfma_f32_16x16x32_bf16 v[114:117], v[174:177], v[224:227], v[114:117]
	v_mfma_f32_16x16x32_bf16 v[102:105], v[158:161], v[232:235], v[102:105]
	v_mfma_f32_16x16x32_bf16 v[98:101], v[174:177], v[232:235], v[98:101]
	s_setprio 0
	s_setprio 1
	v_mfma_f32_16x16x32_bf16 v[142:145], v[184:187], v[66:69], v[142:145]
	v_mfma_f32_16x16x32_bf16 v[66:69], v[192:195], v[66:69], v[138:141]
	v_mfma_f32_16x16x32_bf16 v[138:141], v[180:183], v[70:73], v[66:69]
	v_mfma_f32_16x16x32_bf16 v[66:69], v[184:187], v[74:77], v[126:129]
	v_mfma_f32_16x16x32_bf16 v[126:129], v[188:191], v[78:81], v[66:69]
	v_mfma_f32_16x16x32_bf16 v[66:69], v[192:195], v[74:77], v[122:125]
	v_mfma_f32_16x16x32_bf16 v[122:125], v[180:183], v[78:81], v[66:69]
	v_mfma_f32_16x16x32_bf16 v[66:69], v[184:187], v[216:219], v[110:113]
	v_mfma_f32_16x16x32_bf16 v[110:113], v[188:191], v[224:227], v[66:69]
	v_mfma_f32_16x16x32_bf16 v[66:69], v[192:195], v[216:219], v[106:109]
	v_mfma_f32_16x16x32_bf16 v[106:109], v[180:183], v[224:227], v[66:69]
	v_mfma_f32_16x16x32_bf16 v[66:69], v[184:187], v[228:231], v[94:97]
	v_mfma_f32_16x16x32_bf16 v[94:97], v[188:191], v[232:235], v[66:69]
	v_mfma_f32_16x16x32_bf16 v[66:69], v[192:195], v[228:231], v[90:93]
	v_mfma_f32_16x16x32_bf16 v[142:145], v[188:191], v[70:73], v[142:145]
	v_mfma_f32_16x16x32_bf16 v[90:93], v[180:183], v[232:235], v[66:69]
	s_barrier
	s_setprio 0
	s_add_i32 s68, 0, 0x20000
	v_lshl_add_u64 v[216:217], s[66:67], 0, v[198:199]
	s_add_i32 s66, s69, s18
	v_add_u32_e32 v74, s68, v221
	v_add_u32_e32 v75, s68, v222
	s_mov_b32 m0, s66
	ds_read_b128 v[66:69], v223 offset:16384
	ds_read_b128 v[70:73], v223 offset:17408
	ds_read_b128 v[224:227], v223 offset:18432
	ds_read_b128 v[228:231], v223 offset:19456
	ds_read_b128 v[232:235], v223 offset:20480
	ds_read_b128 v[240:243], v223 offset:21504
	ds_read_b128 v[244:247], v223 offset:22528
	ds_read_b128 v[248:251], v223 offset:23552
	ds_read_b128 v[166:169], v74
	ds_read_b128 v[170:173], v75
	global_load_lds_dwordx4 v[216:217], off
	v_lshl_add_u64 v[74:75], v[216:217], 0, s[64:65]
	s_add_i32 m0, s66, 0x2000
	s_add_i32 s13, s13, s18
	global_load_lds_dwordx4 v[74:75], off
	v_lshl_add_u64 v[74:75], v[216:217], 0, s[0:1]
	s_mov_b32 m0, s13
	v_lshl_add_u64 v[218:219], s[40:41], 0, v[196:197]
	global_load_lds_dwordx4 v[74:75], off
	v_lshl_add_u64 v[74:75], v[216:217], 0, s[74:75]
	s_add_i32 m0, s13, 0x2000
	s_nop 0
	global_load_lds_dwordx4 v[74:75], off
	s_mov_b32 m0, s19
	v_lshl_add_u64 v[74:75], v[218:219], 0, s[64:65]
	global_load_lds_dwordx4 v[218:219], off
	s_mov_b32 m0, s52
	s_nop 0
	global_load_lds_dwordx4 v[74:75], off
	s_waitcnt vmcnt(9)
	s_waitcnt lgkmcnt(0)
	s_setprio 1
	s_barrier
; #define PG8_STAGE(bufoff, gbase, voff) do { _Pragma("unroll") for (int _i = 0; _i < 2; ++_i) \
;         __builtin_amdgcn_global_load_lds((const unsigned*)((const char*)(gbase) + (size_t)_i * qstep + (voff)[0]), (PG8_LAS unsigned*)(lds + (bufoff) + ldsw + _i * 8192), 16, 0, 0); } while (0)
; #define PG8_LDA(dst, b, h) do { _Pragma("unroll") for (int m = 0; m < 4; ++m) _Pragma("unroll") for (int k = 0; k < 2; ++k) dst[m][k] = *(const PG8_LAS bf16x8*)(lds + PG8_SA(b, h) + aoff + m * 2048 + k * 1024); } while (0)
; #define PG8_LDB(dst, b, h) do { _Pragma("unroll") for (int n = 0; n < 2; ++n) _Pragma("unroll") for (int k = 0; k < 2; ++k) dst[n][k] = *(const PG8_LAS bf16x8*)(lds + PG8_SB(b, h) + boff + n * 2048 + k * 1024); } while (0)
; #define PG8_MMA(ai, bj, At, Bt) do { __builtin_amdgcn_s_setprio(1); _Pragma("unroll") for (int m = 0; m < 4; ++m) _Pragma("unroll") for (int n = 0; n < 2; ++n) _Pragma("unroll") for (int k = 0; k < 2; ++k) \
;         acc[ai][bj][m][n] = __builtin_amdgcn_mfma_f32_16x16x32_bf16(Bt[n][k], At[m][k], acc[ai][bj][m][n], 0, 0, 0); __builtin_amdgcn_s_setprio(0); } while (0)
; #define PG8_WAIT_V89() do { if constexpr (SLIVER) PG8_WAIT_V(9); else PG8_WAIT_V(8); } while (0)
; #define PG8_STAGE_S(b, gbase) do { if constexpr (SLIVER) __builtin_amdgcn_global_load_lds((const unsigned*)((const char*)(gbase) + voffS), (PG8_LAS unsigned*)(lds + STAGE_BYTES + (b) * 2048 + wid * 256), 4, 0, 0); } while (0)
; #define PG8_WAIT_L(n) asm volatile("s_waitcnt lgkmcnt(" #n ")" ::: "memory")
; #define PG8_BAR __builtin_amdgcn_s_barrier()
; #define PG8_SCHED __builtin_amdgcn_sched_barrier(0)
; template <class Epi, class Sched, bool ALIGN_EPI = false, bool SP2 = false, bool SLIVER = false>
; __device__ __forceinline__ void gemm_phase(PG8_LAS unsigned char* lds, const Gemm g, const Sched& S, const Epi& E) {
;     ...
;             PG8_WAIT_V89(); PG8_WAIT_L(0); PG8_BAR; PG8_MMA(1, 0, At, B0); PG8_MMA(1, 1, At, B1); PG8_MMA_S(); PG8_BAR; PG8_SCHED;
;             PG8_LDB(B0, 1, 0); PG8_LDB(B1, 1, 1); PG8_SCHED; PG8_LDA(At, 1, 0); PG8_STAGE(PG8_SA(0, 1), a2 + hstep, voffA); PG8_STAGE_S(0, s2);
;             PG8_WAIT_V89(); PG8_WAIT_L(0); PG8_BAR; PG8_MMA(0, 0, At, B0); PG8_MMA(0, 1, At, B1); PG8_BAR; PG8_SCHED;
	v_mfma_f32_16x16x32_bf16 v[74:77], v[154:157], v[66:69], v[86:89]
	v_mfma_f32_16x16x32_bf16 v[78:81], v[162:165], v[66:69], v[82:85]
	v_mfma_f32_16x16x32_bf16 v[54:57], v[154:157], v[224:227], v[54:57]
	v_mfma_f32_16x16x32_bf16 v[50:53], v[162:165], v[224:227], v[50:53]
	v_mfma_f32_16x16x32_bf16 v[38:41], v[154:157], v[232:235], v[38:41]
	v_mfma_f32_16x16x32_bf16 v[34:37], v[162:165], v[232:235], v[34:37]
	v_mfma_f32_16x16x32_bf16 v[22:25], v[154:157], v[244:247], v[22:25]
	v_mfma_f32_16x16x32_bf16 v[18:21], v[162:165], v[244:247], v[18:21]
	v_mfma_f32_16x16x32_bf16 v[74:77], v[158:161], v[70:73], v[74:77]
	v_mfma_f32_16x16x32_bf16 v[78:81], v[174:177], v[70:73], v[78:81]
	v_mfma_f32_16x16x32_bf16 v[54:57], v[158:161], v[228:231], v[54:57]
	v_mfma_f32_16x16x32_bf16 v[50:53], v[174:177], v[228:231], v[50:53]
	v_mfma_f32_16x16x32_bf16 v[38:41], v[158:161], v[240:243], v[38:41]
	v_mfma_f32_16x16x32_bf16 v[34:37], v[174:177], v[240:243], v[34:37]
	v_mfma_f32_16x16x32_bf16 v[22:25], v[158:161], v[248:251], v[22:25]
	v_mfma_f32_16x16x32_bf16 v[18:21], v[174:177], v[248:251], v[18:21]
	s_setprio 0
	s_setprio 1
	v_mfma_f32_16x16x32_bf16 v[62:65], v[184:187], v[66:69], v[62:65]
	v_mfma_f32_16x16x32_bf16 v[58:61], v[192:195], v[66:69], v[58:61]
	v_mfma_f32_16x16x32_bf16 v[46:49], v[184:187], v[224:227], v[46:49]
	v_mfma_f32_16x16x32_bf16 v[42:45], v[192:195], v[224:227], v[42:45]
	v_mfma_f32_16x16x32_bf16 v[30:33], v[184:187], v[232:235], v[30:33]
	v_mfma_f32_16x16x32_bf16 v[26:29], v[192:195], v[232:235], v[26:29]
	v_mfma_f32_16x16x32_bf16 v[14:17], v[184:187], v[244:247], v[14:17]
	v_mfma_f32_16x16x32_bf16 v[10:13], v[192:195], v[244:247], v[10:13]
	v_mfma_f32_16x16x32_bf16 v[62:65], v[188:191], v[70:73], v[62:65]
	v_mfma_f32_16x16x32_bf16 v[58:61], v[180:183], v[70:73], v[58:61]
	v_mfma_f32_16x16x32_bf16 v[46:49], v[188:191], v[228:231], v[46:49]
	v_mfma_f32_16x16x32_bf16 v[42:45], v[180:183], v[228:231], v[42:45]
	v_mfma_f32_16x16x32_bf16 v[30:33], v[188:191], v[240:243], v[30:33]
	v_mfma_f32_16x16x32_bf16 v[26:29], v[180:183], v[240:243], v[26:29]
	v_mfma_f32_16x16x32_bf16 v[14:17], v[188:191], v[248:251], v[14:17]
	v_mfma_f32_16x16x32_bf16 v[10:13], v[180:183], v[248:251], v[10:13]
	s_setprio 0
	s_setprio 1
	v_mfma_f32_16x16x32_bf16 v[66:69], v[184:187], v[166:169], v[6:9]
	v_mfma_f32_16x16x32_bf16 v[70:73], v[192:195], v[166:169], v[2:5]
	v_mfma_f32_16x16x32_bf16 v[66:69], v[188:191], v[170:173], v[66:69]
	v_mfma_f32_16x16x32_bf16 v[70:73], v[180:183], v[170:173], v[70:73]
	s_barrier
	s_setprio 0
	s_add_u32 s13, s92, s62
	s_addc_u32 s66, s93, s63
	s_add_u32 s13, s13, 0x100
	s_addc_u32 s68, s66, 0
	s_and_b64 s[66:67], s[80:81], exec
	s_cselect_b32 s67, s89, s68
	s_cselect_b32 s66, s88, s13
	s_add_i32 s13, 0, 0x18000
	v_add_u32_e32 v2, s13, v220
	s_add_i32 s68, 0, 0x1c000
	ds_read_b128 v[154:157], v2
	ds_read_b128 v[158:161], v2 offset:1024
	ds_read_b128 v[162:165], v2 offset:2048
	ds_read_b128 v[174:177], v2 offset:3072
	v_add_u32_e32 v2, s68, v220
	ds_read_b128 v[184:187], v2
	ds_read_b128 v[188:191], v2 offset:1024
	ds_read_b128 v[192:195], v2 offset:2048
	ds_read_b128 v[180:183], v2 offset:3072
	s_mov_b32 m0, s53
	v_lshl_add_u64 v[166:167], v[218:219], 0, s[0:1]
	ds_read_b128 v[2:5], v223 offset:32768
	ds_read_b128 v[6:9], v223 offset:33792
	ds_read_b128 v[82:85], v223 offset:34816
	ds_read_b128 v[86:89], v223 offset:35840
	ds_read_b128 v[224:227], v223 offset:36864
	ds_read_b128 v[228:231], v223 offset:37888
	ds_read_b128 v[232:235], v223 offset:38912
	ds_read_b128 v[240:243], v223 offset:39936
	global_load_lds_dwordx4 v[166:167], off
	v_lshl_add_u64 v[166:167], v[218:219], 0, s[74:75]
	s_mov_b32 m0, s54
	s_nop 0
	global_load_lds_dwordx4 v[166:167], off
	v_lshl_add_u64 v[166:167], s[66:67], 0, v[200:201]
	s_mov_b32 m0, s55
	s_nop 0
	global_load_lds_dword v[166:167], off
	s_waitcnt vmcnt(9)
	s_waitcnt lgkmcnt(0)
	s_setprio 1
	s_barrier
; #define PG8_SB(B) __builtin_amdgcn_rcpf(1.f + expneg(B))
; #define PG8_SB(B) __builtin_amdgcn_rcpf(1.f + expneg(B))
; #define PG8_STAGE(bufoff, gbase, voff) do { _Pragma("unroll") for (int _i = 0; _i < 2; ++_i) \
;         __builtin_amdgcn_global_load_lds((const unsigned*)((const char*)(gbase) + (size_t)_i * qstep + (voff)[0]), (PG8_LAS unsigned*)(lds + (bufoff) + ldsw + _i * 8192), 16, 0, 0); } while (0)
; #define PG8_LDA(dst, b, h) do { _Pragma("unroll") for (int m = 0; m < 4; ++m) _Pragma("unroll") for (int k = 0; k < 2; ++k) dst[m][k] = *(const PG8_LAS bf16x8*)(lds + PG8_SA(b, h) + aoff + m * 2048 + k * 1024); } while (0)
; #define PG8_MMA(ai, bj, At, Bt) do { __builtin_amdgcn_s_setprio(1); _Pragma("unroll") for (int m = 0; m < 4; ++m) _Pragma("unroll") for (int n = 0; n < 2; ++n) _Pragma("unroll") for (int k = 0; k < 2; ++k) \
;         acc[ai][bj][m][n] = __builtin_amdgcn_mfma_f32_16x16x32_bf16(Bt[n][k], At[m][k], acc[ai][bj][m][n], 0, 0, 0); __builtin_amdgcn_s_setprio(0); } while (0)
; #define PG8_WAIT_V89() do { if constexpr (SLIVER) PG8_WAIT_V(9); else PG8_WAIT_V(8); } while (0)
; #define PG8_LDS_S(b) do { if constexpr (SLIVER) { Sf[0] = *(const PG8_LAS bf16x8*)(lds + STAGE_BYTES + (b) * 2048 + soff0); Sf[1] = *(const PG8_LAS bf16x8*)(lds + STAGE_BYTES + (b) * 2048 + (soff0 ^ 64)); } } while (0)
; #define PG8_WAIT_L(n) asm volatile("s_waitcnt lgkmcnt(" #n ")" ::: "memory")
; #define PG8_BAR __builtin_amdgcn_s_barrier()
; #define PG8_SCHED __builtin_amdgcn_sched_barrier(0)
; template <class Epi, class Sched, bool ALIGN_EPI = false, bool SP2 = false, bool SLIVER = false>
; __device__ __forceinline__ void gemm_phase(PG8_LAS unsigned char* lds, const Gemm g, const Sched& S, const Epi& E) {
;     ...
;             PG8_WAIT_V89(); PG8_WAIT_L(0); PG8_BAR; PG8_MMA(0, 0, At, B0); PG8_MMA(0, 1, At, B1); PG8_BAR; PG8_SCHED;
;             PG8_LDA(At, 1, 1); PG8_LDS_S(1); PG8_STAGE(PG8_SB(1, 0), b3, voffB); PG8_STAGE(PG8_SB(1, 1), b3 + hstep, voffB); PG8_STAGE(PG8_SA(1, 0), a3, voffA);
;             PG8_WAIT_V89(); PG8_WAIT_L(0); PG8_BAR; PG8_MMA(1, 0, At, B0); PG8_MMA(1, 1, At, B1); PG8_MMA_S(); PG8_BAR; PG8_SCHED;
	v_mfma_f32_16x16x32_bf16 v[146:149], v[154:157], v[2:5], v[146:149]
	v_mfma_f32_16x16x32_bf16 v[170:173], v[158:161], v[6:9], v[146:149]
	v_mfma_f32_16x16x32_bf16 v[146:149], v[162:165], v[2:5], v[150:153]
	v_mfma_f32_16x16x32_bf16 v[134:137], v[154:157], v[82:85], v[134:137]
	v_mfma_f32_16x16x32_bf16 v[130:133], v[162:165], v[82:85], v[130:133]
	v_mfma_f32_16x16x32_bf16 v[118:121], v[154:157], v[224:227], v[118:121]
	v_mfma_f32_16x16x32_bf16 v[114:117], v[162:165], v[224:227], v[114:117]
	v_mfma_f32_16x16x32_bf16 v[102:105], v[154:157], v[232:235], v[102:105]
	v_mfma_f32_16x16x32_bf16 v[98:101], v[162:165], v[232:235], v[98:101]
	v_mfma_f32_16x16x32_bf16 v[166:169], v[174:177], v[6:9], v[146:149]
	v_mfma_f32_16x16x32_bf16 v[134:137], v[158:161], v[86:89], v[134:137]
	v_mfma_f32_16x16x32_bf16 v[130:133], v[174:177], v[86:89], v[130:133]
	v_mfma_f32_16x16x32_bf16 v[118:121], v[158:161], v[228:231], v[118:121]
	v_mfma_f32_16x16x32_bf16 v[114:117], v[174:177], v[228:231], v[114:117]
	v_mfma_f32_16x16x32_bf16 v[102:105], v[158:161], v[240:243], v[102:105]
	v_mfma_f32_16x16x32_bf16 v[98:101], v[174:177], v[240:243], v[98:101]
	s_setprio 0
	s_setprio 1
	v_mfma_f32_16x16x32_bf16 v[142:145], v[184:187], v[2:5], v[142:145]
	v_mfma_f32_16x16x32_bf16 v[2:5], v[192:195], v[2:5], v[138:141]
	v_mfma_f32_16x16x32_bf16 v[138:141], v[180:183], v[6:9], v[2:5]
	v_mfma_f32_16x16x32_bf16 v[2:5], v[184:187], v[82:85], v[126:129]
	v_mfma_f32_16x16x32_bf16 v[126:129], v[188:191], v[86:89], v[2:5]
	v_mfma_f32_16x16x32_bf16 v[2:5], v[192:195], v[82:85], v[122:125]
	v_mfma_f32_16x16x32_bf16 v[122:125], v[180:183], v[86:89], v[2:5]
	v_mfma_f32_16x16x32_bf16 v[2:5], v[184:187], v[224:227], v[110:113]
	v_mfma_f32_16x16x32_bf16 v[110:113], v[188:191], v[228:231], v[2:5]
	v_mfma_f32_16x16x32_bf16 v[2:5], v[192:195], v[224:227], v[106:109]
	v_mfma_f32_16x16x32_bf16 v[106:109], v[180:183], v[228:231], v[2:5]
	v_mfma_f32_16x16x32_bf16 v[2:5], v[184:187], v[232:235], v[94:97]
	v_mfma_f32_16x16x32_bf16 v[94:97], v[188:191], v[240:243], v[2:5]
	v_mfma_f32_16x16x32_bf16 v[2:5], v[192:195], v[232:235], v[90:93]
	v_mfma_f32_16x16x32_bf16 v[142:145], v[188:191], v[6:9], v[142:145]
	v_mfma_f32_16x16x32_bf16 v[90:93], v[180:183], v[240:243], v[2:5]
	s_barrier
	s_setprio 0
	s_add_i32 s66, 0, 0x20800
	v_add_u32_e32 v82, s66, v221
	v_add_u32_e32 v83, s66, v222
	s_add_i32 s13, s13, s18
	ds_read_b128 v[2:5], v223 offset:49152
	ds_read_b128 v[6:9], v223 offset:50176
	ds_read_b128 v[224:227], v223 offset:51200
	ds_read_b128 v[228:231], v223 offset:52224
	ds_read_b128 v[232:235], v223 offset:53248
	ds_read_b128 v[240:243], v223 offset:54272
	ds_read_b128 v[244:247], v223 offset:55296
	ds_read_b128 v[248:251], v223 offset:56320
	ds_read_b128 v[146:149], v82
	ds_read_b128 v[150:153], v83
	v_lshl_add_u64 v[82:83], v[216:217], 0, s[26:27]
	s_mov_b32 m0, s13
	s_mov_b64 s[66:67], 0x210080
	global_load_lds_dwordx4 v[82:83], off
	v_lshl_add_u64 v[82:83], v[216:217], 0, s[60:61]
	s_add_i32 m0, s13, 0x2000
	s_add_i32 s13, s68, s18
	global_load_lds_dwordx4 v[82:83], off
	v_lshl_add_u64 v[82:83], v[216:217], 0, s[8:9]
	s_mov_b32 m0, s13
	s_nop 0
	global_load_lds_dwordx4 v[82:83], off
	v_lshl_add_u64 v[82:83], v[216:217], 0, s[66:67]
	s_add_i32 m0, s13, 0x2000
	s_nop 0
	global_load_lds_dwordx4 v[82:83], off
	v_lshl_add_u64 v[82:83], v[218:219], 0, s[26:27]
	s_mov_b32 m0, s10
	s_nop 0
	global_load_lds_dwordx4 v[82:83], off
	v_lshl_add_u64 v[82:83], v[218:219], 0, s[60:61]
	s_mov_b32 m0, s48
	s_nop 0
	global_load_lds_dwordx4 v[82:83], off
	s_waitcnt vmcnt(9)
	s_waitcnt lgkmcnt(0)
	s_setprio 1
	s_barrier
	v_mfma_f32_16x16x32_bf16 v[74:77], v[154:157], v[2:5], v[74:77]
	v_mfma_f32_16x16x32_bf16 v[86:89], v[158:161], v[6:9], v[74:77]
	v_mfma_f32_16x16x32_bf16 v[74:77], v[162:165], v[2:5], v[78:81]
	v_mfma_f32_16x16x32_bf16 v[54:57], v[154:157], v[224:227], v[54:57]
	v_mfma_f32_16x16x32_bf16 v[50:53], v[162:165], v[224:227], v[50:53]
	v_mfma_f32_16x16x32_bf16 v[38:41], v[154:157], v[232:235], v[38:41]
	v_mfma_f32_16x16x32_bf16 v[34:37], v[162:165], v[232:235], v[34:37]
	v_mfma_f32_16x16x32_bf16 v[22:25], v[154:157], v[244:247], v[22:25]
	v_mfma_f32_16x16x32_bf16 v[18:21], v[162:165], v[244:247], v[18:21]
	v_mfma_f32_16x16x32_bf16 v[82:85], v[174:177], v[6:9], v[74:77]
	v_mfma_f32_16x16x32_bf16 v[54:57], v[158:161], v[228:231], v[54:57]
	v_mfma_f32_16x16x32_bf16 v[50:53], v[174:177], v[228:231], v[50:53]
	v_mfma_f32_16x16x32_bf16 v[38:41], v[158:161], v[240:243], v[38:41]
	v_mfma_f32_16x16x32_bf16 v[34:37], v[174:177], v[240:243], v[34:37]
	v_mfma_f32_16x16x32_bf16 v[22:25], v[158:161], v[248:251], v[22:25]
	v_mfma_f32_16x16x32_bf16 v[18:21], v[174:177], v[248:251], v[18:21]
	s_setprio 0
	s_setprio 1
	v_mfma_f32_16x16x32_bf16 v[62:65], v[184:187], v[2:5], v[62:65]
	v_mfma_f32_16x16x32_bf16 v[2:5], v[192:195], v[2:5], v[58:61]
	v_mfma_f32_16x16x32_bf16 v[58:61], v[180:183], v[6:9], v[2:5]
	v_mfma_f32_16x16x32_bf16 v[2:5], v[184:187], v[224:227], v[46:49]
	v_mfma_f32_16x16x32_bf16 v[46:49], v[188:191], v[228:231], v[2:5]
	v_mfma_f32_16x16x32_bf16 v[2:5], v[192:195], v[224:227], v[42:45]
	v_mfma_f32_16x16x32_bf16 v[42:45], v[180:183], v[228:231], v[2:5]
	v_mfma_f32_16x16x32_bf16 v[2:5], v[184:187], v[232:235], v[30:33]
	v_mfma_f32_16x16x32_bf16 v[30:33], v[188:191], v[240:243], v[2:5]
	v_mfma_f32_16x16x32_bf16 v[2:5], v[192:195], v[232:235], v[26:29]
	v_mfma_f32_16x16x32_bf16 v[26:29], v[180:183], v[240:243], v[2:5]
	v_mfma_f32_16x16x32_bf16 v[2:5], v[184:187], v[244:247], v[14:17]
	v_mfma_f32_16x16x32_bf16 v[14:17], v[188:191], v[248:251], v[2:5]
	v_mfma_f32_16x16x32_bf16 v[2:5], v[192:195], v[244:247], v[10:13]
	v_mfma_f32_16x16x32_bf16 v[62:65], v[188:191], v[6:9], v[62:65]
	v_mfma_f32_16x16x32_bf16 v[10:13], v[180:183], v[248:251], v[2:5]
	s_setprio 0
	s_setprio 1
	v_mfma_f32_16x16x32_bf16 v[2:5], v[184:187], v[146:149], v[66:69]
	v_mfma_f32_16x16x32_bf16 v[6:9], v[188:191], v[150:153], v[2:5]
	v_mfma_f32_16x16x32_bf16 v[2:5], v[192:195], v[146:149], v[70:73]
	v_mfma_f32_16x16x32_bf16 v[2:5], v[180:183], v[150:153], v[2:5]
	s_branch .LBB0_810

; #define PG8_SB(B) __builtin_amdgcn_rcpf(1.f + expneg(B))
; #define PG8_SB(B) __builtin_amdgcn_rcpf(1.f + expneg(B))
; #define PG8_STAGE(bufoff, gbase, voff) do { _Pragma("unroll") for (int _i = 0; _i < 2; ++_i) \
;         __builtin_amdgcn_global_load_lds((const unsigned*)((const char*)(gbase) + (size_t)_i * qstep + (voff)[0]), (PG8_LAS unsigned*)(lds + (bufoff) + ldsw + _i * 8192), 16, 0, 0); } while (0)
; #define PG8_LDA(dst, b, h) do { _Pragma("unroll") for (int m = 0; m < 4; ++m) _Pragma("unroll") for (int k = 0; k < 2; ++k) dst[m][k] = *(const PG8_LAS bf16x8*)(lds + PG8_SA(b, h) + aoff + m * 2048 + k * 1024); } while (0)
; #define PG8_LDB(dst, b, h) do { _Pragma("unroll") for (int n = 0; n < 2; ++n) _Pragma("unroll") for (int k = 0; k < 2; ++k) dst[n][k] = *(const PG8_LAS bf16x8*)(lds + PG8_SB(b, h) + boff + n * 2048 + k * 1024); } while (0)
; #define PG8_WAIT_V89() do { if constexpr (SLIVER) PG8_WAIT_V(9); else PG8_WAIT_V(8); } while (0)
; #define PG8_STAGE_S(b, gbase) do { if constexpr (SLIVER) __builtin_amdgcn_global_load_lds((const unsigned*)((const char*)(gbase) + voffS), (PG8_LAS unsigned*)(lds + STAGE_BYTES + (b) * 2048 + wid * 256), 4, 0, 0); } while (0)
; template <class Epi, class Sched, bool ALIGN_EPI = false, bool SP2 = false, bool SLIVER = false>
; __device__ __forceinline__ void gemm_phase(PG8_LAS unsigned char* lds, const Gemm g, const Sched& S, const Epi& E) {
;     ...
;         for (int t = 0; t < nt; t += 2) {
;             const bool last = (t == nt - 2);
;             const char* a1 = cA + (size_t)(t + 1) * kstep;
;             const char* a2 = last ? nA : cA + (size_t)(t + 2) * kstep; const char* b2 = last ? nB : cB + (size_t)(t + 2) * kstep;
;             const char* a3 = a2 + kstep; const char* b3 = b2 + kstep;
;             const char* s1 = cS + (size_t)(t + 1) * kstep; const char* s2 = last ? nS : cS + (size_t)(t + 2) * kstep;
;             if (last && has_next) S.a_ready(nxt);
;             if constexpr (SP2) {
;             PG8_LDB(B0, 0, 0); PG8_LDB(B1, 0, 1); PG8_SCHED; PG8_LDA(At, 0, 0); PG8_STAGE(PG8_SA(1, 1), a1 + hstep, voffA); PG8_STAGE_S(1, s1);
;             PG8_WAIT_V89(); PG8_WAIT_L(0); PG8_BAR; PG8_MMA(0, 0, At, B0); PG8_MMA(0, 1, At, B1); PG8_BAR; PG8_SCHED;
;             PG8_LDA(At, 0, 1); PG8_LDS_S(0); PG8_STAGE(PG8_SB(0, 0), b2, voffB); PG8_STAGE(PG8_SB(0, 1), b2 + hstep, voffB); PG8_STAGE(PG8_SA(0, 0), a2, voffA);
.LslvB_hdr2:
	s_add_u32 s13, s90, s62
	s_addc_u32 s40, s91, s63
	s_add_u32 s13, s13, 0x100
	s_addc_u32 s66, s40, 0
	s_add_u32 s68, s2, s62
	s_addc_u32 s67, s3, s63
	s_add_i32 s69, 0, 0x10000
	s_cmpk_eq_i32 s62, 0x2b00
	s_cselect_b64 s[80:81], -1, 0
	s_and_b64 s[40:41], s[80:81], exec
	s_cselect_b32 s41, s85, s66
	s_cselect_b32 s40, s84, s13
	v_add_u32_e32 v66, s69, v220
	s_cselect_b32 s67, s87, s67
	s_cselect_b32 s66, s86, s68
	s_add_i32 s13, 0, 0x14000
	ds_read_b128 v[154:157], v66
	ds_read_b128 v[158:161], v66 offset:1024
	ds_read_b128 v[162:165], v66 offset:2048
	ds_read_b128 v[174:177], v66 offset:3072
	v_add_u32_e32 v66, s13, v220
	ds_read_b128 v[184:187], v66
	ds_read_b128 v[188:191], v66 offset:1024
	ds_read_b128 v[192:195], v66 offset:2048
	ds_read_b128 v[180:183], v66 offset:3072
	v_lshl_add_u64 v[146:147], v[214:215], 0, s[62:63]
	v_lshl_add_u64 v[148:149], v[146:147], 0, s[8:9]
	s_add_i32 m0, s19, 0xc000
	s_mov_b64 s[94:95], 0x210080
	ds_read_b128 v[66:69], v223
	ds_read_b128 v[70:73], v223 offset:1024
	ds_read_b128 v[74:77], v223 offset:2048
	ds_read_b128 v[78:81], v223 offset:3072
	ds_read_b128 v[216:219], v223 offset:4096
	ds_read_b128 v[224:227], v223 offset:5120
	ds_read_b128 v[228:231], v223 offset:6144
	ds_read_b128 v[232:235], v223 offset:7168
	global_load_lds_dwordx4 v[148:149], off
	v_lshl_add_u64 v[146:147], v[146:147], 0, s[94:95]
	s_add_i32 m0, s19, 0xe000
	s_nop 0
	global_load_lds_dwordx4 v[146:147], off
	v_lshl_add_u64 v[146:147], v[212:213], 0, s[62:63]
	s_add_i32 m0, s96, 0x20800
	s_nop 0
	global_load_lds_dword v[146:147], off
	s_waitcnt vmcnt(9)
	s_waitcnt lgkmcnt(0)
	s_setprio 1
	s_barrier
	v_mfma_f32_16x16x32_bf16 v[146:149], v[154:157], v[66:69], v[170:173]
	v_mfma_f32_16x16x32_bf16 v[150:153], v[162:165], v[66:69], v[166:169]
	v_mfma_f32_16x16x32_bf16 v[134:137], v[154:157], v[74:77], v[134:137]
	v_mfma_f32_16x16x32_bf16 v[130:133], v[162:165], v[74:77], v[130:133]
	v_mfma_f32_16x16x32_bf16 v[118:121], v[154:157], v[216:219], v[118:121]
	v_mfma_f32_16x16x32_bf16 v[114:117], v[162:165], v[216:219], v[114:117]
	v_mfma_f32_16x16x32_bf16 v[102:105], v[154:157], v[228:231], v[102:105]
	v_mfma_f32_16x16x32_bf16 v[98:101], v[162:165], v[228:231], v[98:101]
	v_mfma_f32_16x16x32_bf16 v[146:149], v[158:161], v[70:73], v[146:149]
	v_mfma_f32_16x16x32_bf16 v[150:153], v[174:177], v[70:73], v[150:153]
	v_mfma_f32_16x16x32_bf16 v[134:137], v[158:161], v[78:81], v[134:137]
	v_mfma_f32_16x16x32_bf16 v[130:133], v[174:177], v[78:81], v[130:133]
	v_mfma_f32_16x16x32_bf16 v[118:121], v[158:161], v[224:227], v[118:121]
	v_mfma_f32_16x16x32_bf16 v[114:117], v[174:177], v[224:227], v[114:117]
	v_mfma_f32_16x16x32_bf16 v[102:105], v[158:161], v[232:235], v[102:105]
	v_mfma_f32_16x16x32_bf16 v[98:101], v[174:177], v[232:235], v[98:101]
	s_setprio 0
	s_setprio 1
	v_mfma_f32_16x16x32_bf16 v[142:145], v[184:187], v[66:69], v[142:145]
	v_mfma_f32_16x16x32_bf16 v[66:69], v[192:195], v[66:69], v[138:141]
	v_mfma_f32_16x16x32_bf16 v[138:141], v[180:183], v[70:73], v[66:69]
	v_mfma_f32_16x16x32_bf16 v[66:69], v[184:187], v[74:77], v[126:129]
	v_mfma_f32_16x16x32_bf16 v[126:129], v[188:191], v[78:81], v[66:69]
	v_mfma_f32_16x16x32_bf16 v[66:69], v[192:195], v[74:77], v[122:125]
	v_mfma_f32_16x16x32_bf16 v[122:125], v[180:183], v[78:81], v[66:69]
	v_mfma_f32_16x16x32_bf16 v[66:69], v[184:187], v[216:219], v[110:113]
	v_mfma_f32_16x16x32_bf16 v[110:113], v[188:191], v[224:227], v[66:69]
	v_mfma_f32_16x16x32_bf16 v[66:69], v[192:195], v[216:219], v[106:109]
	v_mfma_f32_16x16x32_bf16 v[106:109], v[180:183], v[224:227], v[66:69]
	v_mfma_f32_16x16x32_bf16 v[66:69], v[184:187], v[228:231], v[94:97]
	v_mfma_f32_16x16x32_bf16 v[94:97], v[188:191], v[232:235], v[66:69]
	v_mfma_f32_16x16x32_bf16 v[66:69], v[192:195], v[228:231], v[90:93]
	v_mfma_f32_16x16x32_bf16 v[142:145], v[188:191], v[70:73], v[142:145]
	v_mfma_f32_16x16x32_bf16 v[90:93], v[180:183], v[232:235], v[66:69]
	s_barrier
	s_setprio 0
	s_add_i32 s68, 0, 0x20000
	v_lshl_add_u64 v[216:217], s[66:67], 0, v[198:199]
	s_add_i32 s66, s69, s18
	v_add_u32_e32 v74, s68, v221
	v_add_u32_e32 v75, s68, v222
	s_mov_b32 m0, s66
	ds_read_b128 v[66:69], v223 offset:16384
	ds_read_b128 v[70:73], v223 offset:17408
	ds_read_b128 v[224:227], v223 offset:18432
	ds_read_b128 v[228:231], v223 offset:19456
	ds_read_b128 v[232:235], v223 offset:20480
	ds_read_b128 v[240:243], v223 offset:21504
	ds_read_b128 v[244:247], v223 offset:22528
	ds_read_b128 v[248:251], v223 offset:23552
	ds_read_b128 v[166:169], v74
	ds_read_b128 v[170:173], v75
	global_load_lds_dwordx4 v[216:217], off
	v_lshl_add_u64 v[74:75], v[216:217], 0, s[64:65]
	s_add_i32 m0, s66, 0x2000
	s_add_i32 s13, s13, s18
	global_load_lds_dwordx4 v[74:75], off
	v_lshl_add_u64 v[74:75], v[216:217], 0, s[0:1]
	s_mov_b32 m0, s13
	v_lshl_add_u64 v[218:219], s[40:41], 0, v[196:197]
	global_load_lds_dwordx4 v[74:75], off
	v_lshl_add_u64 v[74:75], v[216:217], 0, s[74:75]
	s_add_i32 m0, s13, 0x2000
	s_nop 0
	global_load_lds_dwordx4 v[74:75], off
	s_mov_b32 m0, s19
	v_lshl_add_u64 v[74:75], v[218:219], 0, s[64:65]
	global_load_lds_dwordx4 v[218:219], off
	s_mov_b32 m0, s52
	s_nop 0
	global_load_lds_dwordx4 v[74:75], off
	s_waitcnt vmcnt(9)
	s_waitcnt lgkmcnt(0)
	s_setprio 1
	s_barrier
; #define PG8_STAGE(bufoff, gbase, voff) do { _Pragma("unroll") for (int _i = 0; _i < 2; ++_i) \
;         __builtin_amdgcn_global_load_lds((const unsigned*)((const char*)(gbase) + (size_t)_i * qstep + (voff)[0]), (PG8_LAS unsigned*)(lds + (bufoff) + ldsw + _i * 8192), 16, 0, 0); } while (0)
; #define PG8_LDA(dst, b, h) do { _Pragma("unroll") for (int m = 0; m < 4; ++m) _Pragma("unroll") for (int k = 0; k < 2; ++k) dst[m][k] = *(const PG8_LAS bf16x8*)(lds + PG8_SA(b, h) + aoff + m * 2048 + k * 1024); } while (0)
; #define PG8_LDB(dst, b, h) do { _Pragma("unroll") for (int n = 0; n < 2; ++n) _Pragma("unroll") for (int k = 0; k < 2; ++k) dst[n][k] = *(const PG8_LAS bf16x8*)(lds + PG8_SB(b, h) + boff + n * 2048 + k * 1024); } while (0)
; #define PG8_MMA(ai, bj, At, Bt) do { __builtin_amdgcn_s_setprio(1); _Pragma("unroll") for (int m = 0; m < 4; ++m) _Pragma("unroll") for (int n = 0; n < 2; ++n) _Pragma("unroll") for (int k = 0; k < 2; ++k) \
;         acc[ai][bj][m][n] = __builtin_amdgcn_mfma_f32_16x16x32_bf16(Bt[n][k], At[m][k], acc[ai][bj][m][n], 0, 0, 0); __builtin_amdgcn_s_setprio(0); } while (0)
; #define PG8_WAIT_V89() do { if constexpr (SLIVER) PG8_WAIT_V(9); else PG8_WAIT_V(8); } while (0)
; #define PG8_STAGE_S(b, gbase) do { if constexpr (SLIVER) __builtin_amdgcn_global_load_lds((const unsigned*)((const char*)(gbase) + voffS), (PG8_LAS unsigned*)(lds + STAGE_BYTES + (b) * 2048 + wid * 256), 4, 0, 0); } while (0)
; #define PG8_WAIT_L(n) asm volatile("s_waitcnt lgkmcnt(" #n ")" ::: "memory")
; #define PG8_BAR __builtin_amdgcn_s_barrier()
; #define PG8_SCHED __builtin_amdgcn_sched_barrier(0)
; template <class Epi, class Sched, bool ALIGN_EPI = false, bool SP2 = false, bool SLIVER = false>
; __device__ __forceinline__ void gemm_phase(PG8_LAS unsigned char* lds, const Gemm g, const Sched& S, const Epi& E) {
;     ...
;             PG8_WAIT_V89(); PG8_WAIT_L(0); PG8_BAR; PG8_MMA(1, 0, At, B0); PG8_MMA(1, 1, At, B1); PG8_MMA_S(); PG8_BAR; PG8_SCHED;
;             PG8_LDB(B0, 1, 0); PG8_LDB(B1, 1, 1); PG8_SCHED; PG8_LDA(At, 1, 0); PG8_STAGE(PG8_SA(0, 1), a2 + hstep, voffA); PG8_STAGE_S(0, s2);
;             PG8_WAIT_V89(); PG8_WAIT_L(0); PG8_BAR; PG8_MMA(0, 0, At, B0); PG8_MMA(0, 1, At, B1); PG8_BAR; PG8_SCHED;
	v_mfma_f32_16x16x32_bf16 v[74:77], v[154:157], v[66:69], v[86:89]
	v_mfma_f32_16x16x32_bf16 v[78:81], v[162:165], v[66:69], v[82:85]
	v_mfma_f32_16x16x32_bf16 v[54:57], v[154:157], v[224:227], v[54:57]
	v_mfma_f32_16x16x32_bf16 v[50:53], v[162:165], v[224:227], v[50:53]
	v_mfma_f32_16x16x32_bf16 v[38:41], v[154:157], v[232:235], v[38:41]
	v_mfma_f32_16x16x32_bf16 v[34:37], v[162:165], v[232:235], v[34:37]
	v_mfma_f32_16x16x32_bf16 v[22:25], v[154:157], v[244:247], v[22:25]
	v_mfma_f32_16x16x32_bf16 v[18:21], v[162:165], v[244:247], v[18:21]
	v_mfma_f32_16x16x32_bf16 v[74:77], v[158:161], v[70:73], v[74:77]
	v_mfma_f32_16x16x32_bf16 v[78:81], v[174:177], v[70:73], v[78:81]
	v_mfma_f32_16x16x32_bf16 v[54:57], v[158:161], v[228:231], v[54:57]
	v_mfma_f32_16x16x32_bf16 v[50:53], v[174:177], v[228:231], v[50:53]
	v_mfma_f32_16x16x32_bf16 v[38:41], v[158:161], v[240:243], v[38:41]
	v_mfma_f32_16x16x32_bf16 v[34:37], v[174:177], v[240:243], v[34:37]
	v_mfma_f32_16x16x32_bf16 v[22:25], v[158:161], v[248:251], v[22:25]
	v_mfma_f32_16x16x32_bf16 v[18:21], v[174:177], v[248:251], v[18:21]
	s_setprio 0
	s_setprio 1
	v_mfma_f32_16x16x32_bf16 v[62:65], v[184:187], v[66:69], v[62:65]
	v_mfma_f32_16x16x32_bf16 v[58:61], v[192:195], v[66:69], v[58:61]
	v_mfma_f32_16x16x32_bf16 v[46:49], v[184:187], v[224:227], v[46:49]
	v_mfma_f32_16x16x32_bf16 v[42:45], v[192:195], v[224:227], v[42:45]
	v_mfma_f32_16x16x32_bf16 v[30:33], v[184:187], v[232:235], v[30:33]
	v_mfma_f32_16x16x32_bf16 v[26:29], v[192:195], v[232:235], v[26:29]
	v_mfma_f32_16x16x32_bf16 v[14:17], v[184:187], v[244:247], v[14:17]
	v_mfma_f32_16x16x32_bf16 v[10:13], v[192:195], v[244:247], v[10:13]
	v_mfma_f32_16x16x32_bf16 v[62:65], v[188:191], v[70:73], v[62:65]
	v_mfma_f32_16x16x32_bf16 v[58:61], v[180:183], v[70:73], v[58:61]
	v_mfma_f32_16x16x32_bf16 v[46:49], v[188:191], v[228:231], v[46:49]
	v_mfma_f32_16x16x32_bf16 v[42:45], v[180:183], v[228:231], v[42:45]
	v_mfma_f32_16x16x32_bf16 v[30:33], v[188:191], v[240:243], v[30:33]
	v_mfma_f32_16x16x32_bf16 v[26:29], v[180:183], v[240:243], v[26:29]
	v_mfma_f32_16x16x32_bf16 v[14:17], v[188:191], v[248:251], v[14:17]
	v_mfma_f32_16x16x32_bf16 v[10:13], v[180:183], v[248:251], v[10:13]
	s_setprio 0
	s_setprio 1
	v_mfma_f32_16x16x32_bf16 v[6:9], v[154:157], v[166:169], v[6:9]
	v_mfma_f32_16x16x32_bf16 v[2:5], v[162:165], v[166:169], v[2:5]
	v_mfma_f32_16x16x32_bf16 v[66:69], v[158:161], v[170:173], v[6:9]
	v_mfma_f32_16x16x32_bf16 v[70:73], v[174:177], v[170:173], v[2:5]
	s_barrier
	s_setprio 0
	s_add_u32 s13, s92, s62
	s_addc_u32 s66, s93, s63
	s_add_u32 s13, s13, 0x100
	s_addc_u32 s68, s66, 0
	s_and_b64 s[66:67], s[80:81], exec
	s_cselect_b32 s67, s89, s68
	s_cselect_b32 s66, s88, s13
	s_add_i32 s13, 0, 0x18000
	v_add_u32_e32 v2, s13, v220
	s_add_i32 s68, 0, 0x1c000
	ds_read_b128 v[154:157], v2
	ds_read_b128 v[158:161], v2 offset:1024
	ds_read_b128 v[162:165], v2 offset:2048
	ds_read_b128 v[174:177], v2 offset:3072
	v_add_u32_e32 v2, s68, v220
	ds_read_b128 v[184:187], v2
	ds_read_b128 v[188:191], v2 offset:1024
	ds_read_b128 v[192:195], v2 offset:2048
	ds_read_b128 v[180:183], v2 offset:3072
	s_mov_b32 m0, s53
	v_lshl_add_u64 v[166:167], v[218:219], 0, s[0:1]
	ds_read_b128 v[2:5], v223 offset:32768
	ds_read_b128 v[6:9], v223 offset:33792
	ds_read_b128 v[82:85], v223 offset:34816
	ds_read_b128 v[86:89], v223 offset:35840
	ds_read_b128 v[224:227], v223 offset:36864
	ds_read_b128 v[228:231], v223 offset:37888
	ds_read_b128 v[232:235], v223 offset:38912
	ds_read_b128 v[240:243], v223 offset:39936
	global_load_lds_dwordx4 v[166:167], off
	v_lshl_add_u64 v[166:167], v[218:219], 0, s[74:75]
	s_mov_b32 m0, s54
	s_nop 0
	global_load_lds_dwordx4 v[166:167], off
	v_lshl_add_u64 v[166:167], s[66:67], 0, v[200:201]
	s_mov_b32 m0, s55
	s_nop 0
	global_load_lds_dword v[166:167], off
	s_waitcnt vmcnt(9)
	s_waitcnt lgkmcnt(0)
	s_setprio 1
	s_barrier
; #define PG8_SB(B) __builtin_amdgcn_rcpf(1.f + expneg(B))
; #define PG8_SB(B) __builtin_amdgcn_rcpf(1.f + expneg(B))
; #define PG8_STAGE(bufoff, gbase, voff) do { _Pragma("unroll") for (int _i = 0; _i < 2; ++_i) \
;         __builtin_amdgcn_global_load_lds((const unsigned*)((const char*)(gbase) + (size_t)_i * qstep + (voff)[0]), (PG8_LAS unsigned*)(lds + (bufoff) + ldsw + _i * 8192), 16, 0, 0); } while (0)
; #define PG8_LDA(dst, b, h) do { _Pragma("unroll") for (int m = 0; m < 4; ++m) _Pragma("unroll") for (int k = 0; k < 2; ++k) dst[m][k] = *(const PG8_LAS bf16x8*)(lds + PG8_SA(b, h) + aoff + m * 2048 + k * 1024); } while (0)
; #define PG8_MMA(ai, bj, At, Bt) do { __builtin_amdgcn_s_setprio(1); _Pragma("unroll") for (int m = 0; m < 4; ++m) _Pragma("unroll") for (int n = 0; n < 2; ++n) _Pragma("unroll") for (int k = 0; k < 2; ++k) \
;         acc[ai][bj][m][n] = __builtin_amdgcn_mfma_f32_16x16x32_bf16(Bt[n][k], At[m][k], acc[ai][bj][m][n], 0, 0, 0); __builtin_amdgcn_s_setprio(0); } while (0)
; #define PG8_WAIT_V89() do { if constexpr (SLIVER) PG8_WAIT_V(9); else PG8_WAIT_V(8); } while (0)
; #define PG8_LDS_S(b) do { if constexpr (SLIVER) { Sf[0] = *(const PG8_LAS bf16x8*)(lds + STAGE_BYTES + (b) * 2048 + soff0); Sf[1] = *(const PG8_LAS bf16x8*)(lds + STAGE_BYTES + (b) * 2048 + (soff0 ^ 64)); } } while (0)
; #define PG8_WAIT_L(n) asm volatile("s_waitcnt lgkmcnt(" #n ")" ::: "memory")
; #define PG8_BAR __builtin_amdgcn_s_barrier()
; #define PG8_SCHED __builtin_amdgcn_sched_barrier(0)
; template <class Epi, class Sched, bool ALIGN_EPI = false, bool SP2 = false, bool SLIVER = false>
; __device__ __forceinline__ void gemm_phase(PG8_LAS unsigned char* lds, const Gemm g, const Sched& S, const Epi& E) {
;     ...
;             PG8_WAIT_V89(); PG8_WAIT_L(0); PG8_BAR; PG8_MMA(0, 0, At, B0); PG8_MMA(0, 1, At, B1); PG8_BAR; PG8_SCHED;
;             PG8_LDA(At, 1, 1); PG8_LDS_S(1); PG8_STAGE(PG8_SB(1, 0), b3, voffB); PG8_STAGE(PG8_SB(1, 1), b3 + hstep, voffB); PG8_STAGE(PG8_SA(1, 0), a3, voffA);
;             PG8_WAIT_V89(); PG8_WAIT_L(0); PG8_BAR; PG8_MMA(1, 0, At, B0); PG8_MMA(1, 1, At, B1); PG8_MMA_S(); PG8_BAR; PG8_SCHED;
	v_mfma_f32_16x16x32_bf16 v[146:149], v[154:157], v[2:5], v[146:149]
	v_mfma_f32_16x16x32_bf16 v[170:173], v[158:161], v[6:9], v[146:149]
	v_mfma_f32_16x16x32_bf16 v[146:149], v[162:165], v[2:5], v[150:153]
	v_mfma_f32_16x16x32_bf16 v[134:137], v[154:157], v[82:85], v[134:137]
	v_mfma_f32_16x16x32_bf16 v[130:133], v[162:165], v[82:85], v[130:133]
	v_mfma_f32_16x16x32_bf16 v[118:121], v[154:157], v[224:227], v[118:121]
	v_mfma_f32_16x16x32_bf16 v[114:117], v[162:165], v[224:227], v[114:117]
	v_mfma_f32_16x16x32_bf16 v[102:105], v[154:157], v[232:235], v[102:105]
	v_mfma_f32_16x16x32_bf16 v[98:101], v[162:165], v[232:235], v[98:101]
	v_mfma_f32_16x16x32_bf16 v[166:169], v[174:177], v[6:9], v[146:149]
	v_mfma_f32_16x16x32_bf16 v[134:137], v[158:161], v[86:89], v[134:137]
	v_mfma_f32_16x16x32_bf16 v[130:133], v[174:177], v[86:89], v[130:133]
	v_mfma_f32_16x16x32_bf16 v[118:121], v[158:161], v[228:231], v[118:121]
	v_mfma_f32_16x16x32_bf16 v[114:117], v[174:177], v[228:231], v[114:117]
	v_mfma_f32_16x16x32_bf16 v[102:105], v[158:161], v[240:243], v[102:105]
	v_mfma_f32_16x16x32_bf16 v[98:101], v[174:177], v[240:243], v[98:101]
	s_setprio 0
	s_setprio 1
	v_mfma_f32_16x16x32_bf16 v[142:145], v[184:187], v[2:5], v[142:145]
	v_mfma_f32_16x16x32_bf16 v[2:5], v[192:195], v[2:5], v[138:141]
	v_mfma_f32_16x16x32_bf16 v[138:141], v[180:183], v[6:9], v[2:5]
	v_mfma_f32_16x16x32_bf16 v[2:5], v[184:187], v[82:85], v[126:129]
	v_mfma_f32_16x16x32_bf16 v[126:129], v[188:191], v[86:89], v[2:5]
	v_mfma_f32_16x16x32_bf16 v[2:5], v[192:195], v[82:85], v[122:125]
	v_mfma_f32_16x16x32_bf16 v[122:125], v[180:183], v[86:89], v[2:5]
	v_mfma_f32_16x16x32_bf16 v[2:5], v[184:187], v[224:227], v[110:113]
	v_mfma_f32_16x16x32_bf16 v[110:113], v[188:191], v[228:231], v[2:5]
	v_mfma_f32_16x16x32_bf16 v[2:5], v[192:195], v[224:227], v[106:109]
	v_mfma_f32_16x16x32_bf16 v[106:109], v[180:183], v[228:231], v[2:5]
	v_mfma_f32_16x16x32_bf16 v[2:5], v[184:187], v[232:235], v[94:97]
	v_mfma_f32_16x16x32_bf16 v[94:97], v[188:191], v[240:243], v[2:5]
	v_mfma_f32_16x16x32_bf16 v[2:5], v[192:195], v[232:235], v[90:93]
	v_mfma_f32_16x16x32_bf16 v[142:145], v[188:191], v[6:9], v[142:145]
	v_mfma_f32_16x16x32_bf16 v[90:93], v[180:183], v[240:243], v[2:5]
	s_barrier
	s_setprio 0
	s_add_i32 s66, 0, 0x20800
	v_add_u32_e32 v82, s66, v221
	v_add_u32_e32 v83, s66, v222
	s_add_i32 s13, s13, s18
	ds_read_b128 v[2:5], v223 offset:49152
	ds_read_b128 v[6:9], v223 offset:50176
	ds_read_b128 v[224:227], v223 offset:51200
	ds_read_b128 v[228:231], v223 offset:52224
	ds_read_b128 v[232:235], v223 offset:53248
	ds_read_b128 v[240:243], v223 offset:54272
	ds_read_b128 v[244:247], v223 offset:55296
	ds_read_b128 v[248:251], v223 offset:56320
	ds_read_b128 v[146:149], v82
	ds_read_b128 v[150:153], v83
	v_lshl_add_u64 v[82:83], v[216:217], 0, s[26:27]
	s_mov_b32 m0, s13
	s_mov_b64 s[66:67], 0x210080
	global_load_lds_dwordx4 v[82:83], off
	v_lshl_add_u64 v[82:83], v[216:217], 0, s[60:61]
	s_add_i32 m0, s13, 0x2000
	s_add_i32 s13, s68, s18
	global_load_lds_dwordx4 v[82:83], off
	v_lshl_add_u64 v[82:83], v[216:217], 0, s[8:9]
	s_mov_b32 m0, s13
	s_nop 0
	global_load_lds_dwordx4 v[82:83], off
	v_lshl_add_u64 v[82:83], v[216:217], 0, s[66:67]
	s_add_i32 m0, s13, 0x2000
	s_nop 0
	global_load_lds_dwordx4 v[82:83], off
	v_lshl_add_u64 v[82:83], v[218:219], 0, s[26:27]
	s_mov_b32 m0, s10
	s_nop 0
	global_load_lds_dwordx4 v[82:83], off
	v_lshl_add_u64 v[82:83], v[218:219], 0, s[60:61]
	s_mov_b32 m0, s48
	s_nop 0
	global_load_lds_dwordx4 v[82:83], off
	s_waitcnt vmcnt(9)
	s_waitcnt lgkmcnt(0)
	s_setprio 1
	s_barrier
	v_mfma_f32_16x16x32_bf16 v[74:77], v[154:157], v[2:5], v[74:77]
	v_mfma_f32_16x16x32_bf16 v[86:89], v[158:161], v[6:9], v[74:77]
	v_mfma_f32_16x16x32_bf16 v[74:77], v[162:165], v[2:5], v[78:81]
	v_mfma_f32_16x16x32_bf16 v[54:57], v[154:157], v[224:227], v[54:57]
	v_mfma_f32_16x16x32_bf16 v[50:53], v[162:165], v[224:227], v[50:53]
	v_mfma_f32_16x16x32_bf16 v[38:41], v[154:157], v[232:235], v[38:41]
	v_mfma_f32_16x16x32_bf16 v[34:37], v[162:165], v[232:235], v[34:37]
	v_mfma_f32_16x16x32_bf16 v[22:25], v[154:157], v[244:247], v[22:25]
	v_mfma_f32_16x16x32_bf16 v[18:21], v[162:165], v[244:247], v[18:21]
	v_mfma_f32_16x16x32_bf16 v[82:85], v[174:177], v[6:9], v[74:77]
	v_mfma_f32_16x16x32_bf16 v[54:57], v[158:161], v[228:231], v[54:57]
	v_mfma_f32_16x16x32_bf16 v[50:53], v[174:177], v[228:231], v[50:53]
	v_mfma_f32_16x16x32_bf16 v[38:41], v[158:161], v[240:243], v[38:41]
	v_mfma_f32_16x16x32_bf16 v[34:37], v[174:177], v[240:243], v[34:37]
	v_mfma_f32_16x16x32_bf16 v[22:25], v[158:161], v[248:251], v[22:25]
	v_mfma_f32_16x16x32_bf16 v[18:21], v[174:177], v[248:251], v[18:21]
	s_setprio 0
	s_setprio 1
	v_mfma_f32_16x16x32_bf16 v[62:65], v[184:187], v[2:5], v[62:65]
	v_mfma_f32_16x16x32_bf16 v[2:5], v[192:195], v[2:5], v[58:61]
	v_mfma_f32_16x16x32_bf16 v[58:61], v[180:183], v[6:9], v[2:5]
	v_mfma_f32_16x16x32_bf16 v[2:5], v[184:187], v[224:227], v[46:49]
	v_mfma_f32_16x16x32_bf16 v[46:49], v[188:191], v[228:231], v[2:5]
	v_mfma_f32_16x16x32_bf16 v[2:5], v[192:195], v[224:227], v[42:45]
	v_mfma_f32_16x16x32_bf16 v[42:45], v[180:183], v[228:231], v[2:5]
	v_mfma_f32_16x16x32_bf16 v[2:5], v[184:187], v[232:235], v[30:33]
	v_mfma_f32_16x16x32_bf16 v[30:33], v[188:191], v[240:243], v[2:5]
	v_mfma_f32_16x16x32_bf16 v[2:5], v[192:195], v[232:235], v[26:29]
	v_mfma_f32_16x16x32_bf16 v[26:29], v[180:183], v[240:243], v[2:5]
	v_mfma_f32_16x16x32_bf16 v[2:5], v[184:187], v[244:247], v[14:17]
	v_mfma_f32_16x16x32_bf16 v[14:17], v[188:191], v[248:251], v[2:5]
	v_mfma_f32_16x16x32_bf16 v[2:5], v[192:195], v[244:247], v[10:13]
	v_mfma_f32_16x16x32_bf16 v[62:65], v[188:191], v[6:9], v[62:65]
	v_mfma_f32_16x16x32_bf16 v[10:13], v[180:183], v[248:251], v[2:5]
	s_setprio 0
	s_setprio 1
	v_mfma_f32_16x16x32_bf16 v[2:5], v[154:157], v[146:149], v[66:69]
	v_mfma_f32_16x16x32_bf16 v[6:9], v[158:161], v[150:153], v[2:5]
	v_mfma_f32_16x16x32_bf16 v[2:5], v[162:165], v[146:149], v[70:73]
	v_mfma_f32_16x16x32_bf16 v[2:5], v[174:177], v[150:153], v[2:5]
	s_branch .LslvB_lend2

; template <class Epi, class Sched, bool ALIGN_EPI = false, bool SP2 = false, bool SLIVER = false>
; __device__ __forceinline__ void gemm_phase(PG8_LAS unsigned char* lds, const Gemm g, const Sched& S, const Epi& E) {
;     ...
;         const char* nA = has_next ? (const char*)g.A + (size_t)nxt.pm * tstep + Epi::k0(nxt.seg) * 2 : cA; const char* nB = has_next ? (const char*)g.Bt + (size_t)nxt.pn * tstep + Epi::k0(nxt.seg) * 2 : cB;
;         const char* nS = has_next ? (const char*)g.A + (size_t)S.srow0 * K * 2 + (size_t)nxt.pm * sstep + Epi::k0(nxt.seg) * 2 : cS;
;         for (int t = 0; t < nt; t += 2) {
;             const bool last = (t == nt - 2);
;             const char* a1 = cA + (size_t)(t + 1) * kstep;
;             const char* a2 = last ? nA : cA + (size_t)(t + 2) * kstep; const char* b2 = last ? nB : cB + (size_t)(t + 2) * kstep;
;             const char* a3 = a2 + kstep; const char* b3 = b2 + kstep;
;             const char* s1 = cS + (size_t)(t + 1) * kstep; const char* s2 = last ? nS : cS + (size_t)(t + 2) * kstep;
.LBB0_932:
	s_add_u32 s17, s62, 0x100
	v_writelane_b32 v254, s45, 39
	s_addc_u32 s45, s63, 0
	s_lshl_b32 s12, s2, 7
	v_lshl_add_u64 v[138:139], s[54:55], 0, v[196:197]
	s_addk_i32 s12, 0xfe00
	s_mov_b32 s78, s66
	v_lshl_add_u64 v[198:199], s[42:43], 0, v[194:195]
	v_lshl_add_u64 v[200:201], v[138:139], 0, s[26:27]
	s_add_u32 s66, s12, 0x100
	s_mov_b32 s67, 0
	s_mov_b64 s[62:63], 0
	s_and_b64 vcc, exec, s[90:91]
	s_cbranch_vccz .LslvB_hdr3
	s_branch .LBB0_934

; #define PG8_SB(B) __builtin_amdgcn_rcpf(1.f + expneg(B))
; #define PG8_SB(B) __builtin_amdgcn_rcpf(1.f + expneg(B))
; #define PG8_STAGE(bufoff, gbase, voff) do { _Pragma("unroll") for (int _i = 0; _i < 2; ++_i) \
;         __builtin_amdgcn_global_load_lds((const unsigned*)((const char*)(gbase) + (size_t)_i * qstep + (voff)[0]), (PG8_LAS unsigned*)(lds + (bufoff) + ldsw + _i * 8192), 16, 0, 0); } while (0)
; #define PG8_LDA(dst, b, h) do { _Pragma("unroll") for (int m = 0; m < 4; ++m) _Pragma("unroll") for (int k = 0; k < 2; ++k) dst[m][k] = *(const PG8_LAS bf16x8*)(lds + PG8_SA(b, h) + aoff + m * 2048 + k * 1024); } while (0)
; #define PG8_LDB(dst, b, h) do { _Pragma("unroll") for (int n = 0; n < 2; ++n) _Pragma("unroll") for (int k = 0; k < 2; ++k) dst[n][k] = *(const PG8_LAS bf16x8*)(lds + PG8_SB(b, h) + boff + n * 2048 + k * 1024); } while (0)
; #define PG8_MMA(ai, bj, At, Bt) do { __builtin_amdgcn_s_setprio(1); _Pragma("unroll") for (int m = 0; m < 4; ++m) _Pragma("unroll") for (int n = 0; n < 2; ++n) _Pragma("unroll") for (int k = 0; k < 2; ++k) \
;         acc[ai][bj][m][n] = __builtin_amdgcn_mfma_f32_16x16x32_bf16(Bt[n][k], At[m][k], acc[ai][bj][m][n], 0, 0, 0); __builtin_amdgcn_s_setprio(0); } while (0)
; #define PG8_WAIT_V89() do { if constexpr (SLIVER) PG8_WAIT_V(9); else PG8_WAIT_V(8); } while (0)
; #define PG8_STAGE_S(b, gbase) do { if constexpr (SLIVER) __builtin_amdgcn_global_load_lds((const unsigned*)((const char*)(gbase) + voffS), (PG8_LAS unsigned*)(lds + STAGE_BYTES + (b) * 2048 + wid * 256), 4, 0, 0); } while (0)
; #define PG8_BAR __builtin_amdgcn_s_barrier()
; template <class Epi, class Sched, bool ALIGN_EPI = false, bool SP2 = false, bool SLIVER = false>
; __device__ __forceinline__ void gemm_phase(PG8_LAS unsigned char* lds, const Gemm g, const Sched& S, const Epi& E) {
;     ...
;             PG8_LDB(B0, 0, 0); PG8_LDB(B1, 0, 1); PG8_SCHED; PG8_LDA(At, 0, 0); PG8_STAGE(PG8_SA(1, 1), a1 + hstep, voffA); PG8_STAGE_S(1, s1);
;             PG8_WAIT_V89(); PG8_WAIT_L(0); PG8_BAR; PG8_MMA(0, 0, At, B0); PG8_MMA(0, 1, At, B1); PG8_BAR; PG8_SCHED;
;             PG8_LDA(At, 0, 1); PG8_LDS_S(0); PG8_STAGE(PG8_SB(0, 0), b2, voffB); PG8_STAGE(PG8_SB(0, 1), b2 + hstep, voffB); PG8_STAGE(PG8_SA(0, 0), a2, voffA);
;             PG8_WAIT_V89(); PG8_WAIT_L(0); PG8_BAR; PG8_MMA(1, 0, At, B0); PG8_MMA(1, 1, At, B1); PG8_MMA_S(); PG8_BAR; PG8_SCHED;
.LBB0_934:
	s_cmp_eq_u32 s66, s62
	s_cselect_b64 s[80:81], -1, 0
	s_add_u32 s12, s42, s62
	s_addc_u32 s13, s43, s63
	s_add_u32 s40, s12, 0x100
	s_addc_u32 s41, s13, 0
	s_and_b64 s[12:13], s[80:81], exec
	s_cselect_b32 s41, s95, s41
	s_cselect_b32 s40, s94, s40
	s_add_u32 s68, s17, s62
	s_addc_u32 s69, s45, s63
	s_add_i32 s76, 0, 0x10000
	s_and_b64 s[12:13], s[80:81], exec
	v_add_u32_e32 v138, s76, v212
	s_cselect_b32 s13, s97, s69
	s_cselect_b32 s12, s96, s68
	s_add_i32 s68, 0, 0x14000
	ds_read_b128 v[146:149], v138
	ds_read_b128 v[150:153], v138 offset:1024
	ds_read_b128 v[154:157], v138 offset:2048
	ds_read_b128 v[158:161], v138 offset:3072
	v_add_u32_e32 v138, s68, v212
	ds_read_b128 v[166:169], v138
	ds_read_b128 v[170:173], v138 offset:1024
	ds_read_b128 v[174:177], v138 offset:2048
	ds_read_b128 v[162:165], v138 offset:3072
	v_lshl_add_u64 v[202:203], v[198:199], 0, s[62:63]
	s_mov_b64 vcc, 0x90080
	v_lshl_add_u64 v[208:209], v[202:203], 0, vcc
	s_add_i32 m0, s93, 0xc000
	s_mov_b64 vcc, 0xd8080
	ds_read_b128 v[138:141], v215
	ds_read_b128 v[142:145], v215 offset:1024
	ds_read_b128 v[180:183], v215 offset:2048
	ds_read_b128 v[184:187], v215 offset:3072
	ds_read_b128 v[216:219], v215 offset:4096
	ds_read_b128 v[220:223], v215 offset:5120
	ds_read_b128 v[224:227], v215 offset:6144
	ds_read_b128 v[228:231], v215 offset:7168
	global_load_lds_dwordx4 v[208:209], off
	v_lshl_add_u64 v[202:203], v[202:203], 0, vcc
	s_add_i32 m0, s93, 0xe000
	s_nop 0
	global_load_lds_dwordx4 v[202:203], off
	v_lshl_add_u64 v[202:203], v[200:201], 0, s[62:63]
	s_add_i32 m0, s50, 0x20800
	s_nop 0
	global_load_lds_dword v[202:203], off
	s_waitcnt vmcnt(9)
	s_waitcnt lgkmcnt(0)
	s_setprio 1
	s_barrier
	v_mfma_f32_16x16x32_bf16 v[134:137], v[146:149], v[138:141], v[134:137]
	v_mfma_f32_16x16x32_bf16 v[130:133], v[154:157], v[138:141], v[130:133]
	v_mfma_f32_16x16x32_bf16 v[126:129], v[146:149], v[180:183], v[126:129]
	v_mfma_f32_16x16x32_bf16 v[122:125], v[154:157], v[180:183], v[122:125]
	v_mfma_f32_16x16x32_bf16 v[114:117], v[146:149], v[216:219], v[114:117]
	v_mfma_f32_16x16x32_bf16 v[106:109], v[154:157], v[216:219], v[106:109]
	v_mfma_f32_16x16x32_bf16 v[98:101], v[146:149], v[224:227], v[98:101]
	v_mfma_f32_16x16x32_bf16 v[90:93], v[154:157], v[224:227], v[90:93]
	v_mfma_f32_16x16x32_bf16 v[134:137], v[150:153], v[142:145], v[134:137]
	v_mfma_f32_16x16x32_bf16 v[130:133], v[158:161], v[142:145], v[130:133]
	v_mfma_f32_16x16x32_bf16 v[126:129], v[150:153], v[184:187], v[126:129]
	v_mfma_f32_16x16x32_bf16 v[122:125], v[158:161], v[184:187], v[122:125]
	v_mfma_f32_16x16x32_bf16 v[114:117], v[150:153], v[220:223], v[114:117]
	v_mfma_f32_16x16x32_bf16 v[106:109], v[158:161], v[220:223], v[106:109]
	v_mfma_f32_16x16x32_bf16 v[98:101], v[150:153], v[228:231], v[98:101]
	v_mfma_f32_16x16x32_bf16 v[90:93], v[158:161], v[228:231], v[90:93]
	s_setprio 0
	s_setprio 1
	v_mfma_f32_16x16x32_bf16 v[118:121], v[166:169], v[138:141], v[118:121]
	v_mfma_f32_16x16x32_bf16 v[110:113], v[174:177], v[138:141], v[110:113]
	v_mfma_f32_16x16x32_bf16 v[102:105], v[166:169], v[180:183], v[102:105]
	v_mfma_f32_16x16x32_bf16 v[94:97], v[174:177], v[180:183], v[94:97]
	v_mfma_f32_16x16x32_bf16 v[86:89], v[166:169], v[216:219], v[86:89]
	v_mfma_f32_16x16x32_bf16 v[82:85], v[174:177], v[216:219], v[82:85]
	v_mfma_f32_16x16x32_bf16 v[78:81], v[166:169], v[224:227], v[78:81]
	v_mfma_f32_16x16x32_bf16 v[74:77], v[174:177], v[224:227], v[74:77]
	v_mfma_f32_16x16x32_bf16 v[118:121], v[170:173], v[142:145], v[118:121]
	v_mfma_f32_16x16x32_bf16 v[110:113], v[162:165], v[142:145], v[110:113]
	v_mfma_f32_16x16x32_bf16 v[102:105], v[170:173], v[184:187], v[102:105]
	v_mfma_f32_16x16x32_bf16 v[94:97], v[162:165], v[184:187], v[94:97]
	v_mfma_f32_16x16x32_bf16 v[86:89], v[170:173], v[220:223], v[86:89]
	v_mfma_f32_16x16x32_bf16 v[82:85], v[162:165], v[220:223], v[82:85]
	v_mfma_f32_16x16x32_bf16 v[78:81], v[170:173], v[228:231], v[78:81]
	v_mfma_f32_16x16x32_bf16 v[74:77], v[162:165], v[228:231], v[74:77]
	s_barrier
	s_setprio 0
	s_add_i32 s69, 0, 0x20000
	v_lshl_add_u64 v[202:203], s[12:13], 0, v[190:191]
	s_add_i32 s12, s76, s92
	v_add_u32_e32 v178, s69, v213
	v_add_u32_e32 v184, s69, v214
	s_mov_b32 m0, s12
	ds_read_b128 v[138:141], v215 offset:16384
	ds_read_b128 v[142:145], v215 offset:17408
	ds_read_b128 v[216:219], v215 offset:18432
	ds_read_b128 v[220:223], v215 offset:19456
	ds_read_b128 v[224:227], v215 offset:20480
	ds_read_b128 v[228:231], v215 offset:21504
	ds_read_b128 v[232:235], v215 offset:22528
	ds_read_b128 v[240:243], v215 offset:23552
	ds_read_b128 v[180:183], v178
	ds_read_b128 v[184:187], v184
	global_load_lds_dwordx4 v[202:203], off
	v_lshl_add_u64 v[208:209], v[202:203], 0, s[70:71]
	s_add_i32 m0, s12, 0x2000
	s_add_i32 s12, s68, s92
	global_load_lds_dwordx4 v[208:209], off
	v_lshl_add_u64 v[208:209], v[202:203], 0, s[46:47]
	s_mov_b32 m0, s12
	v_lshl_add_u64 v[210:211], s[40:41], 0, v[188:189]
	global_load_lds_dwordx4 v[208:209], off
	v_lshl_add_u64 v[208:209], v[202:203], 0, s[6:7]
	s_add_i32 m0, s12, 0x2000
	s_nop 0
	global_load_lds_dwordx4 v[208:209], off
	s_mov_b32 m0, s93
	v_lshl_add_u64 v[208:209], v[210:211], 0, s[70:71]
	global_load_lds_dwordx4 v[210:211], off
	s_mov_b32 m0, s48
	s_nop 0
	global_load_lds_dwordx4 v[208:209], off
	s_waitcnt vmcnt(9)
	s_waitcnt lgkmcnt(0)
	s_setprio 1
	s_barrier
; #define PG8_STAGE(bufoff, gbase, voff) do { _Pragma("unroll") for (int _i = 0; _i < 2; ++_i) \
;         __builtin_amdgcn_global_load_lds((const unsigned*)((const char*)(gbase) + (size_t)_i * qstep + (voff)[0]), (PG8_LAS unsigned*)(lds + (bufoff) + ldsw + _i * 8192), 16, 0, 0); } while (0)
; #define PG8_LDA(dst, b, h) do { _Pragma("unroll") for (int m = 0; m < 4; ++m) _Pragma("unroll") for (int k = 0; k < 2; ++k) dst[m][k] = *(const PG8_LAS bf16x8*)(lds + PG8_SA(b, h) + aoff + m * 2048 + k * 1024); } while (0)
; #define PG8_LDB(dst, b, h) do { _Pragma("unroll") for (int n = 0; n < 2; ++n) _Pragma("unroll") for (int k = 0; k < 2; ++k) dst[n][k] = *(const PG8_LAS bf16x8*)(lds + PG8_SB(b, h) + boff + n * 2048 + k * 1024); } while (0)
; #define PG8_MMA(ai, bj, At, Bt) do { __builtin_amdgcn_s_setprio(1); _Pragma("unroll") for (int m = 0; m < 4; ++m) _Pragma("unroll") for (int n = 0; n < 2; ++n) _Pragma("unroll") for (int k = 0; k < 2; ++k) \
;         acc[ai][bj][m][n] = __builtin_amdgcn_mfma_f32_16x16x32_bf16(Bt[n][k], At[m][k], acc[ai][bj][m][n], 0, 0, 0); __builtin_amdgcn_s_setprio(0); } while (0)
; #define PG8_WAIT_V89() do { if constexpr (SLIVER) PG8_WAIT_V(9); else PG8_WAIT_V(8); } while (0)
; #define PG8_STAGE_S(b, gbase) do { if constexpr (SLIVER) __builtin_amdgcn_global_load_lds((const unsigned*)((const char*)(gbase) + voffS), (PG8_LAS unsigned*)(lds + STAGE_BYTES + (b) * 2048 + wid * 256), 4, 0, 0); } while (0)
; #define PG8_WAIT_L(n) asm volatile("s_waitcnt lgkmcnt(" #n ")" ::: "memory")
; #define PG8_BAR __builtin_amdgcn_s_barrier()
; #define PG8_SCHED __builtin_amdgcn_sched_barrier(0)
; template <class Epi, class Sched, bool ALIGN_EPI = false, bool SP2 = false, bool SLIVER = false>
; __device__ __forceinline__ void gemm_phase(PG8_LAS unsigned char* lds, const Gemm g, const Sched& S, const Epi& E) {
;     ...
;             PG8_WAIT_V89(); PG8_WAIT_L(0); PG8_BAR; PG8_MMA(1, 0, At, B0); PG8_MMA(1, 1, At, B1); PG8_MMA_S(); PG8_BAR; PG8_SCHED;
;             PG8_LDB(B0, 1, 0); PG8_LDB(B1, 1, 1); PG8_SCHED; PG8_LDA(At, 1, 0); PG8_STAGE(PG8_SA(0, 1), a2 + hstep, voffA); PG8_STAGE_S(0, s2);
	v_mfma_f32_16x16x32_bf16 v[70:73], v[146:149], v[138:141], v[70:73]
	v_mfma_f32_16x16x32_bf16 v[66:69], v[154:157], v[138:141], v[66:69]
	v_mfma_f32_16x16x32_bf16 v[62:65], v[146:149], v[216:219], v[62:65]
	v_mfma_f32_16x16x32_bf16 v[58:61], v[154:157], v[216:219], v[58:61]
	v_mfma_f32_16x16x32_bf16 v[50:53], v[146:149], v[224:227], v[50:53]
	v_mfma_f32_16x16x32_bf16 v[42:45], v[154:157], v[224:227], v[42:45]
	v_mfma_f32_16x16x32_bf16 v[34:37], v[146:149], v[232:235], v[34:37]
	v_mfma_f32_16x16x32_bf16 v[26:29], v[154:157], v[232:235], v[26:29]
	v_mfma_f32_16x16x32_bf16 v[70:73], v[150:153], v[142:145], v[70:73]
	v_mfma_f32_16x16x32_bf16 v[66:69], v[158:161], v[142:145], v[66:69]
	v_mfma_f32_16x16x32_bf16 v[62:65], v[150:153], v[220:223], v[62:65]
	v_mfma_f32_16x16x32_bf16 v[58:61], v[158:161], v[220:223], v[58:61]
	v_mfma_f32_16x16x32_bf16 v[50:53], v[150:153], v[228:231], v[50:53]
	v_mfma_f32_16x16x32_bf16 v[42:45], v[158:161], v[228:231], v[42:45]
	v_mfma_f32_16x16x32_bf16 v[34:37], v[150:153], v[240:243], v[34:37]
	v_mfma_f32_16x16x32_bf16 v[26:29], v[158:161], v[240:243], v[26:29]
	s_setprio 0
	s_setprio 1
	v_mfma_f32_16x16x32_bf16 v[54:57], v[166:169], v[138:141], v[54:57]
	v_mfma_f32_16x16x32_bf16 v[46:49], v[174:177], v[138:141], v[46:49]
	v_mfma_f32_16x16x32_bf16 v[38:41], v[166:169], v[216:219], v[38:41]
	v_mfma_f32_16x16x32_bf16 v[30:33], v[174:177], v[216:219], v[30:33]
	v_mfma_f32_16x16x32_bf16 v[22:25], v[166:169], v[224:227], v[22:25]
	v_mfma_f32_16x16x32_bf16 v[18:21], v[174:177], v[224:227], v[18:21]
	v_mfma_f32_16x16x32_bf16 v[14:17], v[166:169], v[232:235], v[14:17]
	v_mfma_f32_16x16x32_bf16 v[10:13], v[174:177], v[232:235], v[10:13]
	v_mfma_f32_16x16x32_bf16 v[54:57], v[170:173], v[142:145], v[54:57]
	v_mfma_f32_16x16x32_bf16 v[46:49], v[162:165], v[142:145], v[46:49]
	v_mfma_f32_16x16x32_bf16 v[38:41], v[170:173], v[220:223], v[38:41]
	v_mfma_f32_16x16x32_bf16 v[30:33], v[162:165], v[220:223], v[30:33]
	v_mfma_f32_16x16x32_bf16 v[22:25], v[170:173], v[228:231], v[22:25]
	v_mfma_f32_16x16x32_bf16 v[18:21], v[162:165], v[228:231], v[18:21]
	v_mfma_f32_16x16x32_bf16 v[14:17], v[170:173], v[240:243], v[14:17]
	v_mfma_f32_16x16x32_bf16 v[10:13], v[162:165], v[240:243], v[10:13]
	s_setprio 0
	s_setprio 1
	v_mfma_f32_16x16x32_bf16 v[138:141], v[166:169], v[180:183], v[6:9]
	v_mfma_f32_16x16x32_bf16 v[142:145], v[174:177], v[180:183], v[2:5]
	v_mfma_f32_16x16x32_bf16 v[138:141], v[170:173], v[184:187], v[138:141]
	v_mfma_f32_16x16x32_bf16 v[142:145], v[162:165], v[184:187], v[142:145]
	s_barrier
	s_setprio 0
	s_add_u32 s12, s54, s62
	s_addc_u32 s13, s55, s63
	s_add_u32 s68, s12, 0x100
	s_addc_u32 s69, s13, 0
	s_and_b64 s[12:13], s[80:81], exec
	s_cselect_b32 s13, s19, s69
	s_cselect_b32 s12, s18, s68
	s_add_i32 s68, 0, 0x18000
	v_add_u32_e32 v2, s68, v212
	s_add_i32 s69, 0, 0x1c000
	ds_read_b128 v[146:149], v2
	ds_read_b128 v[150:153], v2 offset:1024
	ds_read_b128 v[154:157], v2 offset:2048
	ds_read_b128 v[158:161], v2 offset:3072
	v_add_u32_e32 v2, s69, v212
	ds_read_b128 v[166:169], v2
	ds_read_b128 v[170:173], v2 offset:1024
	ds_read_b128 v[174:177], v2 offset:2048
	ds_read_b128 v[162:165], v2 offset:3072
	s_mov_b32 m0, s49
	v_lshl_add_u64 v[208:209], v[210:211], 0, s[46:47]
	ds_read_b128 v[2:5], v215 offset:32768
	ds_read_b128 v[6:9], v215 offset:33792
	ds_read_b128 v[180:183], v215 offset:34816
	ds_read_b128 v[184:187], v215 offset:35840
	ds_read_b128 v[216:219], v215 offset:36864
	ds_read_b128 v[220:223], v215 offset:37888
	ds_read_b128 v[224:227], v215 offset:38912
	ds_read_b128 v[228:231], v215 offset:39936
	global_load_lds_dwordx4 v[208:209], off
	v_lshl_add_u64 v[208:209], v[210:211], 0, s[6:7]
	s_mov_b32 m0, s88
	s_nop 0
	global_load_lds_dwordx4 v[208:209], off
	v_lshl_add_u64 v[208:209], s[12:13], 0, v[192:193]
	s_mov_b32 m0, s89
	s_nop 0
	global_load_lds_dword v[208:209], off
	s_waitcnt vmcnt(9)
	s_waitcnt lgkmcnt(0)
	s_setprio 1
	s_barrier
; #define PG8_SB(B) __builtin_amdgcn_rcpf(1.f + expneg(B))
; #define PG8_SB(B) __builtin_amdgcn_rcpf(1.f + expneg(B))
; #define PG8_STAGE(bufoff, gbase, voff) do { _Pragma("unroll") for (int _i = 0; _i < 2; ++_i) \
;         __builtin_amdgcn_global_load_lds((const unsigned*)((const char*)(gbase) + (size_t)_i * qstep + (voff)[0]), (PG8_LAS unsigned*)(lds + (bufoff) + ldsw + _i * 8192), 16, 0, 0); } while (0)
; #define PG8_LDA(dst, b, h) do { _Pragma("unroll") for (int m = 0; m < 4; ++m) _Pragma("unroll") for (int k = 0; k < 2; ++k) dst[m][k] = *(const PG8_LAS bf16x8*)(lds + PG8_SA(b, h) + aoff + m * 2048 + k * 1024); } while (0)
; #define PG8_MMA(ai, bj, At, Bt) do { __builtin_amdgcn_s_setprio(1); _Pragma("unroll") for (int m = 0; m < 4; ++m) _Pragma("unroll") for (int n = 0; n < 2; ++n) _Pragma("unroll") for (int k = 0; k < 2; ++k) \
;         acc[ai][bj][m][n] = __builtin_amdgcn_mfma_f32_16x16x32_bf16(Bt[n][k], At[m][k], acc[ai][bj][m][n], 0, 0, 0); __builtin_amdgcn_s_setprio(0); } while (0)
; #define PG8_WAIT_V89() do { if constexpr (SLIVER) PG8_WAIT_V(9); else PG8_WAIT_V(8); } while (0)
; #define PG8_LDS_S(b) do { if constexpr (SLIVER) { Sf[0] = *(const PG8_LAS bf16x8*)(lds + STAGE_BYTES + (b) * 2048 + soff0); Sf[1] = *(const PG8_LAS bf16x8*)(lds + STAGE_BYTES + (b) * 2048 + (soff0 ^ 64)); } } while (0)
; #define PG8_WAIT_L(n) asm volatile("s_waitcnt lgkmcnt(" #n ")" ::: "memory")
; #define PG8_BAR __builtin_amdgcn_s_barrier()
; #define PG8_SCHED __builtin_amdgcn_sched_barrier(0)
; template <class Epi, class Sched, bool ALIGN_EPI = false, bool SP2 = false, bool SLIVER = false>
; __device__ __forceinline__ void gemm_phase(PG8_LAS unsigned char* lds, const Gemm g, const Sched& S, const Epi& E) {
;     ...
;             PG8_WAIT_V89(); PG8_WAIT_L(0); PG8_BAR; PG8_MMA(0, 0, At, B0); PG8_MMA(0, 1, At, B1); PG8_BAR; PG8_SCHED;
;             PG8_LDA(At, 1, 1); PG8_LDS_S(1); PG8_STAGE(PG8_SB(1, 0), b3, voffB); PG8_STAGE(PG8_SB(1, 1), b3 + hstep, voffB); PG8_STAGE(PG8_SA(1, 0), a3, voffA);
;             PG8_WAIT_V89(); PG8_WAIT_L(0); PG8_BAR; PG8_MMA(1, 0, At, B0); PG8_MMA(1, 1, At, B1); PG8_MMA_S(); PG8_BAR; PG8_SCHED;
	v_mfma_f32_16x16x32_bf16 v[134:137], v[146:149], v[2:5], v[134:137]
	v_mfma_f32_16x16x32_bf16 v[130:133], v[154:157], v[2:5], v[130:133]
	v_mfma_f32_16x16x32_bf16 v[126:129], v[146:149], v[180:183], v[126:129]
	v_mfma_f32_16x16x32_bf16 v[122:125], v[154:157], v[180:183], v[122:125]
	v_mfma_f32_16x16x32_bf16 v[114:117], v[146:149], v[216:219], v[114:117]
	v_mfma_f32_16x16x32_bf16 v[106:109], v[154:157], v[216:219], v[106:109]
	v_mfma_f32_16x16x32_bf16 v[98:101], v[146:149], v[224:227], v[98:101]
	v_mfma_f32_16x16x32_bf16 v[90:93], v[154:157], v[224:227], v[90:93]
	v_mfma_f32_16x16x32_bf16 v[134:137], v[150:153], v[6:9], v[134:137]
	v_mfma_f32_16x16x32_bf16 v[130:133], v[158:161], v[6:9], v[130:133]
	v_mfma_f32_16x16x32_bf16 v[126:129], v[150:153], v[184:187], v[126:129]
	v_mfma_f32_16x16x32_bf16 v[122:125], v[158:161], v[184:187], v[122:125]
	v_mfma_f32_16x16x32_bf16 v[114:117], v[150:153], v[220:223], v[114:117]
	v_mfma_f32_16x16x32_bf16 v[106:109], v[158:161], v[220:223], v[106:109]
	v_mfma_f32_16x16x32_bf16 v[98:101], v[150:153], v[228:231], v[98:101]
	v_mfma_f32_16x16x32_bf16 v[90:93], v[158:161], v[228:231], v[90:93]
	s_setprio 0
	s_setprio 1
	v_mfma_f32_16x16x32_bf16 v[118:121], v[166:169], v[2:5], v[118:121]
	v_mfma_f32_16x16x32_bf16 v[2:5], v[174:177], v[2:5], v[110:113]
	v_mfma_f32_16x16x32_bf16 v[110:113], v[162:165], v[6:9], v[2:5]
	v_mfma_f32_16x16x32_bf16 v[2:5], v[166:169], v[180:183], v[102:105]
	v_mfma_f32_16x16x32_bf16 v[102:105], v[170:173], v[184:187], v[2:5]
	v_mfma_f32_16x16x32_bf16 v[2:5], v[174:177], v[180:183], v[94:97]
	v_mfma_f32_16x16x32_bf16 v[94:97], v[162:165], v[184:187], v[2:5]
	v_mfma_f32_16x16x32_bf16 v[2:5], v[166:169], v[216:219], v[86:89]
	v_mfma_f32_16x16x32_bf16 v[86:89], v[170:173], v[220:223], v[2:5]
	v_mfma_f32_16x16x32_bf16 v[2:5], v[174:177], v[216:219], v[82:85]
	v_mfma_f32_16x16x32_bf16 v[82:85], v[162:165], v[220:223], v[2:5]
	v_mfma_f32_16x16x32_bf16 v[2:5], v[166:169], v[224:227], v[78:81]
	v_mfma_f32_16x16x32_bf16 v[78:81], v[170:173], v[228:231], v[2:5]
	v_mfma_f32_16x16x32_bf16 v[2:5], v[174:177], v[224:227], v[74:77]
	v_mfma_f32_16x16x32_bf16 v[118:121], v[170:173], v[6:9], v[118:121]
	v_mfma_f32_16x16x32_bf16 v[74:77], v[162:165], v[228:231], v[2:5]
	s_barrier
	s_setprio 0
	s_add_i32 s12, 0, 0x20800
	v_add_u32_e32 v178, s12, v213
	v_add_u32_e32 v184, s12, v214
	s_add_i32 s12, s68, s92
	v_lshl_add_u64 v[208:209], v[202:203], 0, s[26:27]
	s_mov_b32 m0, s12
	ds_read_b128 v[2:5], v215 offset:49152
	ds_read_b128 v[6:9], v215 offset:50176
	ds_read_b128 v[216:219], v215 offset:51200
	ds_read_b128 v[220:223], v215 offset:52224
	ds_read_b128 v[224:227], v215 offset:53248
	ds_read_b128 v[228:231], v215 offset:54272
	ds_read_b128 v[232:235], v215 offset:55296
	ds_read_b128 v[240:243], v215 offset:56320
	ds_read_b128 v[180:183], v178
	ds_read_b128 v[184:187], v184
	global_load_lds_dwordx4 v[208:209], off
	v_lshl_add_u64 v[208:209], v[202:203], 0, s[58:59]
	s_add_i32 m0, s12, 0x2000
	s_mov_b64 s[12:13], 0x90080
	global_load_lds_dwordx4 v[208:209], off
	v_lshl_add_u64 v[208:209], v[202:203], 0, s[12:13]
	s_add_i32 s12, s69, s92
	s_mov_b32 m0, s12
	s_mov_b64 s[68:69], 0xd8080
	global_load_lds_dwordx4 v[208:209], off
	v_lshl_add_u64 v[202:203], v[202:203], 0, s[68:69]
	s_add_i32 m0, s12, 0x2000
	s_nop 0
	global_load_lds_dwordx4 v[202:203], off
	v_lshl_add_u64 v[202:203], v[210:211], 0, s[26:27]
	s_mov_b32 m0, s51
	s_nop 0
	global_load_lds_dwordx4 v[202:203], off
	v_lshl_add_u64 v[202:203], v[210:211], 0, s[58:59]
	s_mov_b32 m0, s53
	s_nop 0
	global_load_lds_dwordx4 v[202:203], off
	s_waitcnt vmcnt(9)
	s_waitcnt lgkmcnt(0)
	s_setprio 1
	s_barrier
	v_mfma_f32_16x16x32_bf16 v[70:73], v[146:149], v[2:5], v[70:73]
	v_mfma_f32_16x16x32_bf16 v[66:69], v[154:157], v[2:5], v[66:69]
	v_mfma_f32_16x16x32_bf16 v[62:65], v[146:149], v[216:219], v[62:65]
	v_mfma_f32_16x16x32_bf16 v[58:61], v[154:157], v[216:219], v[58:61]
	v_mfma_f32_16x16x32_bf16 v[50:53], v[146:149], v[224:227], v[50:53]
	v_mfma_f32_16x16x32_bf16 v[42:45], v[154:157], v[224:227], v[42:45]
	v_mfma_f32_16x16x32_bf16 v[34:37], v[146:149], v[232:235], v[34:37]
	v_mfma_f32_16x16x32_bf16 v[26:29], v[154:157], v[232:235], v[26:29]
	v_mfma_f32_16x16x32_bf16 v[70:73], v[150:153], v[6:9], v[70:73]
	v_mfma_f32_16x16x32_bf16 v[66:69], v[158:161], v[6:9], v[66:69]
	v_mfma_f32_16x16x32_bf16 v[62:65], v[150:153], v[220:223], v[62:65]
	v_mfma_f32_16x16x32_bf16 v[58:61], v[158:161], v[220:223], v[58:61]
	v_mfma_f32_16x16x32_bf16 v[50:53], v[150:153], v[228:231], v[50:53]
	v_mfma_f32_16x16x32_bf16 v[42:45], v[158:161], v[228:231], v[42:45]
	v_mfma_f32_16x16x32_bf16 v[34:37], v[150:153], v[240:243], v[34:37]
	v_mfma_f32_16x16x32_bf16 v[26:29], v[158:161], v[240:243], v[26:29]
	s_setprio 0
	s_setprio 1
	v_mfma_f32_16x16x32_bf16 v[54:57], v[166:169], v[2:5], v[54:57]
	v_mfma_f32_16x16x32_bf16 v[2:5], v[174:177], v[2:5], v[46:49]
	v_mfma_f32_16x16x32_bf16 v[46:49], v[162:165], v[6:9], v[2:5]
	v_mfma_f32_16x16x32_bf16 v[2:5], v[166:169], v[216:219], v[38:41]
	v_mfma_f32_16x16x32_bf16 v[38:41], v[170:173], v[220:223], v[2:5]
	v_mfma_f32_16x16x32_bf16 v[2:5], v[174:177], v[216:219], v[30:33]
	v_mfma_f32_16x16x32_bf16 v[30:33], v[162:165], v[220:223], v[2:5]
	v_mfma_f32_16x16x32_bf16 v[2:5], v[166:169], v[224:227], v[22:25]
	v_mfma_f32_16x16x32_bf16 v[22:25], v[170:173], v[228:231], v[2:5]
	v_mfma_f32_16x16x32_bf16 v[2:5], v[174:177], v[224:227], v[18:21]
	v_mfma_f32_16x16x32_bf16 v[18:21], v[162:165], v[228:231], v[2:5]
	v_mfma_f32_16x16x32_bf16 v[2:5], v[166:169], v[232:235], v[14:17]
	v_mfma_f32_16x16x32_bf16 v[14:17], v[170:173], v[240:243], v[2:5]
	v_mfma_f32_16x16x32_bf16 v[2:5], v[174:177], v[232:235], v[10:13]
	v_mfma_f32_16x16x32_bf16 v[54:57], v[170:173], v[6:9], v[54:57]
	v_mfma_f32_16x16x32_bf16 v[10:13], v[162:165], v[240:243], v[2:5]
	s_setprio 0
	s_setprio 1
	v_mfma_f32_16x16x32_bf16 v[2:5], v[166:169], v[180:183], v[138:141]
	v_mfma_f32_16x16x32_bf16 v[6:9], v[170:173], v[184:187], v[2:5]
	v_mfma_f32_16x16x32_bf16 v[2:5], v[174:177], v[180:183], v[142:145]
	v_mfma_f32_16x16x32_bf16 v[2:5], v[162:165], v[184:187], v[2:5]
	s_branch .LBB0_933

; #define PG8_SB(B) __builtin_amdgcn_rcpf(1.f + expneg(B))
; #define PG8_SB(B) __builtin_amdgcn_rcpf(1.f + expneg(B))
; #define PG8_STAGE(bufoff, gbase, voff) do { _Pragma("unroll") for (int _i = 0; _i < 2; ++_i) \
;         __builtin_amdgcn_global_load_lds((const unsigned*)((const char*)(gbase) + (size_t)_i * qstep + (voff)[0]), (PG8_LAS unsigned*)(lds + (bufoff) + ldsw + _i * 8192), 16, 0, 0); } while (0)
; #define PG8_LDA(dst, b, h) do { _Pragma("unroll") for (int m = 0; m < 4; ++m) _Pragma("unroll") for (int k = 0; k < 2; ++k) dst[m][k] = *(const PG8_LAS bf16x8*)(lds + PG8_SA(b, h) + aoff + m * 2048 + k * 1024); } while (0)
; #define PG8_LDB(dst, b, h) do { _Pragma("unroll") for (int n = 0; n < 2; ++n) _Pragma("unroll") for (int k = 0; k < 2; ++k) dst[n][k] = *(const PG8_LAS bf16x8*)(lds + PG8_SB(b, h) + boff + n * 2048 + k * 1024); } while (0)
; #define PG8_MMA(ai, bj, At, Bt) do { __builtin_amdgcn_s_setprio(1); _Pragma("unroll") for (int m = 0; m < 4; ++m) _Pragma("unroll") for (int n = 0; n < 2; ++n) _Pragma("unroll") for (int k = 0; k < 2; ++k) \
;         acc[ai][bj][m][n] = __builtin_amdgcn_mfma_f32_16x16x32_bf16(Bt[n][k], At[m][k], acc[ai][bj][m][n], 0, 0, 0); __builtin_amdgcn_s_setprio(0); } while (0)
; #define PG8_WAIT_V89() do { if constexpr (SLIVER) PG8_WAIT_V(9); else PG8_WAIT_V(8); } while (0)
; #define PG8_STAGE_S(b, gbase) do { if constexpr (SLIVER) __builtin_amdgcn_global_load_lds((const unsigned*)((const char*)(gbase) + voffS), (PG8_LAS unsigned*)(lds + STAGE_BYTES + (b) * 2048 + wid * 256), 4, 0, 0); } while (0)
; #define PG8_BAR __builtin_amdgcn_s_barrier()
; template <class Epi, class Sched, bool ALIGN_EPI = false, bool SP2 = false, bool SLIVER = false>
; __device__ __forceinline__ void gemm_phase(PG8_LAS unsigned char* lds, const Gemm g, const Sched& S, const Epi& E) {
;     ...
;             PG8_LDB(B0, 0, 0); PG8_LDB(B1, 0, 1); PG8_SCHED; PG8_LDA(At, 0, 0); PG8_STAGE(PG8_SA(1, 1), a1 + hstep, voffA); PG8_STAGE_S(1, s1);
;             PG8_WAIT_V89(); PG8_WAIT_L(0); PG8_BAR; PG8_MMA(0, 0, At, B0); PG8_MMA(0, 1, At, B1); PG8_BAR; PG8_SCHED;
;             PG8_LDA(At, 0, 1); PG8_LDS_S(0); PG8_STAGE(PG8_SB(0, 0), b2, voffB); PG8_STAGE(PG8_SB(0, 1), b2 + hstep, voffB); PG8_STAGE(PG8_SA(0, 0), a2, voffA);
;             PG8_WAIT_V89(); PG8_WAIT_L(0); PG8_BAR; PG8_MMA(1, 0, At, B0); PG8_MMA(1, 1, At, B1); PG8_MMA_S(); PG8_BAR; PG8_SCHED;
.LslvB_hdr3:
	s_cmp_eq_u32 s66, s62
	s_cselect_b64 s[80:81], -1, 0
	s_add_u32 s12, s42, s62
	s_addc_u32 s13, s43, s63
	s_add_u32 s40, s12, 0x100
	s_addc_u32 s41, s13, 0
	s_and_b64 s[12:13], s[80:81], exec
	s_cselect_b32 s41, s95, s41
	s_cselect_b32 s40, s94, s40
	s_add_u32 s68, s17, s62
	s_addc_u32 s69, s45, s63
	s_add_i32 s76, 0, 0x10000
	s_and_b64 s[12:13], s[80:81], exec
	v_add_u32_e32 v138, s76, v212
	s_cselect_b32 s13, s97, s69
	s_cselect_b32 s12, s96, s68
	s_add_i32 s68, 0, 0x14000
	ds_read_b128 v[146:149], v138
	ds_read_b128 v[150:153], v138 offset:1024
	ds_read_b128 v[154:157], v138 offset:2048
	ds_read_b128 v[158:161], v138 offset:3072
	v_add_u32_e32 v138, s68, v212
	ds_read_b128 v[166:169], v138
	ds_read_b128 v[170:173], v138 offset:1024
	ds_read_b128 v[174:177], v138 offset:2048
	ds_read_b128 v[162:165], v138 offset:3072
	v_lshl_add_u64 v[202:203], v[198:199], 0, s[62:63]
	s_mov_b64 vcc, 0x90080
	v_lshl_add_u64 v[208:209], v[202:203], 0, vcc
	s_add_i32 m0, s93, 0xc000
	s_mov_b64 vcc, 0xd8080
	ds_read_b128 v[138:141], v215
	ds_read_b128 v[142:145], v215 offset:1024
	ds_read_b128 v[180:183], v215 offset:2048
	ds_read_b128 v[184:187], v215 offset:3072
	ds_read_b128 v[216:219], v215 offset:4096
	ds_read_b128 v[220:223], v215 offset:5120
	ds_read_b128 v[224:227], v215 offset:6144
	ds_read_b128 v[228:231], v215 offset:7168
	global_load_lds_dwordx4 v[208:209], off
	v_lshl_add_u64 v[202:203], v[202:203], 0, vcc
	s_add_i32 m0, s93, 0xe000
	s_nop 0
	global_load_lds_dwordx4 v[202:203], off
	v_lshl_add_u64 v[202:203], v[200:201], 0, s[62:63]
	s_add_i32 m0, s50, 0x20800
	s_nop 0
	global_load_lds_dword v[202:203], off
	s_waitcnt vmcnt(9)
	s_waitcnt lgkmcnt(0)
	s_setprio 1
	s_barrier
	v_mfma_f32_16x16x32_bf16 v[134:137], v[146:149], v[138:141], v[134:137]
	v_mfma_f32_16x16x32_bf16 v[130:133], v[154:157], v[138:141], v[130:133]
	v_mfma_f32_16x16x32_bf16 v[126:129], v[146:149], v[180:183], v[126:129]
	v_mfma_f32_16x16x32_bf16 v[122:125], v[154:157], v[180:183], v[122:125]
	v_mfma_f32_16x16x32_bf16 v[114:117], v[146:149], v[216:219], v[114:117]
	v_mfma_f32_16x16x32_bf16 v[106:109], v[154:157], v[216:219], v[106:109]
	v_mfma_f32_16x16x32_bf16 v[98:101], v[146:149], v[224:227], v[98:101]
	v_mfma_f32_16x16x32_bf16 v[90:93], v[154:157], v[224:227], v[90:93]
	v_mfma_f32_16x16x32_bf16 v[134:137], v[150:153], v[142:145], v[134:137]
	v_mfma_f32_16x16x32_bf16 v[130:133], v[158:161], v[142:145], v[130:133]
	v_mfma_f32_16x16x32_bf16 v[126:129], v[150:153], v[184:187], v[126:129]
	v_mfma_f32_16x16x32_bf16 v[122:125], v[158:161], v[184:187], v[122:125]
	v_mfma_f32_16x16x32_bf16 v[114:117], v[150:153], v[220:223], v[114:117]
	v_mfma_f32_16x16x32_bf16 v[106:109], v[158:161], v[220:223], v[106:109]
	v_mfma_f32_16x16x32_bf16 v[98:101], v[150:153], v[228:231], v[98:101]
	v_mfma_f32_16x16x32_bf16 v[90:93], v[158:161], v[228:231], v[90:93]
	s_setprio 0
	s_setprio 1
	v_mfma_f32_16x16x32_bf16 v[118:121], v[166:169], v[138:141], v[118:121]
	v_mfma_f32_16x16x32_bf16 v[110:113], v[174:177], v[138:141], v[110:113]
	v_mfma_f32_16x16x32_bf16 v[102:105], v[166:169], v[180:183], v[102:105]
	v_mfma_f32_16x16x32_bf16 v[94:97], v[174:177], v[180:183], v[94:97]
	v_mfma_f32_16x16x32_bf16 v[86:89], v[166:169], v[216:219], v[86:89]
	v_mfma_f32_16x16x32_bf16 v[82:85], v[174:177], v[216:219], v[82:85]
	v_mfma_f32_16x16x32_bf16 v[78:81], v[166:169], v[224:227], v[78:81]
	v_mfma_f32_16x16x32_bf16 v[74:77], v[174:177], v[224:227], v[74:77]
	v_mfma_f32_16x16x32_bf16 v[118:121], v[170:173], v[142:145], v[118:121]
	v_mfma_f32_16x16x32_bf16 v[110:113], v[162:165], v[142:145], v[110:113]
	v_mfma_f32_16x16x32_bf16 v[102:105], v[170:173], v[184:187], v[102:105]
	v_mfma_f32_16x16x32_bf16 v[94:97], v[162:165], v[184:187], v[94:97]
	v_mfma_f32_16x16x32_bf16 v[86:89], v[170:173], v[220:223], v[86:89]
	v_mfma_f32_16x16x32_bf16 v[82:85], v[162:165], v[220:223], v[82:85]
	v_mfma_f32_16x16x32_bf16 v[78:81], v[170:173], v[228:231], v[78:81]
	v_mfma_f32_16x16x32_bf16 v[74:77], v[162:165], v[228:231], v[74:77]
	s_barrier
	s_setprio 0
	s_add_i32 s69, 0, 0x20000
	v_lshl_add_u64 v[202:203], s[12:13], 0, v[190:191]
	s_add_i32 s12, s76, s92
	v_add_u32_e32 v178, s69, v213
	v_add_u32_e32 v184, s69, v214
	s_mov_b32 m0, s12
	ds_read_b128 v[138:141], v215 offset:16384
	ds_read_b128 v[142:145], v215 offset:17408
	ds_read_b128 v[216:219], v215 offset:18432
	ds_read_b128 v[220:223], v215 offset:19456
	ds_read_b128 v[224:227], v215 offset:20480
	ds_read_b128 v[228:231], v215 offset:21504
	ds_read_b128 v[232:235], v215 offset:22528
	ds_read_b128 v[240:243], v215 offset:23552
	ds_read_b128 v[180:183], v178
	ds_read_b128 v[184:187], v184
	global_load_lds_dwordx4 v[202:203], off
	v_lshl_add_u64 v[208:209], v[202:203], 0, s[70:71]
	s_add_i32 m0, s12, 0x2000
	s_add_i32 s12, s68, s92
	global_load_lds_dwordx4 v[208:209], off
	v_lshl_add_u64 v[208:209], v[202:203], 0, s[46:47]
	s_mov_b32 m0, s12
	v_lshl_add_u64 v[210:211], s[40:41], 0, v[188:189]
	global_load_lds_dwordx4 v[208:209], off
	v_lshl_add_u64 v[208:209], v[202:203], 0, s[6:7]
	s_add_i32 m0, s12, 0x2000
	s_nop 0
	global_load_lds_dwordx4 v[208:209], off
	s_mov_b32 m0, s93
	v_lshl_add_u64 v[208:209], v[210:211], 0, s[70:71]
	global_load_lds_dwordx4 v[210:211], off
	s_mov_b32 m0, s48
	s_nop 0
	global_load_lds_dwordx4 v[208:209], off
	s_waitcnt vmcnt(9)
	s_waitcnt lgkmcnt(0)
	s_setprio 1
	s_barrier
; #define PG8_STAGE(bufoff, gbase, voff) do { _Pragma("unroll") for (int _i = 0; _i < 2; ++_i) \
;         __builtin_amdgcn_global_load_lds((const unsigned*)((const char*)(gbase) + (size_t)_i * qstep + (voff)[0]), (PG8_LAS unsigned*)(lds + (bufoff) + ldsw + _i * 8192), 16, 0, 0); } while (0)
; #define PG8_LDA(dst, b, h) do { _Pragma("unroll") for (int m = 0; m < 4; ++m) _Pragma("unroll") for (int k = 0; k < 2; ++k) dst[m][k] = *(const PG8_LAS bf16x8*)(lds + PG8_SA(b, h) + aoff + m * 2048 + k * 1024); } while (0)
; #define PG8_LDB(dst, b, h) do { _Pragma("unroll") for (int n = 0; n < 2; ++n) _Pragma("unroll") for (int k = 0; k < 2; ++k) dst[n][k] = *(const PG8_LAS bf16x8*)(lds + PG8_SB(b, h) + boff + n * 2048 + k * 1024); } while (0)
; #define PG8_MMA(ai, bj, At, Bt) do { __builtin_amdgcn_s_setprio(1); _Pragma("unroll") for (int m = 0; m < 4; ++m) _Pragma("unroll") for (int n = 0; n < 2; ++n) _Pragma("unroll") for (int k = 0; k < 2; ++k) \
;         acc[ai][bj][m][n] = __builtin_amdgcn_mfma_f32_16x16x32_bf16(Bt[n][k], At[m][k], acc[ai][bj][m][n], 0, 0, 0); __builtin_amdgcn_s_setprio(0); } while (0)
; #define PG8_WAIT_V89() do { if constexpr (SLIVER) PG8_WAIT_V(9); else PG8_WAIT_V(8); } while (0)
; #define PG8_STAGE_S(b, gbase) do { if constexpr (SLIVER) __builtin_amdgcn_global_load_lds((const unsigned*)((const char*)(gbase) + voffS), (PG8_LAS unsigned*)(lds + STAGE_BYTES + (b) * 2048 + wid * 256), 4, 0, 0); } while (0)
; #define PG8_WAIT_L(n) asm volatile("s_waitcnt lgkmcnt(" #n ")" ::: "memory")
; #define PG8_BAR __builtin_amdgcn_s_barrier()
; #define PG8_SCHED __builtin_amdgcn_sched_barrier(0)
; template <class Epi, class Sched, bool ALIGN_EPI = false, bool SP2 = false, bool SLIVER = false>
; __device__ __forceinline__ void gemm_phase(PG8_LAS unsigned char* lds, const Gemm g, const Sched& S, const Epi& E) {
;     ...
;             PG8_WAIT_V89(); PG8_WAIT_L(0); PG8_BAR; PG8_MMA(1, 0, At, B0); PG8_MMA(1, 1, At, B1); PG8_MMA_S(); PG8_BAR; PG8_SCHED;
;             PG8_LDB(B0, 1, 0); PG8_LDB(B1, 1, 1); PG8_SCHED; PG8_LDA(At, 1, 0); PG8_STAGE(PG8_SA(0, 1), a2 + hstep, voffA); PG8_STAGE_S(0, s2);
	v_mfma_f32_16x16x32_bf16 v[70:73], v[146:149], v[138:141], v[70:73]
	v_mfma_f32_16x16x32_bf16 v[66:69], v[154:157], v[138:141], v[66:69]
	v_mfma_f32_16x16x32_bf16 v[62:65], v[146:149], v[216:219], v[62:65]
	v_mfma_f32_16x16x32_bf16 v[58:61], v[154:157], v[216:219], v[58:61]
	v_mfma_f32_16x16x32_bf16 v[50:53], v[146:149], v[224:227], v[50:53]
	v_mfma_f32_16x16x32_bf16 v[42:45], v[154:157], v[224:227], v[42:45]
	v_mfma_f32_16x16x32_bf16 v[34:37], v[146:149], v[232:235], v[34:37]
	v_mfma_f32_16x16x32_bf16 v[26:29], v[154:157], v[232:235], v[26:29]
	v_mfma_f32_16x16x32_bf16 v[70:73], v[150:153], v[142:145], v[70:73]
	v_mfma_f32_16x16x32_bf16 v[66:69], v[158:161], v[142:145], v[66:69]
	v_mfma_f32_16x16x32_bf16 v[62:65], v[150:153], v[220:223], v[62:65]
	v_mfma_f32_16x16x32_bf16 v[58:61], v[158:161], v[220:223], v[58:61]
	v_mfma_f32_16x16x32_bf16 v[50:53], v[150:153], v[228:231], v[50:53]
	v_mfma_f32_16x16x32_bf16 v[42:45], v[158:161], v[228:231], v[42:45]
	v_mfma_f32_16x16x32_bf16 v[34:37], v[150:153], v[240:243], v[34:37]
	v_mfma_f32_16x16x32_bf16 v[26:29], v[158:161], v[240:243], v[26:29]
	s_setprio 0
	s_setprio 1
	v_mfma_f32_16x16x32_bf16 v[54:57], v[166:169], v[138:141], v[54:57]
	v_mfma_f32_16x16x32_bf16 v[46:49], v[174:177], v[138:141], v[46:49]
	v_mfma_f32_16x16x32_bf16 v[38:41], v[166:169], v[216:219], v[38:41]
	v_mfma_f32_16x16x32_bf16 v[30:33], v[174:177], v[216:219], v[30:33]
	v_mfma_f32_16x16x32_bf16 v[22:25], v[166:169], v[224:227], v[22:25]
	v_mfma_f32_16x16x32_bf16 v[18:21], v[174:177], v[224:227], v[18:21]
	v_mfma_f32_16x16x32_bf16 v[14:17], v[166:169], v[232:235], v[14:17]
	v_mfma_f32_16x16x32_bf16 v[10:13], v[174:177], v[232:235], v[10:13]
	v_mfma_f32_16x16x32_bf16 v[54:57], v[170:173], v[142:145], v[54:57]
	v_mfma_f32_16x16x32_bf16 v[46:49], v[162:165], v[142:145], v[46:49]
	v_mfma_f32_16x16x32_bf16 v[38:41], v[170:173], v[220:223], v[38:41]
	v_mfma_f32_16x16x32_bf16 v[30:33], v[162:165], v[220:223], v[30:33]
	v_mfma_f32_16x16x32_bf16 v[22:25], v[170:173], v[228:231], v[22:25]
	v_mfma_f32_16x16x32_bf16 v[18:21], v[162:165], v[228:231], v[18:21]
	v_mfma_f32_16x16x32_bf16 v[14:17], v[170:173], v[240:243], v[14:17]
	v_mfma_f32_16x16x32_bf16 v[10:13], v[162:165], v[240:243], v[10:13]
	s_setprio 0
	s_setprio 1
	v_mfma_f32_16x16x32_bf16 v[6:9], v[146:149], v[180:183], v[6:9]
	v_mfma_f32_16x16x32_bf16 v[2:5], v[154:157], v[180:183], v[2:5]
	v_mfma_f32_16x16x32_bf16 v[138:141], v[150:153], v[184:187], v[6:9]
	v_mfma_f32_16x16x32_bf16 v[142:145], v[158:161], v[184:187], v[2:5]
	s_barrier
	s_setprio 0
	s_add_u32 s12, s54, s62
	s_addc_u32 s13, s55, s63
	s_add_u32 s68, s12, 0x100
	s_addc_u32 s69, s13, 0
	s_and_b64 s[12:13], s[80:81], exec
	s_cselect_b32 s13, s19, s69
	s_cselect_b32 s12, s18, s68
	s_add_i32 s68, 0, 0x18000
	v_add_u32_e32 v2, s68, v212
	s_add_i32 s69, 0, 0x1c000
	ds_read_b128 v[146:149], v2
	ds_read_b128 v[150:153], v2 offset:1024
	ds_read_b128 v[154:157], v2 offset:2048
	ds_read_b128 v[158:161], v2 offset:3072
	v_add_u32_e32 v2, s69, v212
	ds_read_b128 v[166:169], v2
	ds_read_b128 v[170:173], v2 offset:1024
	ds_read_b128 v[174:177], v2 offset:2048
	ds_read_b128 v[162:165], v2 offset:3072
	s_mov_b32 m0, s49
	v_lshl_add_u64 v[208:209], v[210:211], 0, s[46:47]
	ds_read_b128 v[2:5], v215 offset:32768
	ds_read_b128 v[6:9], v215 offset:33792
	ds_read_b128 v[180:183], v215 offset:34816
	ds_read_b128 v[184:187], v215 offset:35840
	ds_read_b128 v[216:219], v215 offset:36864
	ds_read_b128 v[220:223], v215 offset:37888
	ds_read_b128 v[224:227], v215 offset:38912
	ds_read_b128 v[228:231], v215 offset:39936
	global_load_lds_dwordx4 v[208:209], off
	v_lshl_add_u64 v[208:209], v[210:211], 0, s[6:7]
	s_mov_b32 m0, s88
	s_nop 0
	global_load_lds_dwordx4 v[208:209], off
	v_lshl_add_u64 v[208:209], s[12:13], 0, v[192:193]
	s_mov_b32 m0, s89
	s_nop 0
	global_load_lds_dword v[208:209], off
	s_waitcnt vmcnt(9)
	s_waitcnt lgkmcnt(0)
	s_setprio 1
	s_barrier
; #define PG8_SB(B) __builtin_amdgcn_rcpf(1.f + expneg(B))
; #define PG8_SB(B) __builtin_amdgcn_rcpf(1.f + expneg(B))
; #define PG8_STAGE(bufoff, gbase, voff) do { _Pragma("unroll") for (int _i = 0; _i < 2; ++_i) \
;         __builtin_amdgcn_global_load_lds((const unsigned*)((const char*)(gbase) + (size_t)_i * qstep + (voff)[0]), (PG8_LAS unsigned*)(lds + (bufoff) + ldsw + _i * 8192), 16, 0, 0); } while (0)
; #define PG8_LDA(dst, b, h) do { _Pragma("unroll") for (int m = 0; m < 4; ++m) _Pragma("unroll") for (int k = 0; k < 2; ++k) dst[m][k] = *(const PG8_LAS bf16x8*)(lds + PG8_SA(b, h) + aoff + m * 2048 + k * 1024); } while (0)
; #define PG8_MMA(ai, bj, At, Bt) do { __builtin_amdgcn_s_setprio(1); _Pragma("unroll") for (int m = 0; m < 4; ++m) _Pragma("unroll") for (int n = 0; n < 2; ++n) _Pragma("unroll") for (int k = 0; k < 2; ++k) \
;         acc[ai][bj][m][n] = __builtin_amdgcn_mfma_f32_16x16x32_bf16(Bt[n][k], At[m][k], acc[ai][bj][m][n], 0, 0, 0); __builtin_amdgcn_s_setprio(0); } while (0)
; #define PG8_WAIT_V89() do { if constexpr (SLIVER) PG8_WAIT_V(9); else PG8_WAIT_V(8); } while (0)
; #define PG8_LDS_S(b) do { if constexpr (SLIVER) { Sf[0] = *(const PG8_LAS bf16x8*)(lds + STAGE_BYTES + (b) * 2048 + soff0); Sf[1] = *(const PG8_LAS bf16x8*)(lds + STAGE_BYTES + (b) * 2048 + (soff0 ^ 64)); } } while (0)
; #define PG8_WAIT_L(n) asm volatile("s_waitcnt lgkmcnt(" #n ")" ::: "memory")
; #define PG8_BAR __builtin_amdgcn_s_barrier()
; #define PG8_SCHED __builtin_amdgcn_sched_barrier(0)
; template <class Epi, class Sched, bool ALIGN_EPI = false, bool SP2 = false, bool SLIVER = false>
; __device__ __forceinline__ void gemm_phase(PG8_LAS unsigned char* lds, const Gemm g, const Sched& S, const Epi& E) {
;     ...
;             PG8_WAIT_V89(); PG8_WAIT_L(0); PG8_BAR; PG8_MMA(0, 0, At, B0); PG8_MMA(0, 1, At, B1); PG8_BAR; PG8_SCHED;
;             PG8_LDA(At, 1, 1); PG8_LDS_S(1); PG8_STAGE(PG8_SB(1, 0), b3, voffB); PG8_STAGE(PG8_SB(1, 1), b3 + hstep, voffB); PG8_STAGE(PG8_SA(1, 0), a3, voffA);
;             PG8_WAIT_V89(); PG8_WAIT_L(0); PG8_BAR; PG8_MMA(1, 0, At, B0); PG8_MMA(1, 1, At, B1); PG8_MMA_S(); PG8_BAR; PG8_SCHED;
	v_mfma_f32_16x16x32_bf16 v[134:137], v[146:149], v[2:5], v[134:137]
	v_mfma_f32_16x16x32_bf16 v[130:133], v[154:157], v[2:5], v[130:133]
	v_mfma_f32_16x16x32_bf16 v[126:129], v[146:149], v[180:183], v[126:129]
	v_mfma_f32_16x16x32_bf16 v[122:125], v[154:157], v[180:183], v[122:125]
	v_mfma_f32_16x16x32_bf16 v[114:117], v[146:149], v[216:219], v[114:117]
	v_mfma_f32_16x16x32_bf16 v[106:109], v[154:157], v[216:219], v[106:109]
	v_mfma_f32_16x16x32_bf16 v[98:101], v[146:149], v[224:227], v[98:101]
	v_mfma_f32_16x16x32_bf16 v[90:93], v[154:157], v[224:227], v[90:93]
	v_mfma_f32_16x16x32_bf16 v[134:137], v[150:153], v[6:9], v[134:137]
	v_mfma_f32_16x16x32_bf16 v[130:133], v[158:161], v[6:9], v[130:133]
	v_mfma_f32_16x16x32_bf16 v[126:129], v[150:153], v[184:187], v[126:129]
	v_mfma_f32_16x16x32_bf16 v[122:125], v[158:161], v[184:187], v[122:125]
	v_mfma_f32_16x16x32_bf16 v[114:117], v[150:153], v[220:223], v[114:117]
	v_mfma_f32_16x16x32_bf16 v[106:109], v[158:161], v[220:223], v[106:109]
	v_mfma_f32_16x16x32_bf16 v[98:101], v[150:153], v[228:231], v[98:101]
	v_mfma_f32_16x16x32_bf16 v[90:93], v[158:161], v[228:231], v[90:93]
	s_setprio 0
	s_setprio 1
	v_mfma_f32_16x16x32_bf16 v[118:121], v[166:169], v[2:5], v[118:121]
	v_mfma_f32_16x16x32_bf16 v[2:5], v[174:177], v[2:5], v[110:113]
	v_mfma_f32_16x16x32_bf16 v[110:113], v[162:165], v[6:9], v[2:5]
	v_mfma_f32_16x16x32_bf16 v[2:5], v[166:169], v[180:183], v[102:105]
	v_mfma_f32_16x16x32_bf16 v[102:105], v[170:173], v[184:187], v[2:5]
	v_mfma_f32_16x16x32_bf16 v[2:5], v[174:177], v[180:183], v[94:97]
	v_mfma_f32_16x16x32_bf16 v[94:97], v[162:165], v[184:187], v[2:5]
	v_mfma_f32_16x16x32_bf16 v[2:5], v[166:169], v[216:219], v[86:89]
	v_mfma_f32_16x16x32_bf16 v[86:89], v[170:173], v[220:223], v[2:5]
	v_mfma_f32_16x16x32_bf16 v[2:5], v[174:177], v[216:219], v[82:85]
	v_mfma_f32_16x16x32_bf16 v[82:85], v[162:165], v[220:223], v[2:5]
	v_mfma_f32_16x16x32_bf16 v[2:5], v[166:169], v[224:227], v[78:81]
	v_mfma_f32_16x16x32_bf16 v[78:81], v[170:173], v[228:231], v[2:5]
	v_mfma_f32_16x16x32_bf16 v[2:5], v[174:177], v[224:227], v[74:77]
	v_mfma_f32_16x16x32_bf16 v[118:121], v[170:173], v[6:9], v[118:121]
	v_mfma_f32_16x16x32_bf16 v[74:77], v[162:165], v[228:231], v[2:5]
	s_barrier
	s_setprio 0
	s_add_i32 s12, 0, 0x20800
	v_add_u32_e32 v178, s12, v213
	v_add_u32_e32 v184, s12, v214
	s_add_i32 s12, s68, s92
	v_lshl_add_u64 v[208:209], v[202:203], 0, s[26:27]
	s_mov_b32 m0, s12
	ds_read_b128 v[2:5], v215 offset:49152
	ds_read_b128 v[6:9], v215 offset:50176
	ds_read_b128 v[216:219], v215 offset:51200
	ds_read_b128 v[220:223], v215 offset:52224
	ds_read_b128 v[224:227], v215 offset:53248
	ds_read_b128 v[228:231], v215 offset:54272
	ds_read_b128 v[232:235], v215 offset:55296
	ds_read_b128 v[240:243], v215 offset:56320
	ds_read_b128 v[180:183], v178
	ds_read_b128 v[184:187], v184
	global_load_lds_dwordx4 v[208:209], off
	v_lshl_add_u64 v[208:209], v[202:203], 0, s[58:59]
	s_add_i32 m0, s12, 0x2000
	s_mov_b64 s[12:13], 0x90080
	global_load_lds_dwordx4 v[208:209], off
	v_lshl_add_u64 v[208:209], v[202:203], 0, s[12:13]
	s_add_i32 s12, s69, s92
	s_mov_b32 m0, s12
	s_mov_b64 s[68:69], 0xd8080
	global_load_lds_dwordx4 v[208:209], off
	v_lshl_add_u64 v[202:203], v[202:203], 0, s[68:69]
	s_add_i32 m0, s12, 0x2000
	s_nop 0
	global_load_lds_dwordx4 v[202:203], off
	v_lshl_add_u64 v[202:203], v[210:211], 0, s[26:27]
	s_mov_b32 m0, s51
	s_nop 0
	global_load_lds_dwordx4 v[202:203], off
	v_lshl_add_u64 v[202:203], v[210:211], 0, s[58:59]
	s_mov_b32 m0, s53
	s_nop 0
	global_load_lds_dwordx4 v[202:203], off
	s_waitcnt vmcnt(9)
	s_waitcnt lgkmcnt(0)
	s_setprio 1
	s_barrier
	v_mfma_f32_16x16x32_bf16 v[70:73], v[146:149], v[2:5], v[70:73]
	v_mfma_f32_16x16x32_bf16 v[66:69], v[154:157], v[2:5], v[66:69]
	v_mfma_f32_16x16x32_bf16 v[62:65], v[146:149], v[216:219], v[62:65]
	v_mfma_f32_16x16x32_bf16 v[58:61], v[154:157], v[216:219], v[58:61]
	v_mfma_f32_16x16x32_bf16 v[50:53], v[146:149], v[224:227], v[50:53]
	v_mfma_f32_16x16x32_bf16 v[42:45], v[154:157], v[224:227], v[42:45]
	v_mfma_f32_16x16x32_bf16 v[34:37], v[146:149], v[232:235], v[34:37]
	v_mfma_f32_16x16x32_bf16 v[26:29], v[154:157], v[232:235], v[26:29]
	v_mfma_f32_16x16x32_bf16 v[70:73], v[150:153], v[6:9], v[70:73]
	v_mfma_f32_16x16x32_bf16 v[66:69], v[158:161], v[6:9], v[66:69]
	v_mfma_f32_16x16x32_bf16 v[62:65], v[150:153], v[220:223], v[62:65]
	v_mfma_f32_16x16x32_bf16 v[58:61], v[158:161], v[220:223], v[58:61]
	v_mfma_f32_16x16x32_bf16 v[50:53], v[150:153], v[228:231], v[50:53]
	v_mfma_f32_16x16x32_bf16 v[42:45], v[158:161], v[228:231], v[42:45]
	v_mfma_f32_16x16x32_bf16 v[34:37], v[150:153], v[240:243], v[34:37]
	v_mfma_f32_16x16x32_bf16 v[26:29], v[158:161], v[240:243], v[26:29]
	s_setprio 0
	s_setprio 1
	v_mfma_f32_16x16x32_bf16 v[54:57], v[166:169], v[2:5], v[54:57]
	v_mfma_f32_16x16x32_bf16 v[2:5], v[174:177], v[2:5], v[46:49]
	v_mfma_f32_16x16x32_bf16 v[46:49], v[162:165], v[6:9], v[2:5]
	v_mfma_f32_16x16x32_bf16 v[2:5], v[166:169], v[216:219], v[38:41]
	v_mfma_f32_16x16x32_bf16 v[38:41], v[170:173], v[220:223], v[2:5]
	v_mfma_f32_16x16x32_bf16 v[2:5], v[174:177], v[216:219], v[30:33]
	v_mfma_f32_16x16x32_bf16 v[30:33], v[162:165], v[220:223], v[2:5]
	v_mfma_f32_16x16x32_bf16 v[2:5], v[166:169], v[224:227], v[22:25]
	v_mfma_f32_16x16x32_bf16 v[22:25], v[170:173], v[228:231], v[2:5]
	v_mfma_f32_16x16x32_bf16 v[2:5], v[174:177], v[224:227], v[18:21]
	v_mfma_f32_16x16x32_bf16 v[18:21], v[162:165], v[228:231], v[2:5]
	v_mfma_f32_16x16x32_bf16 v[2:5], v[166:169], v[232:235], v[14:17]
	v_mfma_f32_16x16x32_bf16 v[14:17], v[170:173], v[240:243], v[2:5]
	v_mfma_f32_16x16x32_bf16 v[2:5], v[174:177], v[232:235], v[10:13]
	v_mfma_f32_16x16x32_bf16 v[54:57], v[170:173], v[6:9], v[54:57]
	v_mfma_f32_16x16x32_bf16 v[10:13], v[162:165], v[240:243], v[2:5]
	s_setprio 0
	s_setprio 1
	v_mfma_f32_16x16x32_bf16 v[2:5], v[146:149], v[180:183], v[138:141]
	v_mfma_f32_16x16x32_bf16 v[6:9], v[150:153], v[184:187], v[2:5]
	v_mfma_f32_16x16x32_bf16 v[2:5], v[154:157], v[180:183], v[142:145]
	v_mfma_f32_16x16x32_bf16 v[2:5], v[158:161], v[184:187], v[2:5]
	s_branch .LslvB_lend3
